# EpiRes epilogues (Gout,G2): hoist tile-uniform table loads, pipeline X loads one 16-row section ahead, drop per-group vmcnt(0)
# speedup vs baseline: 1.0140x; 1.0140x over previous
.LBB0_92:
	s_add_i32 s0, s1, 2
	s_setprio 1
	v_add_u32_e32 v111, v104, v105
	ds_read_b128 v[136:139], v111 offset:16384
	ds_read_b128 v[140:143], v111 offset:18432
	ds_read_b128 v[144:147], v111 offset:20480
	ds_read_b128 v[148:151], v111 offset:22528
	v_add_u32_e32 v110, v103, v105
	ds_read_b128 v[116:119], v110
	s_add_i32 s1, s1, 4
	ds_read_b128 v[120:123], v110 offset:2048
	s_min_u32 s1, s1, 15
	v_add_u32_e32 v113, v104, v114
	s_lshl_b32 s92, s1, 7
	ds_read_b128 v[124:127], v110 offset:4096
	v_add_u32_e32 v112, v103, v114
	ds_read_b128 v[194:197], v113 offset:16384
	ds_read_b128 v[198:201], v113 offset:18432
	ds_read_b128 v[202:205], v113 offset:20480
	ds_read_b128 v[206:209], v113 offset:22528
	v_lshl_add_u64 v[164:165], v[98:99], 0, s[92:93]
	ds_read_b128 v[132:135], v110 offset:6144
	ds_read_b128 v[152:155], v112
	ds_read_b128 v[156:159], v112 offset:2048
	ds_read_b128 v[160:163], v112 offset:4096
	ds_read_b128 v[190:193], v112 offset:6144
	s_waitcnt lgkmcnt(11)
	v_mfma_f32_16x16x32_bf16 v[92:95], v[136:139], v[116:119], v[92:95]
	v_mfma_f32_16x16x32_bf16 v[88:91], v[140:143], v[116:119], v[88:91]
	v_mfma_f32_16x16x32_bf16 v[52:55], v[144:147], v[116:119], v[52:55]
	v_mfma_f32_16x16x32_bf16 v[48:51], v[148:151], v[116:119], v[48:51]
	global_load_dwordx4 v[116:119], v[164:165], off
	s_waitcnt vmcnt(6)
	ds_write_b128 v109, v[56:59] offset:32768
	v_add_co_u32_e32 v56, vcc, s11, v164
	s_waitcnt lgkmcnt(11)
	v_mfma_f32_16x16x32_bf16 v[44:47], v[136:139], v[120:123], v[44:47]
	v_addc_co_u32_e32 v57, vcc, 0, v165, vcc
	v_mfma_f32_16x16x32_bf16 v[40:43], v[140:143], v[120:123], v[40:43]
	v_mfma_f32_16x16x32_bf16 v[36:39], v[144:147], v[120:123], v[36:39]
	v_mfma_f32_16x16x32_bf16 v[32:35], v[148:151], v[120:123], v[32:35]
	global_load_dwordx4 v[120:123], v[56:57], off
	v_add_co_u32_e32 v56, vcc, s33, v164
	ds_write_b128 v109, v[60:63] offset:36864
	s_nop 0
	v_addc_co_u32_e32 v57, vcc, 0, v165, vcc
	s_waitcnt lgkmcnt(11)
	v_mfma_f32_16x16x32_bf16 v[28:31], v[136:139], v[124:127], v[28:31]
	v_mfma_f32_16x16x32_bf16 v[24:27], v[140:143], v[124:127], v[24:27]
	v_mfma_f32_16x16x32_bf16 v[20:23], v[144:147], v[124:127], v[20:23]
	v_mfma_f32_16x16x32_bf16 v[16:19], v[148:151], v[124:127], v[16:19]
	global_load_dwordx4 v[124:127], v[56:57], off
	v_add_co_u32_e32 v56, vcc, s59, v164
	ds_write_b128 v109, v[64:67] offset:40960
	s_nop 0
	v_addc_co_u32_e32 v57, vcc, 0, v165, vcc
	v_lshl_add_u64 v[64:65], v[100:101], 0, s[92:93]
	v_add_co_u32_e32 v66, vcc, s11, v64
	s_waitcnt lgkmcnt(7)
	v_mfma_f32_16x16x32_bf16 v[12:15], v[136:139], v[132:135], v[12:15]
	v_addc_co_u32_e32 v67, vcc, 0, v65, vcc
	v_mfma_f32_16x16x32_bf16 v[8:11], v[140:143], v[132:135], v[8:11]
	v_mfma_f32_16x16x32_bf16 v[4:7], v[144:147], v[132:135], v[4:7]
	v_mfma_f32_16x16x32_bf16 v[0:3], v[148:151], v[132:135], v[0:3]
	global_load_dwordx4 v[132:135], v[56:57], off
	s_waitcnt vmcnt(7)
	ds_write_b128 v109, v[72:75] offset:45056
	s_waitcnt lgkmcnt(7)
	v_mfma_f32_16x16x32_bf16 v[56:59], v[194:197], v[152:155], v[92:95]
	v_mfma_f32_16x16x32_bf16 v[60:63], v[198:201], v[152:155], v[88:91]
	v_mfma_f32_16x16x32_bf16 v[52:55], v[202:205], v[152:155], v[52:55]
	v_mfma_f32_16x16x32_bf16 v[48:51], v[206:209], v[152:155], v[48:51]
	global_load_dwordx4 v[136:139], v[64:65], off
	ds_write_b128 v109, v[68:71] offset:49152
	s_waitcnt lgkmcnt(7)
	v_mfma_f32_16x16x32_bf16 v[44:47], v[194:197], v[156:159], v[44:47]
	v_mfma_f32_16x16x32_bf16 v[40:43], v[198:201], v[156:159], v[40:43]
	v_mfma_f32_16x16x32_bf16 v[36:39], v[202:205], v[156:159], v[36:39]
	v_mfma_f32_16x16x32_bf16 v[32:35], v[206:209], v[156:159], v[32:35]
	global_load_dwordx4 v[140:143], v[66:67], off
	v_add_co_u32_e32 v66, vcc, s33, v64
	s_waitcnt vmcnt(8)
	ds_write_b128 v109, v[76:79] offset:53248
	v_addc_co_u32_e32 v67, vcc, 0, v65, vcc
	v_add_co_u32_e32 v64, vcc, s59, v64
	s_waitcnt lgkmcnt(7)
	v_mfma_f32_16x16x32_bf16 v[28:31], v[194:197], v[160:163], v[28:31]
	v_addc_co_u32_e32 v65, vcc, 0, v65, vcc
	v_mfma_f32_16x16x32_bf16 v[24:27], v[198:201], v[160:163], v[24:27]
	v_mfma_f32_16x16x32_bf16 v[20:23], v[202:205], v[160:163], v[20:23]
	v_mfma_f32_16x16x32_bf16 v[16:19], v[206:209], v[160:163], v[16:19]
	global_load_dwordx4 v[144:147], v[66:67], off
	s_waitcnt vmcnt(8)
	ds_write_b128 v109, v[80:83] offset:57344
	s_waitcnt lgkmcnt(7)
	v_mfma_f32_16x16x32_bf16 v[12:15], v[194:197], v[190:193], v[12:15]
	v_mfma_f32_16x16x32_bf16 v[8:11], v[198:201], v[190:193], v[8:11]
	v_mfma_f32_16x16x32_bf16 v[4:7], v[202:205], v[190:193], v[4:7]
	v_mfma_f32_16x16x32_bf16 v[0:3], v[206:209], v[190:193], v[0:3]
	global_load_dwordx4 v[148:151], v[64:65], off
	s_waitcnt vmcnt(8)
	ds_write_b128 v109, v[84:87] offset:61440
	s_setprio 0
	s_waitcnt lgkmcnt(0)
	s_barrier
	s_setprio 1
	ds_read_b128 v[84:87], v111 offset:51200
	ds_read_b128 v[80:83], v111 offset:49152
	ds_read_b128 v[88:91], v111 offset:53248
	ds_read_b128 v[92:95], v111 offset:55296
	ds_read_b128 v[64:67], v110 offset:32768
	s_min_u32 s1, s0, 12
	s_lshl_b32 s92, s1, 7
	ds_read_b128 v[68:71], v110 offset:34816
	v_lshl_add_u64 v[164:165], v[98:99], 0, s[92:93]
	ds_read_b128 v[72:75], v110 offset:36864
	ds_read_b128 v[76:79], v110 offset:38912
	ds_read_b128 v[152:155], v112 offset:32768
	ds_read_b128 v[156:159], v112 offset:34816
	ds_read_b128 v[160:163], v112 offset:36864
	ds_read_b128 v[190:193], v112 offset:38912
	ds_read_b128 v[194:197], v113 offset:49152
	ds_read_b128 v[198:201], v113 offset:51200
	ds_read_b128 v[202:205], v113 offset:53248
	ds_read_b128 v[206:209], v113 offset:55296
	s_waitcnt lgkmcnt(11)
	v_mfma_f32_16x16x32_bf16 v[214:217], v[84:87], v[64:67], v[60:63]
	v_mfma_f32_16x16x32_bf16 v[210:213], v[80:83], v[64:67], v[56:59]
	s_nop 1
	v_add_co_u32_e32 v60, vcc, s11, v164
	s_nop 1
	v_addc_co_u32_e32 v61, vcc, 0, v165, vcc
	v_mfma_f32_16x16x32_bf16 v[52:55], v[88:91], v[64:67], v[52:55]
	v_mfma_f32_16x16x32_bf16 v[48:51], v[92:95], v[64:67], v[48:51]
	v_add_co_u32_e32 v64, vcc, s33, v164
	global_load_dwordx4 v[56:59], v[164:165], off offset:384
	s_nop 0
	v_addc_co_u32_e32 v65, vcc, 0, v165, vcc
	s_waitcnt vmcnt(8)
	ds_write_b128 v109, v[116:119]
	s_waitcnt lgkmcnt(11)
	v_mfma_f32_16x16x32_bf16 v[44:47], v[80:83], v[68:71], v[44:47]
	v_mfma_f32_16x16x32_bf16 v[40:43], v[84:87], v[68:71], v[40:43]
	v_mfma_f32_16x16x32_bf16 v[36:39], v[88:91], v[68:71], v[36:39]
	v_mfma_f32_16x16x32_bf16 v[32:35], v[92:95], v[68:71], v[32:35]
	v_add_co_u32_e32 v68, vcc, s59, v164
	global_load_dwordx4 v[60:63], v[60:61], off offset:384
	s_waitcnt vmcnt(8)
	ds_write_b128 v109, v[120:123] offset:4096
	s_waitcnt lgkmcnt(11)
	v_mfma_f32_16x16x32_bf16 v[28:31], v[80:83], v[72:75], v[28:31]
	v_addc_co_u32_e32 v69, vcc, 0, v165, vcc
	v_mfma_f32_16x16x32_bf16 v[24:27], v[84:87], v[72:75], v[24:27]
	v_mfma_f32_16x16x32_bf16 v[20:23], v[88:91], v[72:75], v[20:23]
	v_mfma_f32_16x16x32_bf16 v[16:19], v[92:95], v[72:75], v[16:19]
	global_load_dwordx4 v[64:67], v[64:65], off offset:384
	s_waitcnt vmcnt(8)
	ds_write_b128 v109, v[124:127] offset:8192
	s_waitcnt lgkmcnt(11)
	v_mfma_f32_16x16x32_bf16 v[8:11], v[84:87], v[76:79], v[8:11]
	v_lshl_add_u64 v[84:85], v[100:101], 0, s[92:93]
	v_mfma_f32_16x16x32_bf16 v[12:15], v[80:83], v[76:79], v[12:15]
	v_mfma_f32_16x16x32_bf16 v[4:7], v[88:91], v[76:79], v[4:7]
	v_mfma_f32_16x16x32_bf16 v[0:3], v[92:95], v[76:79], v[0:3]
	v_add_co_u32_e32 v76, vcc, s11, v84
	global_load_dwordx4 v[72:75], v[68:69], off offset:384
	s_nop 0
	v_addc_co_u32_e32 v77, vcc, 0, v85, vcc
	v_add_co_u32_e32 v80, vcc, s33, v84
	s_waitcnt vmcnt(8)
	ds_write_b128 v109, v[132:135] offset:12288
	v_addc_co_u32_e32 v81, vcc, 0, v85, vcc
	s_waitcnt lgkmcnt(7)
	v_mfma_f32_16x16x32_bf16 v[92:95], v[194:197], v[152:155], v[210:213]
	s_waitcnt lgkmcnt(6)
	v_mfma_f32_16x16x32_bf16 v[88:91], v[198:201], v[152:155], v[214:217]
	s_waitcnt lgkmcnt(5)
	v_mfma_f32_16x16x32_bf16 v[52:55], v[202:205], v[152:155], v[52:55]
	s_waitcnt lgkmcnt(4)
	v_mfma_f32_16x16x32_bf16 v[48:51], v[206:209], v[152:155], v[48:51]
	global_load_dwordx4 v[68:71], v[84:85], off offset:384
	v_add_co_u32_e32 v84, vcc, s59, v84
	s_waitcnt vmcnt(8)
	ds_write_b128 v109, v[136:139] offset:16384
	v_addc_co_u32_e32 v85, vcc, 0, v85, vcc
	v_mfma_f32_16x16x32_bf16 v[44:47], v[194:197], v[156:159], v[44:47]
	v_mfma_f32_16x16x32_bf16 v[40:43], v[198:201], v[156:159], v[40:43]
	v_mfma_f32_16x16x32_bf16 v[36:39], v[202:205], v[156:159], v[36:39]
	v_mfma_f32_16x16x32_bf16 v[32:35], v[206:209], v[156:159], v[32:35]
	global_load_dwordx4 v[76:79], v[76:77], off offset:384
	s_waitcnt vmcnt(8)
	ds_write_b128 v109, v[140:143] offset:20480
	v_mfma_f32_16x16x32_bf16 v[28:31], v[194:197], v[160:163], v[28:31]
	v_mfma_f32_16x16x32_bf16 v[24:27], v[198:201], v[160:163], v[24:27]
	v_mfma_f32_16x16x32_bf16 v[20:23], v[202:205], v[160:163], v[20:23]
	v_mfma_f32_16x16x32_bf16 v[16:19], v[206:209], v[160:163], v[16:19]
	global_load_dwordx4 v[80:83], v[80:81], off offset:384
	s_waitcnt vmcnt(8)
	ds_write_b128 v109, v[144:147] offset:24576
	v_mfma_f32_16x16x32_bf16 v[12:15], v[194:197], v[190:193], v[12:15]
	v_mfma_f32_16x16x32_bf16 v[8:11], v[198:201], v[190:193], v[8:11]
	v_mfma_f32_16x16x32_bf16 v[4:7], v[202:205], v[190:193], v[4:7]
	v_mfma_f32_16x16x32_bf16 v[0:3], v[206:209], v[190:193], v[0:3]
	global_load_dwordx4 v[84:87], v[84:85], off offset:384
	s_waitcnt vmcnt(8)
	ds_write_b128 v109, v[148:151] offset:28672
	s_setprio 0
	s_cmp_lt_u32 s0, 14
	s_mov_b32 s1, s0
	s_waitcnt lgkmcnt(0)
	s_barrier
	s_cbranch_scc1 .LBB0_92
	s_mul_i32 s0, s69, 0x12000
	v_readlane_b32 s16, v250, 25
	s_add_u32 s24, s16, s0
	v_readlane_b32 s0, v251, 5
	v_lshlrev_b32_e32 v114, 6, v102
	v_readlane_b32 s17, v250, 26
	s_waitcnt vmcnt(5)
	v_add_u32_e32 v64, s0, v108
	v_readlane_b32 s0, v251, 6
	v_add_u32_e32 v56, 0xffffe000, v64
	v_or_b32_e32 v62, v64, v107
	v_or_b32_e32 v65, s0, v114
	v_lshrrev_b32_e32 v56, 10, v56
	s_movk_i32 s0, 0x1800
	v_mad_u32_u24 v56, v56, s0, s0
	v_cmp_lt_i32_e32 vcc, s13, v62
	s_addc_u32 s25, s17, 0
	v_lshlrev_b32_e32 v115, 2, v97
	v_cndmask_b32_e32 v56, 0, v56, vcc
	s_add_u32 s40, s24, 0x2000
	v_or_b32_e32 v58, v65, v115
	v_ashrrev_i32_e32 v57, 31, v56
	s_addc_u32 s41, s25, 0
	s_waitcnt vmcnt(4)
	v_lshlrev_b64 v[74:75], 2, v[56:57]
	v_ashrrev_i32_e32 v59, 31, v58
	v_ashrrev_i32_e32 v63, 31, v62
	v_lshl_add_u64 v[56:57], s[40:41], 0, v[74:75]
	v_lshlrev_b64 v[60:61], 2, v[58:59]
	v_readlane_b32 s0, v250, 15
	s_waitcnt vmcnt(1)
	v_lshl_add_u64 v[82:83], v[56:57], 0, v[60:61]
	v_lshlrev_b64 v[56:57], 12, v[62:63]
	v_readlane_b32 s1, v250, 16
	v_readlane_b32 s16, v250, 21
	v_lshlrev_b64 v[78:79], 11, v[62:63]
	v_lshl_add_u64 v[56:57], s[0:1], 0, v[56:57]
	s_waitcnt vmcnt(0)
	v_lshl_add_u64 v[84:85], v[56:57], 0, v[60:61]
	global_load_dwordx4 v[116:119], v[82:83], off
	global_load_dwordx4 v[120:123], v[82:83], off offset:64
	global_load_dwordx4 v[124:127], v[82:83], off offset:128
	global_load_dwordx4 v[132:135], v[82:83], off offset:192
	global_load_dwordx4 v[190:193], v[84:85], off
	global_load_dwordx4 v[194:197], v[84:85], off offset:64
	global_load_dwordx4 v[198:201], v[84:85], off offset:128
	global_load_dwordx4 v[202:205], v[84:85], off offset:192
	v_add_co_u32_e32 v164, vcc, 0x10000, v84
	s_nop 1
	v_addc_co_u32_e32 v165, vcc, 0, v85, vcc
	v_add_co_u32_e32 v222, vcc, 0x20000, v84
	s_nop 1
	v_addc_co_u32_e32 v223, vcc, 0, v85, vcc
	v_add_co_u32_e32 v224, vcc, 0x30000, v84
	s_nop 1
	v_addc_co_u32_e32 v225, vcc, 0, v85, vcc
	global_load_dwordx4 v[206:209], v[164:165], off
	global_load_dwordx4 v[210:213], v[164:165], off offset:64
	global_load_dwordx4 v[214:217], v[164:165], off offset:128
	global_load_dwordx4 v[218:221], v[164:165], off offset:192
	s_lshl_b32 s0, s69, 12
	v_readlane_b32 s68, v250, 41
	v_readlane_b32 s72, v250, 45
	v_readlane_b32 s73, v250, 46
	s_add_u32 s0, s72, s0
	s_addc_u32 s1, s73, 0
	s_add_u32 s42, s24, 0x4000
	s_addc_u32 s43, s25, 0
	v_lshl_add_u64 v[74:75], s[42:43], 0, v[74:75]
	v_lshl_add_u64 v[56:57], s[0:1], 0, v[60:61]
	v_lshl_add_u64 v[86:87], v[74:75], 0, v[60:61]
	v_readlane_b32 s17, v250, 22
	v_readlane_b32 s69, v250, 42
	v_readlane_b32 s69, v254, 49
	v_lshl_add_u64 v[78:79], s[16:17], 0, v[78:79]
	s_mul_i32 s24, s69, 0x140000
	s_add_u32 s24, s86, s24
	v_lshrrev_b32_e32 v65, 6, v65
	s_mov_b32 s16, 0xa000
	s_addc_u32 s25, s87, 0
	s_add_u32 s26, s24, 0xaf1a000
	s_addc_u32 s27, s25, 0
	v_cmp_eq_u32_e64 s[36:37], 0, v97
	v_readlane_b32 s70, v250, 43
	v_readlane_b32 s71, v250, 44
	v_readlane_b32 s74, v250, 47
	v_readlane_b32 s75, v250, 48
	v_readlane_b32 s76, v250, 49
	v_readlane_b32 s77, v250, 50
	v_readlane_b32 s78, v250, 51
	v_readlane_b32 s79, v250, 52
	v_readlane_b32 s80, v250, 53
	v_readlane_b32 s81, v250, 54
	v_readlane_b32 s82, v250, 55
	v_readlane_b32 s83, v250, 56
	s_waitcnt vmcnt(4)
	v_pk_fma_f32 v[68:69], v[94:95], v[118:119], v[192:193]
	v_pk_fma_f32 v[66:67], v[92:93], v[116:117], v[190:191]
	global_store_dwordx4 v[84:85], v[66:69], off
	global_load_dwordx4 v[136:139], v[56:57], off
	global_load_dwordx4 v[140:143], v[56:57], off offset:64
	global_load_dwordx4 v[144:147], v[56:57], off offset:128
	global_load_dwordx4 v[148:151], v[56:57], off offset:192
	global_load_dwordx4 v[152:155], v[86:87], off
	global_load_dwordx4 v[156:159], v[86:87], off offset:64
	global_load_dwordx4 v[160:163], v[86:87], off offset:128
	global_load_dwordx4 v[180:183], v[86:87], off offset:192
	v_lshl_add_u64 v[92:93], v[58:59], 1, v[78:79]
	s_waitcnt vmcnt(0)
	v_pk_mul_f32 v[72:73], v[68:69], v[138:139]
	v_pk_mul_f32 v[70:71], v[66:67], v[136:137]
	s_waitcnt vmcnt(0)
	v_pk_add_f32 v[76:77], v[154:155], 1.0 op_sel_hi:[1,0]
	v_pk_add_f32 v[74:75], v[152:153], 1.0 op_sel_hi:[1,0]
	v_pk_mul_f32 v[72:73], v[72:73], v[76:77]
	v_pk_mul_f32 v[70:71], v[70:71], v[74:75]
	v_and_b32_sdwa v76, v73, v170 dst_sel:DWORD dst_unused:UNUSED_PAD src0_sel:WORD_1 src1_sel:DWORD
	v_and_b32_sdwa v77, v71, v170 dst_sel:DWORD dst_unused:UNUSED_PAD src0_sel:WORD_1 src1_sel:DWORD
	v_and_b32_sdwa v74, v72, v170 dst_sel:DWORD dst_unused:UNUSED_PAD src0_sel:WORD_1 src1_sel:DWORD
	v_and_b32_sdwa v75, v70, v170 dst_sel:DWORD dst_unused:UNUSED_PAD src0_sel:WORD_1 src1_sel:DWORD
	v_add3_u32 v73, v73, v76, s56
	v_add3_u32 v71, v71, v77, s56
	v_add3_u32 v70, v70, v75, s56
	v_add3_u32 v72, v72, v74, s56
	v_and_b32_e32 v73, 0xffff0000, v73
	v_and_b32_e32 v74, 0xffff0000, v71
	v_or_b32_sdwa v71, v73, v72 dst_sel:DWORD dst_unused:UNUSED_PAD src0_sel:DWORD src1_sel:WORD_1
	v_or_b32_sdwa v70, v74, v70 dst_sel:DWORD dst_unused:UNUSED_PAD src0_sel:DWORD src1_sel:WORD_1
	global_store_dwordx2 v[92:93], v[70:71], off
	s_nop 0
	s_waitcnt vmcnt(0)
	v_pk_fma_f32 v[72:73], v[90:91], v[122:123], v[196:197]
	v_pk_fma_f32 v[70:71], v[88:89], v[120:121], v[194:195]
	global_store_dwordx4 v[84:85], v[70:73], off offset:64
	v_pk_mul_f32 v[76:77], v[72:73], v[142:143]
	v_pk_mul_f32 v[74:75], v[70:71], v[140:141]
	v_pk_add_f32 v[80:81], v[158:159], 1.0 op_sel_hi:[1,0]
	v_pk_add_f32 v[78:79], v[156:157], 1.0 op_sel_hi:[1,0]
	v_pk_mul_f32 v[76:77], v[76:77], v[80:81]
	v_pk_mul_f32 v[74:75], v[74:75], v[78:79]
	v_and_b32_sdwa v80, v77, v170 dst_sel:DWORD dst_unused:UNUSED_PAD src0_sel:WORD_1 src1_sel:DWORD
	v_and_b32_sdwa v81, v75, v170 dst_sel:DWORD dst_unused:UNUSED_PAD src0_sel:WORD_1 src1_sel:DWORD
	v_and_b32_sdwa v78, v76, v170 dst_sel:DWORD dst_unused:UNUSED_PAD src0_sel:WORD_1 src1_sel:DWORD
	v_and_b32_sdwa v79, v74, v170 dst_sel:DWORD dst_unused:UNUSED_PAD src0_sel:WORD_1 src1_sel:DWORD
	v_add3_u32 v77, v77, v80, s56
	v_add3_u32 v75, v75, v81, s56
	v_add3_u32 v74, v74, v79, s56
	v_add3_u32 v76, v76, v78, s56
	v_and_b32_e32 v77, 0xffff0000, v77
	v_and_b32_e32 v78, 0xffff0000, v75
	v_or_b32_sdwa v75, v77, v76 dst_sel:DWORD dst_unused:UNUSED_PAD src0_sel:DWORD src1_sel:WORD_1
	v_or_b32_sdwa v74, v78, v74 dst_sel:DWORD dst_unused:UNUSED_PAD src0_sel:DWORD src1_sel:WORD_1
	global_store_dwordx2 v[92:93], v[74:75], off offset:32
	s_nop 0
	v_pk_fma_f32 v[54:55], v[54:55], v[126:127], v[200:201]
	v_pk_fma_f32 v[52:53], v[52:53], v[124:125], v[198:199]
	global_store_dwordx4 v[84:85], v[52:55], off offset:128
	v_pk_mul_f32 v[76:77], v[54:55], v[146:147]
	v_pk_mul_f32 v[74:75], v[52:53], v[144:145]
	v_pk_add_f32 v[80:81], v[162:163], 1.0 op_sel_hi:[1,0]
	v_pk_add_f32 v[78:79], v[160:161], 1.0 op_sel_hi:[1,0]
	v_pk_mul_f32 v[76:77], v[76:77], v[80:81]
	v_pk_mul_f32 v[74:75], v[74:75], v[78:79]
	v_and_b32_sdwa v80, v77, v170 dst_sel:DWORD dst_unused:UNUSED_PAD src0_sel:WORD_1 src1_sel:DWORD
	v_and_b32_sdwa v81, v75, v170 dst_sel:DWORD dst_unused:UNUSED_PAD src0_sel:WORD_1 src1_sel:DWORD
	v_and_b32_sdwa v78, v76, v170 dst_sel:DWORD dst_unused:UNUSED_PAD src0_sel:WORD_1 src1_sel:DWORD
	v_and_b32_sdwa v79, v74, v170 dst_sel:DWORD dst_unused:UNUSED_PAD src0_sel:WORD_1 src1_sel:DWORD
	v_add3_u32 v77, v77, v80, s56
	v_add3_u32 v75, v75, v81, s56
	v_add3_u32 v74, v74, v79, s56
	v_add3_u32 v76, v76, v78, s56
	v_and_b32_e32 v77, 0xffff0000, v77
	v_and_b32_e32 v78, 0xffff0000, v75
	v_or_b32_sdwa v75, v77, v76 dst_sel:DWORD dst_unused:UNUSED_PAD src0_sel:DWORD src1_sel:WORD_1
	v_or_b32_sdwa v74, v78, v74 dst_sel:DWORD dst_unused:UNUSED_PAD src0_sel:DWORD src1_sel:WORD_1
	global_store_dwordx2 v[92:93], v[74:75], off offset:64
	s_nop 0
	v_pk_fma_f32 v[76:77], v[50:51], v[134:135], v[204:205]
	v_pk_fma_f32 v[74:75], v[48:49], v[132:133], v[202:203]
	global_store_dwordx4 v[84:85], v[74:77], off offset:192
	s_nop 0
	v_mbcnt_lo_u32_b32 v48, -1, 0
	v_mbcnt_hi_u32_b32 v48, -1, v48
	v_and_b32_e32 v50, 64, v48
	v_xor_b32_e32 v49, 16, v48
	v_add_u32_e32 v50, 64, v50
	v_xor_b32_e32 v51, 32, v48
	v_cmp_lt_i32_e32 vcc, v49, v50
	s_nop 1
	v_cndmask_b32_e32 v49, v48, v49, vcc
	v_cmp_lt_i32_e32 vcc, v51, v50
	v_lshlrev_b32_e32 v105, 2, v49
	s_nop 0
	v_cndmask_b32_e32 v50, v48, v51, vcc
	v_lshlrev_b32_e32 v104, 2, v50
	v_mul_f32_e32 v50, v67, v67
	v_mul_f32_e32 v51, v71, v71
	v_fmac_f32_e32 v50, v66, v66
	v_fmac_f32_e32 v51, v70, v70
	v_fmac_f32_e32 v50, v68, v68
	v_fmac_f32_e32 v51, v72, v72
	v_fmac_f32_e32 v50, v69, v69
	v_fmac_f32_e32 v51, v73, v73
	v_add_f32_e32 v50, v50, v51
	v_mul_f32_e32 v51, v53, v53
	v_fmac_f32_e32 v51, v52, v52
	v_fmac_f32_e32 v51, v54, v54
	v_fmac_f32_e32 v51, v55, v55
	v_add_f32_e32 v50, v50, v51
	v_mul_f32_e32 v51, v75, v75
	v_fmac_f32_e32 v51, v74, v74
	v_fmac_f32_e32 v51, v76, v76
	v_fmac_f32_e32 v51, v77, v77
	v_add_f32_e32 v50, v50, v51
	ds_bpermute_b32 v51, v105, v50
	v_mul_lo_u32 v48, v65, s16
	v_ashrrev_i32_e32 v49, 31, v48
	v_lshl_add_u64 v[48:49], s[26:27], 0, v[48:49]
	v_lshl_add_u64 v[48:49], v[62:63], 2, v[48:49]
	s_waitcnt lgkmcnt(0)
	v_add_f32_e32 v50, v50, v51
	ds_bpermute_b32 v51, v104, v50
	v_pk_mul_f32 v[52:53], v[76:77], v[150:151]
	v_pk_mul_f32 v[54:55], v[74:75], v[148:149]
	v_pk_add_f32 v[66:67], v[182:183], 1.0 op_sel_hi:[1,0]
	v_pk_add_f32 v[68:69], v[180:181], 1.0 op_sel_hi:[1,0]
	v_pk_mul_f32 v[52:53], v[52:53], v[66:67]
	v_pk_mul_f32 v[54:55], v[54:55], v[68:69]
	v_and_b32_sdwa v67, v53, v170 dst_sel:DWORD dst_unused:UNUSED_PAD src0_sel:WORD_1 src1_sel:DWORD
	v_and_b32_sdwa v68, v55, v170 dst_sel:DWORD dst_unused:UNUSED_PAD src0_sel:WORD_1 src1_sel:DWORD
	v_and_b32_sdwa v65, v52, v170 dst_sel:DWORD dst_unused:UNUSED_PAD src0_sel:WORD_1 src1_sel:DWORD
	v_and_b32_sdwa v66, v54, v170 dst_sel:DWORD dst_unused:UNUSED_PAD src0_sel:WORD_1 src1_sel:DWORD
	v_add3_u32 v53, v53, v67, s56
	v_add3_u32 v55, v55, v68, s56
	v_add3_u32 v54, v54, v66, s56
	v_add3_u32 v52, v52, v65, s56
	v_and_b32_e32 v53, 0xffff0000, v53
	v_and_b32_e32 v55, 0xffff0000, v55
	v_or_b32_sdwa v53, v53, v52 dst_sel:DWORD dst_unused:UNUSED_PAD src0_sel:DWORD src1_sel:WORD_1
	v_or_b32_sdwa v52, v55, v54 dst_sel:DWORD dst_unused:UNUSED_PAD src0_sel:DWORD src1_sel:WORD_1
	global_store_dwordx2 v[92:93], v[52:53], off offset:96
	s_and_saveexec_b64 s[24:25], s[36:37]
	s_cbranch_execz .LBB0_95
	s_waitcnt lgkmcnt(0)
	v_add_f32_e32 v50, v50, v51
	global_store_dword v[48:49], v50, off
.LBB0_95:
	s_or_b64 exec, exec, s[24:25]
	v_add_u32_e32 v50, 0xffffe010, v64
	v_or_b32_e32 v54, 16, v62
	v_lshrrev_b32_e32 v50, 10, v50
	s_movk_i32 s5, 0x1800
	s_movk_i32 s13, 0x1fff
	v_mad_u32_u24 v50, v50, s5, s5
	v_cmp_lt_i32_e32 vcc, s13, v54
	v_ashrrev_i32_e32 v55, 31, v54
	v_readlane_b32 s16, v250, 15
	v_cndmask_b32_e32 v50, 0, v50, vcc
	s_waitcnt lgkmcnt(0)
	v_ashrrev_i32_e32 v51, 31, v50
	v_lshlrev_b64 v[70:71], 2, v[50:51]
	v_lshl_add_u64 v[50:51], s[40:41], 0, v[70:71]
	v_lshl_add_u64 v[72:73], v[50:51], 0, v[60:61]
	v_lshlrev_b64 v[50:51], 12, v[54:55]
	v_readlane_b32 s17, v250, 16
	v_lshl_add_u64 v[70:71], s[42:43], 0, v[70:71]
	v_lshl_add_u64 v[70:71], v[70:71], 0, v[60:61]
	v_lshl_add_u64 v[50:51], s[16:17], 0, v[50:51]
	v_lshl_add_u64 v[74:75], v[50:51], 0, v[60:61]
	v_readlane_b32 s16, v250, 21
	v_lshlrev_b64 v[54:55], 11, v[54:55]
	v_readlane_b32 s17, v250, 22
	global_load_dwordx4 v[190:193], v[222:223], off
	global_load_dwordx4 v[194:197], v[222:223], off offset:64
	global_load_dwordx4 v[198:201], v[222:223], off offset:128
	global_load_dwordx4 v[202:205], v[222:223], off offset:192
	s_waitcnt vmcnt(20)
	v_pk_fma_f32 v[46:47], v[46:47], v[118:119], v[208:209]
	v_pk_fma_f32 v[44:45], v[44:45], v[116:117], v[206:207]
	global_store_dwordx4 v[74:75], v[44:47], off
	v_lshl_add_u64 v[54:55], s[16:17], 0, v[54:55]
	v_lshl_add_u64 v[54:55], v[58:59], 1, v[54:55]
	v_pk_mul_f32 v[52:53], v[46:47], v[138:139]
	v_pk_mul_f32 v[50:51], v[44:45], v[136:137]
	v_pk_add_f32 v[68:69], v[154:155], 1.0 op_sel_hi:[1,0]
	v_pk_add_f32 v[66:67], v[152:153], 1.0 op_sel_hi:[1,0]
	v_pk_mul_f32 v[52:53], v[52:53], v[68:69]
	v_pk_mul_f32 v[50:51], v[50:51], v[66:67]
	v_and_b32_sdwa v66, v53, v170 dst_sel:DWORD dst_unused:UNUSED_PAD src0_sel:WORD_1 src1_sel:DWORD
	v_and_b32_sdwa v67, v51, v170 dst_sel:DWORD dst_unused:UNUSED_PAD src0_sel:WORD_1 src1_sel:DWORD
	v_and_b32_sdwa v63, v52, v170 dst_sel:DWORD dst_unused:UNUSED_PAD src0_sel:WORD_1 src1_sel:DWORD
	v_and_b32_sdwa v65, v50, v170 dst_sel:DWORD dst_unused:UNUSED_PAD src0_sel:WORD_1 src1_sel:DWORD
	v_add3_u32 v53, v53, v66, s56
	v_add3_u32 v51, v51, v67, s56
	v_add3_u32 v50, v50, v65, s56
	v_add3_u32 v52, v52, v63, s56
	v_and_b32_e32 v53, 0xffff0000, v53
	v_and_b32_e32 v63, 0xffff0000, v51
	v_or_b32_sdwa v51, v53, v52 dst_sel:DWORD dst_unused:UNUSED_PAD src0_sel:DWORD src1_sel:WORD_1
	v_or_b32_sdwa v50, v63, v50 dst_sel:DWORD dst_unused:UNUSED_PAD src0_sel:DWORD src1_sel:WORD_1
	global_store_dwordx2 v[54:55], v[50:51], off
	s_nop 0
	v_pk_fma_f32 v[42:43], v[42:43], v[122:123], v[212:213]
	v_pk_fma_f32 v[40:41], v[40:41], v[120:121], v[210:211]
	global_store_dwordx4 v[74:75], v[40:43], off offset:64
	v_pk_mul_f32 v[52:53], v[42:43], v[142:143]
	v_pk_mul_f32 v[50:51], v[40:41], v[140:141]
	v_pk_add_f32 v[68:69], v[158:159], 1.0 op_sel_hi:[1,0]
	v_pk_add_f32 v[66:67], v[156:157], 1.0 op_sel_hi:[1,0]
	v_pk_mul_f32 v[52:53], v[52:53], v[68:69]
	v_pk_mul_f32 v[50:51], v[50:51], v[66:67]
	v_and_b32_sdwa v66, v53, v170 dst_sel:DWORD dst_unused:UNUSED_PAD src0_sel:WORD_1 src1_sel:DWORD
	v_and_b32_sdwa v67, v51, v170 dst_sel:DWORD dst_unused:UNUSED_PAD src0_sel:WORD_1 src1_sel:DWORD
	v_and_b32_sdwa v63, v52, v170 dst_sel:DWORD dst_unused:UNUSED_PAD src0_sel:WORD_1 src1_sel:DWORD
	v_and_b32_sdwa v65, v50, v170 dst_sel:DWORD dst_unused:UNUSED_PAD src0_sel:WORD_1 src1_sel:DWORD
	v_add3_u32 v53, v53, v66, s56
	v_add3_u32 v51, v51, v67, s56
	v_add3_u32 v50, v50, v65, s56
	v_add3_u32 v52, v52, v63, s56
	v_and_b32_e32 v53, 0xffff0000, v53
	v_and_b32_e32 v63, 0xffff0000, v51
	v_or_b32_sdwa v51, v53, v52 dst_sel:DWORD dst_unused:UNUSED_PAD src0_sel:DWORD src1_sel:WORD_1
	v_or_b32_sdwa v50, v63, v50 dst_sel:DWORD dst_unused:UNUSED_PAD src0_sel:DWORD src1_sel:WORD_1
	global_store_dwordx2 v[54:55], v[50:51], off offset:32
	s_nop 0
	v_pk_fma_f32 v[38:39], v[38:39], v[126:127], v[216:217]
	v_pk_fma_f32 v[36:37], v[36:37], v[124:125], v[214:215]
	global_store_dwordx4 v[74:75], v[36:39], off offset:128
	v_pk_mul_f32 v[52:53], v[38:39], v[146:147]
	v_pk_mul_f32 v[50:51], v[36:37], v[144:145]
	v_pk_add_f32 v[68:69], v[162:163], 1.0 op_sel_hi:[1,0]
	v_pk_add_f32 v[66:67], v[160:161], 1.0 op_sel_hi:[1,0]
	v_pk_mul_f32 v[52:53], v[52:53], v[68:69]
	v_pk_mul_f32 v[50:51], v[50:51], v[66:67]
	v_and_b32_sdwa v66, v53, v170 dst_sel:DWORD dst_unused:UNUSED_PAD src0_sel:WORD_1 src1_sel:DWORD
	v_and_b32_sdwa v67, v51, v170 dst_sel:DWORD dst_unused:UNUSED_PAD src0_sel:WORD_1 src1_sel:DWORD
	v_and_b32_sdwa v63, v52, v170 dst_sel:DWORD dst_unused:UNUSED_PAD src0_sel:WORD_1 src1_sel:DWORD
	v_and_b32_sdwa v65, v50, v170 dst_sel:DWORD dst_unused:UNUSED_PAD src0_sel:WORD_1 src1_sel:DWORD
	v_add3_u32 v53, v53, v66, s56
	v_add3_u32 v51, v51, v67, s56
	v_add3_u32 v50, v50, v65, s56
	v_add3_u32 v52, v52, v63, s56
	v_and_b32_e32 v53, 0xffff0000, v53
	v_and_b32_e32 v63, 0xffff0000, v51
	v_or_b32_sdwa v51, v53, v52 dst_sel:DWORD dst_unused:UNUSED_PAD src0_sel:DWORD src1_sel:WORD_1
	v_or_b32_sdwa v50, v63, v50 dst_sel:DWORD dst_unused:UNUSED_PAD src0_sel:DWORD src1_sel:WORD_1
	global_store_dwordx2 v[54:55], v[50:51], off offset:64
	s_nop 0
	v_pk_fma_f32 v[52:53], v[34:35], v[134:135], v[220:221]
	v_pk_fma_f32 v[50:51], v[32:33], v[132:133], v[218:219]
	global_store_dwordx4 v[74:75], v[50:53], off offset:192
	s_nop 0
	v_mul_f32_e32 v32, v45, v45
	v_mul_f32_e32 v33, v41, v41
	v_fmac_f32_e32 v32, v44, v44
	v_fmac_f32_e32 v33, v40, v40
	v_fmac_f32_e32 v32, v46, v46
	v_fmac_f32_e32 v33, v42, v42
	v_fmac_f32_e32 v32, v47, v47
	v_fmac_f32_e32 v33, v43, v43
	v_add_f32_e32 v32, v32, v33
	v_mul_f32_e32 v33, v37, v37
	v_fmac_f32_e32 v33, v36, v36
	v_fmac_f32_e32 v33, v38, v38
	v_fmac_f32_e32 v33, v39, v39
	v_add_f32_e32 v32, v32, v33
	v_mul_f32_e32 v33, v51, v51
	v_fmac_f32_e32 v33, v50, v50
	v_fmac_f32_e32 v33, v52, v52
	v_fmac_f32_e32 v33, v53, v53
	v_add_f32_e32 v32, v32, v33
	ds_bpermute_b32 v33, v105, v32
	s_waitcnt lgkmcnt(0)
	v_add_f32_e32 v32, v32, v33
	ds_bpermute_b32 v33, v104, v32
	v_pk_mul_f32 v[34:35], v[52:53], v[150:151]
	v_pk_mul_f32 v[36:37], v[50:51], v[148:149]
	v_pk_add_f32 v[38:39], v[182:183], 1.0 op_sel_hi:[1,0]
	v_pk_add_f32 v[40:41], v[180:181], 1.0 op_sel_hi:[1,0]
	v_pk_mul_f32 v[34:35], v[34:35], v[38:39]
	v_pk_mul_f32 v[36:37], v[36:37], v[40:41]
	v_and_b32_sdwa v40, v35, v170 dst_sel:DWORD dst_unused:UNUSED_PAD src0_sel:WORD_1 src1_sel:DWORD
	v_and_b32_sdwa v41, v37, v170 dst_sel:DWORD dst_unused:UNUSED_PAD src0_sel:WORD_1 src1_sel:DWORD
	v_and_b32_sdwa v38, v34, v170 dst_sel:DWORD dst_unused:UNUSED_PAD src0_sel:WORD_1 src1_sel:DWORD
	v_and_b32_sdwa v39, v36, v170 dst_sel:DWORD dst_unused:UNUSED_PAD src0_sel:WORD_1 src1_sel:DWORD
	v_add3_u32 v35, v35, v40, s56
	v_add3_u32 v37, v37, v41, s56
	v_add3_u32 v36, v36, v39, s56
	v_add3_u32 v34, v34, v38, s56
	v_and_b32_e32 v35, 0xffff0000, v35
	v_and_b32_e32 v37, 0xffff0000, v37
	v_or_b32_sdwa v35, v35, v34 dst_sel:DWORD dst_unused:UNUSED_PAD src0_sel:DWORD src1_sel:WORD_1
	v_or_b32_sdwa v34, v37, v36 dst_sel:DWORD dst_unused:UNUSED_PAD src0_sel:DWORD src1_sel:WORD_1
	global_store_dwordx2 v[54:55], v[34:35], off offset:96
	s_and_saveexec_b64 s[24:25], s[36:37]
	s_cbranch_execz .LBB0_97
	s_waitcnt lgkmcnt(0)
	v_add_f32_e32 v32, v32, v33
	global_store_dword v[48:49], v32, off offset:64
.LBB0_97:
	s_or_b64 exec, exec, s[24:25]
	v_add_u32_e32 v32, 0xffffe020, v64
	v_or_b32_e32 v40, 32, v62
	v_lshrrev_b32_e32 v32, 10, v32
	v_mad_u32_u24 v32, v32, s5, s5
	v_cmp_lt_i32_e32 vcc, s13, v40
	v_ashrrev_i32_e32 v41, 31, v40
	v_readlane_b32 s16, v250, 15
	v_cndmask_b32_e32 v32, 0, v32, vcc
	s_waitcnt lgkmcnt(0)
	v_ashrrev_i32_e32 v33, 31, v32
	v_lshlrev_b64 v[42:43], 2, v[32:33]
	v_lshl_add_u64 v[32:33], s[40:41], 0, v[42:43]
	v_lshl_add_u64 v[44:45], v[32:33], 0, v[60:61]
	v_lshlrev_b64 v[32:33], 12, v[40:41]
	v_readlane_b32 s17, v250, 16
	v_lshl_add_u64 v[42:43], s[42:43], 0, v[42:43]
	v_lshl_add_u64 v[42:43], v[42:43], 0, v[60:61]
	v_lshl_add_u64 v[32:33], s[16:17], 0, v[32:33]
	v_lshl_add_u64 v[46:47], v[32:33], 0, v[60:61]
	v_readlane_b32 s16, v250, 21
	v_lshlrev_b64 v[40:41], 11, v[40:41]
	v_readlane_b32 s17, v250, 22
	global_load_dwordx4 v[206:209], v[224:225], off
	global_load_dwordx4 v[210:213], v[224:225], off offset:64
	global_load_dwordx4 v[214:217], v[224:225], off offset:128
	global_load_dwordx4 v[218:221], v[224:225], off offset:192
	s_waitcnt vmcnt(12)
	v_pk_fma_f32 v[30:31], v[30:31], v[118:119], v[192:193]
	v_pk_fma_f32 v[28:29], v[28:29], v[116:117], v[190:191]
	global_store_dwordx4 v[46:47], v[28:31], off
	v_lshl_add_u64 v[40:41], s[16:17], 0, v[40:41]
	v_lshl_add_u64 v[50:51], v[58:59], 1, v[40:41]
	v_pk_mul_f32 v[34:35], v[30:31], v[138:139]
	v_pk_mul_f32 v[32:33], v[28:29], v[136:137]
	v_pk_add_f32 v[38:39], v[154:155], 1.0 op_sel_hi:[1,0]
	v_pk_add_f32 v[36:37], v[152:153], 1.0 op_sel_hi:[1,0]
	v_pk_mul_f32 v[34:35], v[34:35], v[38:39]
	v_pk_mul_f32 v[32:33], v[32:33], v[36:37]
	v_and_b32_sdwa v38, v35, v170 dst_sel:DWORD dst_unused:UNUSED_PAD src0_sel:WORD_1 src1_sel:DWORD
	v_and_b32_sdwa v39, v33, v170 dst_sel:DWORD dst_unused:UNUSED_PAD src0_sel:WORD_1 src1_sel:DWORD
	v_and_b32_sdwa v36, v34, v170 dst_sel:DWORD dst_unused:UNUSED_PAD src0_sel:WORD_1 src1_sel:DWORD
	v_and_b32_sdwa v37, v32, v170 dst_sel:DWORD dst_unused:UNUSED_PAD src0_sel:WORD_1 src1_sel:DWORD
	v_add3_u32 v35, v35, v38, s56
	v_add3_u32 v33, v33, v39, s56
	v_add3_u32 v32, v32, v37, s56
	v_add3_u32 v34, v34, v36, s56
	v_and_b32_e32 v35, 0xffff0000, v35
	v_and_b32_e32 v36, 0xffff0000, v33
	v_or_b32_sdwa v33, v35, v34 dst_sel:DWORD dst_unused:UNUSED_PAD src0_sel:DWORD src1_sel:WORD_1
	v_or_b32_sdwa v32, v36, v32 dst_sel:DWORD dst_unused:UNUSED_PAD src0_sel:DWORD src1_sel:WORD_1
	global_store_dwordx2 v[50:51], v[32:33], off
	s_nop 0
	v_pk_fma_f32 v[26:27], v[26:27], v[122:123], v[196:197]
	v_pk_fma_f32 v[24:25], v[24:25], v[120:121], v[194:195]
	global_store_dwordx4 v[46:47], v[24:27], off offset:64
	v_pk_mul_f32 v[34:35], v[26:27], v[142:143]
	v_pk_mul_f32 v[32:33], v[24:25], v[140:141]
	v_pk_add_f32 v[38:39], v[158:159], 1.0 op_sel_hi:[1,0]
	v_pk_add_f32 v[36:37], v[156:157], 1.0 op_sel_hi:[1,0]
	v_pk_mul_f32 v[34:35], v[34:35], v[38:39]
	v_pk_mul_f32 v[32:33], v[32:33], v[36:37]
	v_and_b32_sdwa v38, v35, v170 dst_sel:DWORD dst_unused:UNUSED_PAD src0_sel:WORD_1 src1_sel:DWORD
	v_and_b32_sdwa v39, v33, v170 dst_sel:DWORD dst_unused:UNUSED_PAD src0_sel:WORD_1 src1_sel:DWORD
	v_and_b32_sdwa v36, v34, v170 dst_sel:DWORD dst_unused:UNUSED_PAD src0_sel:WORD_1 src1_sel:DWORD
	v_and_b32_sdwa v37, v32, v170 dst_sel:DWORD dst_unused:UNUSED_PAD src0_sel:WORD_1 src1_sel:DWORD
	v_add3_u32 v35, v35, v38, s56
	v_add3_u32 v33, v33, v39, s56
	v_add3_u32 v32, v32, v37, s56
	v_add3_u32 v34, v34, v36, s56
	v_and_b32_e32 v35, 0xffff0000, v35
	v_and_b32_e32 v36, 0xffff0000, v33
	v_or_b32_sdwa v33, v35, v34 dst_sel:DWORD dst_unused:UNUSED_PAD src0_sel:DWORD src1_sel:WORD_1
	v_or_b32_sdwa v32, v36, v32 dst_sel:DWORD dst_unused:UNUSED_PAD src0_sel:DWORD src1_sel:WORD_1
	global_store_dwordx2 v[50:51], v[32:33], off offset:32
	s_nop 0
	v_pk_fma_f32 v[22:23], v[22:23], v[126:127], v[200:201]
	v_pk_fma_f32 v[20:21], v[20:21], v[124:125], v[198:199]
	global_store_dwordx4 v[46:47], v[20:23], off offset:128
	v_pk_mul_f32 v[34:35], v[22:23], v[146:147]
	v_pk_mul_f32 v[32:33], v[20:21], v[144:145]
	v_pk_add_f32 v[38:39], v[162:163], 1.0 op_sel_hi:[1,0]
	v_pk_add_f32 v[36:37], v[160:161], 1.0 op_sel_hi:[1,0]
	v_pk_mul_f32 v[34:35], v[34:35], v[38:39]
	v_pk_mul_f32 v[32:33], v[32:33], v[36:37]
	v_and_b32_sdwa v38, v35, v170 dst_sel:DWORD dst_unused:UNUSED_PAD src0_sel:WORD_1 src1_sel:DWORD
	v_and_b32_sdwa v39, v33, v170 dst_sel:DWORD dst_unused:UNUSED_PAD src0_sel:WORD_1 src1_sel:DWORD
	v_and_b32_sdwa v36, v34, v170 dst_sel:DWORD dst_unused:UNUSED_PAD src0_sel:WORD_1 src1_sel:DWORD
	v_and_b32_sdwa v37, v32, v170 dst_sel:DWORD dst_unused:UNUSED_PAD src0_sel:WORD_1 src1_sel:DWORD
	v_add3_u32 v35, v35, v38, s56
	v_add3_u32 v33, v33, v39, s56
	v_add3_u32 v32, v32, v37, s56
	v_add3_u32 v34, v34, v36, s56
	v_and_b32_e32 v35, 0xffff0000, v35
	v_and_b32_e32 v36, 0xffff0000, v33
	v_or_b32_sdwa v33, v35, v34 dst_sel:DWORD dst_unused:UNUSED_PAD src0_sel:DWORD src1_sel:WORD_1
	v_or_b32_sdwa v32, v36, v32 dst_sel:DWORD dst_unused:UNUSED_PAD src0_sel:DWORD src1_sel:WORD_1
	global_store_dwordx2 v[50:51], v[32:33], off offset:64
	s_nop 0
	v_pk_fma_f32 v[34:35], v[18:19], v[134:135], v[204:205]
	v_pk_fma_f32 v[32:33], v[16:17], v[132:133], v[202:203]
	global_store_dwordx4 v[46:47], v[32:35], off offset:192
	s_nop 0
	v_mul_f32_e32 v16, v29, v29
	v_mul_f32_e32 v17, v25, v25
	v_fmac_f32_e32 v16, v28, v28
	v_fmac_f32_e32 v17, v24, v24
	v_fmac_f32_e32 v16, v30, v30
	v_fmac_f32_e32 v17, v26, v26
	v_fmac_f32_e32 v16, v31, v31
	v_fmac_f32_e32 v17, v27, v27
	v_add_f32_e32 v16, v16, v17
	v_mul_f32_e32 v17, v21, v21
	v_fmac_f32_e32 v17, v20, v20
	v_fmac_f32_e32 v17, v22, v22
	v_fmac_f32_e32 v17, v23, v23
	v_add_f32_e32 v16, v16, v17
	v_mul_f32_e32 v17, v33, v33
	v_fmac_f32_e32 v17, v32, v32
	v_fmac_f32_e32 v17, v34, v34
	v_fmac_f32_e32 v17, v35, v35
	v_add_f32_e32 v16, v16, v17
	ds_bpermute_b32 v17, v105, v16
	s_waitcnt lgkmcnt(0)
	v_add_f32_e32 v16, v16, v17
	ds_bpermute_b32 v17, v104, v16
	v_pk_mul_f32 v[18:19], v[34:35], v[150:151]
	v_pk_mul_f32 v[20:21], v[32:33], v[148:149]
	v_pk_add_f32 v[22:23], v[182:183], 1.0 op_sel_hi:[1,0]
	v_pk_add_f32 v[24:25], v[180:181], 1.0 op_sel_hi:[1,0]
	v_pk_mul_f32 v[18:19], v[18:19], v[22:23]
	v_pk_mul_f32 v[20:21], v[20:21], v[24:25]
	v_and_b32_sdwa v24, v19, v170 dst_sel:DWORD dst_unused:UNUSED_PAD src0_sel:WORD_1 src1_sel:DWORD
	v_and_b32_sdwa v25, v21, v170 dst_sel:DWORD dst_unused:UNUSED_PAD src0_sel:WORD_1 src1_sel:DWORD
	v_and_b32_sdwa v22, v18, v170 dst_sel:DWORD dst_unused:UNUSED_PAD src0_sel:WORD_1 src1_sel:DWORD
	v_and_b32_sdwa v23, v20, v170 dst_sel:DWORD dst_unused:UNUSED_PAD src0_sel:WORD_1 src1_sel:DWORD
	v_add3_u32 v19, v19, v24, s56
	v_add3_u32 v21, v21, v25, s56
	v_add3_u32 v20, v20, v23, s56
	v_add3_u32 v18, v18, v22, s56
	v_and_b32_e32 v19, 0xffff0000, v19
	v_and_b32_e32 v21, 0xffff0000, v21
	v_or_b32_sdwa v19, v19, v18 dst_sel:DWORD dst_unused:UNUSED_PAD src0_sel:DWORD src1_sel:WORD_1
	v_or_b32_sdwa v18, v21, v20 dst_sel:DWORD dst_unused:UNUSED_PAD src0_sel:DWORD src1_sel:WORD_1
	global_store_dwordx2 v[50:51], v[18:19], off offset:96
	s_and_saveexec_b64 s[24:25], s[36:37]
	s_movk_i32 s8, 0x400
	s_mov_b32 s5, 0xffff0000
	s_mov_b32 s9, 0x12000
	s_movk_i32 s89, 0xff
	s_mov_b64 s[78:79], s[50:51]
	s_cbranch_execz .LBB0_99
	s_waitcnt lgkmcnt(0)
	v_add_f32_e32 v16, v16, v17
	global_store_dword v[48:49], v16, off offset:128
.LBB0_99:
	s_or_b64 exec, exec, s[24:25]
	v_add_u32_e32 v16, 0xffffe030, v64
	v_or_b32_e32 v24, 48, v62
	v_lshrrev_b32_e32 v16, 10, v16
	s_movk_i32 s16, 0x1800
	v_mad_u32_u24 v16, v16, s16, s16
	v_cmp_lt_i32_e32 vcc, s13, v24
	v_ashrrev_i32_e32 v25, 31, v24
	v_readlane_b32 s16, v250, 15
	v_cndmask_b32_e32 v16, 0, v16, vcc
	s_waitcnt lgkmcnt(0)
	v_ashrrev_i32_e32 v17, 31, v16
	v_lshlrev_b64 v[26:27], 2, v[16:17]
	v_lshl_add_u64 v[16:17], s[40:41], 0, v[26:27]
	v_lshl_add_u64 v[28:29], v[16:17], 0, v[60:61]
	v_lshlrev_b64 v[16:17], 12, v[24:25]
	v_readlane_b32 s17, v250, 16
	v_lshl_add_u64 v[26:27], s[42:43], 0, v[26:27]
	v_lshl_add_u64 v[26:27], v[26:27], 0, v[60:61]
	v_lshl_add_u64 v[16:17], s[16:17], 0, v[16:17]
	v_lshl_add_u64 v[30:31], v[16:17], 0, v[60:61]
	v_readlane_b32 s16, v250, 21
	v_lshlrev_b64 v[24:25], 11, v[24:25]
	v_readlane_b32 s17, v250, 22
	s_waitcnt vmcnt(8)
	v_pk_fma_f32 v[14:15], v[14:15], v[118:119], v[208:209]
	v_pk_fma_f32 v[12:13], v[12:13], v[116:117], v[206:207]
	global_store_dwordx4 v[30:31], v[12:15], off
	v_lshl_add_u64 v[24:25], s[16:17], 0, v[24:25]
	v_lshl_add_u64 v[32:33], v[58:59], 1, v[24:25]
	v_pk_mul_f32 v[18:19], v[14:15], v[138:139]
	v_pk_mul_f32 v[16:17], v[12:13], v[136:137]
	v_pk_add_f32 v[22:23], v[154:155], 1.0 op_sel_hi:[1,0]
	v_pk_add_f32 v[20:21], v[152:153], 1.0 op_sel_hi:[1,0]
	v_pk_mul_f32 v[18:19], v[18:19], v[22:23]
	v_pk_mul_f32 v[16:17], v[16:17], v[20:21]
	v_and_b32_sdwa v22, v19, v170 dst_sel:DWORD dst_unused:UNUSED_PAD src0_sel:WORD_1 src1_sel:DWORD
	v_and_b32_sdwa v23, v17, v170 dst_sel:DWORD dst_unused:UNUSED_PAD src0_sel:WORD_1 src1_sel:DWORD
	v_and_b32_sdwa v20, v18, v170 dst_sel:DWORD dst_unused:UNUSED_PAD src0_sel:WORD_1 src1_sel:DWORD
	v_and_b32_sdwa v21, v16, v170 dst_sel:DWORD dst_unused:UNUSED_PAD src0_sel:WORD_1 src1_sel:DWORD
	v_add3_u32 v19, v19, v22, s56
	v_add3_u32 v17, v17, v23, s56
	v_add3_u32 v16, v16, v21, s56
	v_add3_u32 v18, v18, v20, s56
	v_and_b32_e32 v19, 0xffff0000, v19
	v_and_b32_e32 v20, 0xffff0000, v17
	v_or_b32_sdwa v17, v19, v18 dst_sel:DWORD dst_unused:UNUSED_PAD src0_sel:DWORD src1_sel:WORD_1
	v_or_b32_sdwa v16, v20, v16 dst_sel:DWORD dst_unused:UNUSED_PAD src0_sel:DWORD src1_sel:WORD_1
	global_store_dwordx2 v[32:33], v[16:17], off
	s_nop 0
	v_pk_fma_f32 v[10:11], v[10:11], v[122:123], v[212:213]
	v_pk_fma_f32 v[8:9], v[8:9], v[120:121], v[210:211]
	global_store_dwordx4 v[30:31], v[8:11], off offset:64
	v_pk_mul_f32 v[18:19], v[10:11], v[142:143]
	v_pk_mul_f32 v[16:17], v[8:9], v[140:141]
	v_pk_add_f32 v[22:23], v[158:159], 1.0 op_sel_hi:[1,0]
	v_pk_add_f32 v[20:21], v[156:157], 1.0 op_sel_hi:[1,0]
	v_pk_mul_f32 v[18:19], v[18:19], v[22:23]
	v_pk_mul_f32 v[16:17], v[16:17], v[20:21]
	v_and_b32_sdwa v22, v19, v170 dst_sel:DWORD dst_unused:UNUSED_PAD src0_sel:WORD_1 src1_sel:DWORD
	v_and_b32_sdwa v23, v17, v170 dst_sel:DWORD dst_unused:UNUSED_PAD src0_sel:WORD_1 src1_sel:DWORD
	v_and_b32_sdwa v20, v18, v170 dst_sel:DWORD dst_unused:UNUSED_PAD src0_sel:WORD_1 src1_sel:DWORD
	v_and_b32_sdwa v21, v16, v170 dst_sel:DWORD dst_unused:UNUSED_PAD src0_sel:WORD_1 src1_sel:DWORD
	v_add3_u32 v19, v19, v22, s56
	v_add3_u32 v17, v17, v23, s56
	v_add3_u32 v16, v16, v21, s56
	v_add3_u32 v18, v18, v20, s56
	v_and_b32_e32 v19, 0xffff0000, v19
	v_and_b32_e32 v20, 0xffff0000, v17
	v_or_b32_sdwa v17, v19, v18 dst_sel:DWORD dst_unused:UNUSED_PAD src0_sel:DWORD src1_sel:WORD_1
	v_or_b32_sdwa v16, v20, v16 dst_sel:DWORD dst_unused:UNUSED_PAD src0_sel:DWORD src1_sel:WORD_1
	global_store_dwordx2 v[32:33], v[16:17], off offset:32
	s_nop 0
	v_pk_fma_f32 v[6:7], v[6:7], v[126:127], v[216:217]
	v_pk_fma_f32 v[4:5], v[4:5], v[124:125], v[214:215]
	global_store_dwordx4 v[30:31], v[4:7], off offset:128
	v_pk_mul_f32 v[18:19], v[6:7], v[146:147]
	v_pk_mul_f32 v[16:17], v[4:5], v[144:145]
	v_pk_add_f32 v[22:23], v[162:163], 1.0 op_sel_hi:[1,0]
	v_pk_add_f32 v[20:21], v[160:161], 1.0 op_sel_hi:[1,0]
	v_pk_mul_f32 v[18:19], v[18:19], v[22:23]
	v_pk_mul_f32 v[16:17], v[16:17], v[20:21]
	v_and_b32_sdwa v22, v19, v170 dst_sel:DWORD dst_unused:UNUSED_PAD src0_sel:WORD_1 src1_sel:DWORD
	v_and_b32_sdwa v23, v17, v170 dst_sel:DWORD dst_unused:UNUSED_PAD src0_sel:WORD_1 src1_sel:DWORD
	v_and_b32_sdwa v20, v18, v170 dst_sel:DWORD dst_unused:UNUSED_PAD src0_sel:WORD_1 src1_sel:DWORD
	v_and_b32_sdwa v21, v16, v170 dst_sel:DWORD dst_unused:UNUSED_PAD src0_sel:WORD_1 src1_sel:DWORD
	v_add3_u32 v19, v19, v22, s56
	v_add3_u32 v17, v17, v23, s56
	v_add3_u32 v16, v16, v21, s56
	v_add3_u32 v18, v18, v20, s56
	v_and_b32_e32 v19, 0xffff0000, v19
	v_and_b32_e32 v20, 0xffff0000, v17
	v_or_b32_sdwa v17, v19, v18 dst_sel:DWORD dst_unused:UNUSED_PAD src0_sel:DWORD src1_sel:WORD_1
	v_or_b32_sdwa v16, v20, v16 dst_sel:DWORD dst_unused:UNUSED_PAD src0_sel:DWORD src1_sel:WORD_1
	global_store_dwordx2 v[32:33], v[16:17], off offset:64
	s_nop 0
	v_pk_fma_f32 v[18:19], v[2:3], v[134:135], v[220:221]
	v_pk_fma_f32 v[16:17], v[0:1], v[132:133], v[218:219]
	global_store_dwordx4 v[30:31], v[16:19], off offset:192
	s_nop 0
	v_mul_f32_e32 v0, v13, v13
	v_mul_f32_e32 v1, v9, v9
	v_fmac_f32_e32 v0, v12, v12
	v_fmac_f32_e32 v1, v8, v8
	v_fmac_f32_e32 v0, v14, v14
	v_fmac_f32_e32 v1, v10, v10
	v_fmac_f32_e32 v0, v15, v15
	v_fmac_f32_e32 v1, v11, v11
	v_add_f32_e32 v0, v0, v1
	v_mul_f32_e32 v1, v5, v5
	v_fmac_f32_e32 v1, v4, v4
	v_fmac_f32_e32 v1, v6, v6
	v_fmac_f32_e32 v1, v7, v7
	v_add_f32_e32 v0, v0, v1
	v_mul_f32_e32 v1, v17, v17
	v_fmac_f32_e32 v1, v16, v16
	v_fmac_f32_e32 v1, v18, v18
	v_fmac_f32_e32 v1, v19, v19
	v_add_f32_e32 v0, v0, v1
	ds_bpermute_b32 v1, v105, v0
	s_waitcnt lgkmcnt(0)
	v_add_f32_e32 v0, v0, v1
	ds_bpermute_b32 v1, v104, v0
	v_pk_mul_f32 v[2:3], v[18:19], v[150:151]
	v_pk_mul_f32 v[4:5], v[16:17], v[148:149]
	v_pk_add_f32 v[6:7], v[182:183], 1.0 op_sel_hi:[1,0]
	v_pk_add_f32 v[8:9], v[180:181], 1.0 op_sel_hi:[1,0]
	v_pk_mul_f32 v[2:3], v[2:3], v[6:7]
	v_pk_mul_f32 v[4:5], v[4:5], v[8:9]
	v_and_b32_sdwa v8, v3, v170 dst_sel:DWORD dst_unused:UNUSED_PAD src0_sel:WORD_1 src1_sel:DWORD
	v_and_b32_sdwa v9, v5, v170 dst_sel:DWORD dst_unused:UNUSED_PAD src0_sel:WORD_1 src1_sel:DWORD
	v_and_b32_sdwa v6, v2, v170 dst_sel:DWORD dst_unused:UNUSED_PAD src0_sel:WORD_1 src1_sel:DWORD
	v_and_b32_sdwa v7, v4, v170 dst_sel:DWORD dst_unused:UNUSED_PAD src0_sel:WORD_1 src1_sel:DWORD
	v_add3_u32 v3, v3, v8, s56
	v_add3_u32 v5, v5, v9, s56
	v_add3_u32 v4, v4, v7, s56
	v_add3_u32 v2, v2, v6, s56
	v_and_b32_e32 v3, 0xffff0000, v3
	v_and_b32_e32 v5, 0xffff0000, v5
	v_or_b32_sdwa v3, v3, v2 dst_sel:DWORD dst_unused:UNUSED_PAD src0_sel:DWORD src1_sel:WORD_1
	v_or_b32_sdwa v2, v5, v4 dst_sel:DWORD dst_unused:UNUSED_PAD src0_sel:DWORD src1_sel:WORD_1
	global_store_dwordx2 v[32:33], v[2:3], off offset:96
	s_and_saveexec_b64 s[24:25], s[36:37]
	s_cbranch_execz .LBB0_101
	s_waitcnt lgkmcnt(0)
	v_add_f32_e32 v0, v0, v1
	global_store_dword v[48:49], v0, off offset:192

.LBB0_119:
	s_add_i32 s2, s3, 2
	s_setprio 1
	v_add_u32_e32 v127, v89, v90
	ds_read_b128 v[100:103], v127 offset:16384
	ds_read_b128 v[106:109], v127 offset:18432
	ds_read_b128 v[110:113], v127 offset:20480
	ds_read_b128 v[114:117], v127 offset:22528
	v_add_u32_e32 v126, v88, v90
	ds_read_b128 v[92:95], v126
	ds_read_b128 v[96:99], v126 offset:2048
	s_add_i32 s3, s3, 4
	s_min_u32 s3, s3, 15
	v_add_u32_e32 v128, v88, v91
	v_add_u32_e32 v130, v89, v91
	s_lshl_b32 s92, s3, 7
	ds_read_b128 v[118:121], v130 offset:18432
	ds_read_b128 v[122:125], v130 offset:20480
	ds_read_b128 v[132:135], v130 offset:22528
	s_waitcnt lgkmcnt(4)
	v_mfma_f32_16x16x32_bf16 v[76:79], v[100:103], v[92:95], v[76:79]
	v_lshl_add_u64 v[44:45], v[80:81], 0, s[92:93]
	v_add_co_u32_e32 v46, vcc, s11, v44
	v_mfma_f32_16x16x32_bf16 v[68:71], v[106:109], v[92:95], v[68:71]
	s_nop 0
	v_addc_co_u32_e32 v47, vcc, 0, v45, vcc
	v_mfma_f32_16x16x32_bf16 v[52:55], v[110:113], v[92:95], v[52:55]
	v_mfma_f32_16x16x32_bf16 v[40:43], v[114:117], v[92:95], v[40:43]
	s_waitcnt lgkmcnt(3)
	v_mfma_f32_16x16x32_bf16 v[92:95], v[100:103], v[96:99], v[36:39]
	s_nop 2
	ds_read_b128 v[36:39], v128
	v_mfma_f32_16x16x32_bf16 v[100:103], v[106:109], v[96:99], v[8:11]
	v_mfma_f32_16x16x32_bf16 v[106:109], v[110:113], v[96:99], v[4:7]
	ds_read_b128 v[110:113], v128 offset:2048
	v_mfma_f32_16x16x32_bf16 v[96:99], v[114:117], v[96:99], v[0:3]
	ds_read_b128 v[114:117], v130 offset:16384
	global_load_dwordx4 v[72:75], v[44:45], off
	s_waitcnt vmcnt(1)
	ds_write_b128 v87, v[12:15] offset:53248
	global_load_dwordx4 v[64:67], v[46:47], off
	v_add_co_u32_e32 v46, vcc, s33, v44
	ds_write_b128 v87, v[16:19] offset:49152
	s_nop 0
	v_addc_co_u32_e32 v47, vcc, 0, v45, vcc
	v_add_co_u32_e32 v44, vcc, s59, v44
	global_load_dwordx4 v[60:63], v[46:47], off
	s_nop 0
	v_addc_co_u32_e32 v45, vcc, 0, v45, vcc
	ds_write_b128 v87, v[20:23] offset:45056
	global_load_dwordx4 v[56:59], v[44:45], off
	v_lshl_add_u64 v[44:45], v[82:83], 0, s[92:93]
	ds_write_b128 v87, v[28:31] offset:32768
	s_waitcnt lgkmcnt(4)
	v_mfma_f32_16x16x32_bf16 v[0:3], v[114:117], v[36:39], v[76:79]
	v_mfma_f32_16x16x32_bf16 v[4:7], v[118:121], v[36:39], v[68:71]
	global_load_dwordx4 v[48:51], v[44:45], off
	v_add_co_u32_e32 v44, vcc, s11, v44
	ds_write_b128 v87, v[32:35] offset:36864
	s_nop 0
	v_addc_co_u32_e32 v45, vcc, 0, v45, vcc
	v_mfma_f32_16x16x32_bf16 v[8:11], v[122:125], v[36:39], v[52:55]
	v_mfma_f32_16x16x32_bf16 v[36:39], v[132:135], v[36:39], v[40:43]
	global_load_dwordx4 v[44:47], v[44:45], off
	ds_write_b128 v87, v[24:27] offset:40960
	v_mfma_f32_16x16x32_bf16 v[40:43], v[114:117], v[110:113], v[92:95]
	v_mfma_f32_16x16x32_bf16 v[52:55], v[118:121], v[110:113], v[100:103]
	v_mfma_f32_16x16x32_bf16 v[68:71], v[122:125], v[110:113], v[106:109]
	v_mfma_f32_16x16x32_bf16 v[76:79], v[132:135], v[110:113], v[96:99]
	s_setprio 0
	s_waitcnt lgkmcnt(0)
	s_barrier
	s_setprio 1
	ds_read_b128 v[100:103], v127 offset:49152
	ds_read_b128 v[106:109], v127 offset:51200
	ds_read_b128 v[110:113], v127 offset:53248
	ds_read_b128 v[114:117], v127 offset:55296
	ds_read_b128 v[92:95], v126 offset:32768
	ds_read_b128 v[96:99], v126 offset:34816
	s_min_u32 s3, s2, 12
	s_lshl_b32 s92, s3, 7
	ds_read_b128 v[118:121], v130 offset:51200
	ds_read_b128 v[122:125], v130 offset:53248
	ds_read_b128 v[132:135], v130 offset:55296
	s_waitcnt lgkmcnt(4)
	v_mfma_f32_16x16x32_bf16 v[0:3], v[100:103], v[92:95], v[0:3]
	v_lshl_add_u64 v[12:13], v[80:81], 0, s[92:93]
	v_add_co_u32_e32 v14, vcc, s11, v12
	v_mfma_f32_16x16x32_bf16 v[4:7], v[106:109], v[92:95], v[4:7]
	s_nop 0
	v_addc_co_u32_e32 v15, vcc, 0, v13, vcc
	v_mfma_f32_16x16x32_bf16 v[8:11], v[110:113], v[92:95], v[8:11]
	v_mfma_f32_16x16x32_bf16 v[36:39], v[114:117], v[92:95], v[36:39]
	s_waitcnt lgkmcnt(3)
	v_mfma_f32_16x16x32_bf16 v[92:95], v[100:103], v[96:99], v[40:43]
	s_nop 2
	ds_read_b128 v[40:43], v128 offset:32768
	v_mfma_f32_16x16x32_bf16 v[100:103], v[106:109], v[96:99], v[52:55]
	v_mfma_f32_16x16x32_bf16 v[106:109], v[110:113], v[96:99], v[68:71]
	ds_read_b128 v[110:113], v128 offset:34816
	v_mfma_f32_16x16x32_bf16 v[96:99], v[114:117], v[96:99], v[76:79]
	ds_read_b128 v[114:117], v130 offset:49152
	global_load_dwordx4 v[28:31], v[12:13], off offset:384
	s_waitcnt vmcnt(1)
	ds_write_b128 v87, v[44:47] offset:20480
	global_load_dwordx4 v[32:35], v[14:15], off offset:384
	v_add_co_u32_e32 v14, vcc, s33, v12
	ds_write_b128 v87, v[48:51] offset:16384
	s_nop 0
	v_addc_co_u32_e32 v15, vcc, 0, v13, vcc
	v_add_co_u32_e32 v12, vcc, s59, v12
	global_load_dwordx4 v[24:27], v[14:15], off offset:384
	s_nop 0
	v_addc_co_u32_e32 v13, vcc, 0, v13, vcc
	ds_write_b128 v87, v[56:59] offset:12288
	global_load_dwordx4 v[20:23], v[12:13], off offset:384
	v_lshl_add_u64 v[12:13], v[82:83], 0, s[92:93]
	ds_write_b128 v87, v[72:75]
	s_waitcnt lgkmcnt(4)
	v_mfma_f32_16x16x32_bf16 v[76:79], v[114:117], v[40:43], v[0:3]
	v_mfma_f32_16x16x32_bf16 v[68:71], v[118:121], v[40:43], v[4:7]
	global_load_dwordx4 v[16:19], v[12:13], off offset:384
	v_add_co_u32_e32 v12, vcc, s11, v12
	ds_write_b128 v87, v[64:67] offset:4096
	s_nop 0
	v_addc_co_u32_e32 v13, vcc, 0, v13, vcc
	v_mfma_f32_16x16x32_bf16 v[52:55], v[122:125], v[40:43], v[8:11]
	v_mfma_f32_16x16x32_bf16 v[40:43], v[132:135], v[40:43], v[36:39]
	global_load_dwordx4 v[12:15], v[12:13], off offset:384
	ds_write_b128 v87, v[60:63] offset:8192
	v_mfma_f32_16x16x32_bf16 v[36:39], v[114:117], v[110:113], v[92:95]
	v_mfma_f32_16x16x32_bf16 v[8:11], v[118:121], v[110:113], v[100:103]
	v_mfma_f32_16x16x32_bf16 v[4:7], v[122:125], v[110:113], v[106:109]
	v_mfma_f32_16x16x32_bf16 v[0:3], v[132:135], v[110:113], v[96:99]
	s_setprio 0
	s_cmp_lt_u32 s2, 14
	s_mov_b32 s3, s2
	s_waitcnt lgkmcnt(0)
	s_barrier
	s_cbranch_scc1 .LBB0_119
	v_readlane_b32 s2, v251, 18
	s_waitcnt vmcnt(1)
	s_nop 0
	v_add_u32_e32 v18, s2, v86
	v_readlane_b32 s2, v251, 19
	s_waitcnt vmcnt(0)
	v_add_u32_e32 v13, 0xffffe000, v18
	v_or_b32_e32 v12, v18, v85
	v_lshl_or_b32 v19, v84, 2, s2
	v_lshrrev_b32_e32 v13, 10, v13
	s_movk_i32 s2, 0x1800
	v_mad_u32_u24 v13, v13, s2, s2
	v_cmp_lt_i32_e32 vcc, s13, v12
	v_lshlrev_b32_e32 v128, 2, v19
	v_readlane_b32 s2, v250, 15
	v_cndmask_b32_e32 v14, 0, v13, vcc
	v_ashrrev_i32_e32 v15, 31, v14
	v_lshlrev_b64 v[24:25], 2, v[14:15]
	v_ashrrev_i32_e32 v13, 31, v12
	v_lshl_add_u64 v[14:15], s[40:41], 0, v[24:25]
	v_lshl_add_u64 v[48:49], v[14:15], 0, v[128:129]
	v_lshlrev_b64 v[14:15], 12, v[12:13]
	v_readlane_b32 s3, v250, 16
	v_lshl_add_u64 v[28:29], s[42:43], 0, v[24:25]
	v_lshlrev_b64 v[32:33], 11, v[12:13]
	v_lshl_add_u64 v[14:15], s[2:3], 0, v[14:15]
	v_lshl_add_u64 v[50:51], v[14:15], 0, v[128:129]
	global_load_dwordx4 v[72:75], v[48:49], off
	global_load_dwordx4 v[80:83], v[48:49], off offset:64
	global_load_dwordx4 v[88:91], v[48:49], off offset:128
	global_load_dwordx4 v[136:139], v[48:49], off offset:192
	global_load_dwordx4 v[194:197], v[50:51], off
	global_load_dwordx4 v[198:201], v[50:51], off offset:64
	global_load_dwordx4 v[202:205], v[50:51], off offset:128
	global_load_dwordx4 v[206:209], v[50:51], off offset:192
	v_add_co_u32_e32 v58, vcc, 0x10000, v50
	s_nop 1
	v_addc_co_u32_e32 v59, vcc, 0, v51, vcc
	global_load_dwordx4 v[210:213], v[58:59], off
	global_load_dwordx4 v[214:217], v[58:59], off offset:64
	global_load_dwordx4 v[218:221], v[58:59], off offset:128
	global_load_dwordx4 v[222:225], v[58:59], off offset:192
	v_readlane_b32 s2, v250, 21
	v_readlane_b32 s3, v250, 22
	v_cmp_eq_u32_e32 vcc, 0, v84
	s_waitcnt vmcnt(4)
	v_pk_fma_f32 v[22:23], v[78:79], v[74:75], v[196:197]
	v_pk_fma_f32 v[20:21], v[76:77], v[72:73], v[194:195]
	global_store_dwordx4 v[50:51], v[20:23], off
	v_lshl_add_u64 v[14:15], v[28:29], 0, v[128:129]
	global_load_dwordx4 v[140:143], v128, s[0:1]
	global_load_dwordx4 v[144:147], v128, s[0:1] offset:64
	global_load_dwordx4 v[148:151], v128, s[0:1] offset:128
	global_load_dwordx4 v[152:155], v128, s[0:1] offset:192
	global_load_dwordx4 v[156:159], v[14:15], off
	global_load_dwordx4 v[160:163], v[14:15], off offset:64
	global_load_dwordx4 v[180:183], v[14:15], off offset:128
	global_load_dwordx4 v[190:193], v[14:15], off offset:192
	v_lshlrev_b32_e32 v16, 1, v19
	v_mov_b32_e32 v17, v129
	v_lshl_add_u64 v[32:33], s[2:3], 0, v[32:33]
	v_lshl_add_u64 v[56:57], v[32:33], 0, v[16:17]
	s_waitcnt vmcnt(0)
	v_pk_mul_f32 v[26:27], v[22:23], v[142:143]
	v_pk_mul_f32 v[24:25], v[20:21], v[140:141]
	s_waitcnt vmcnt(0)
	v_pk_add_f32 v[30:31], v[158:159], 1.0 op_sel_hi:[1,0]
	v_pk_add_f32 v[28:29], v[156:157], 1.0 op_sel_hi:[1,0]
	v_pk_mul_f32 v[26:27], v[26:27], v[30:31]
	v_pk_mul_f32 v[24:25], v[24:25], v[28:29]
	v_and_b32_sdwa v19, v26, v170 dst_sel:DWORD dst_unused:UNUSED_PAD src0_sel:WORD_1 src1_sel:DWORD
	v_and_b32_sdwa v29, v27, v170 dst_sel:DWORD dst_unused:UNUSED_PAD src0_sel:WORD_1 src1_sel:DWORD
	v_and_b32_sdwa v30, v25, v170 dst_sel:DWORD dst_unused:UNUSED_PAD src0_sel:WORD_1 src1_sel:DWORD
	v_and_b32_sdwa v28, v24, v170 dst_sel:DWORD dst_unused:UNUSED_PAD src0_sel:WORD_1 src1_sel:DWORD
	v_add3_u32 v19, v26, v19, s56
	v_add3_u32 v26, v27, v29, s56
	v_add3_u32 v25, v25, v30, s56
	v_add3_u32 v24, v24, v28, s56
	v_and_b32_e32 v26, 0xffff0000, v26
	v_and_b32_e32 v27, 0xffff0000, v25
	v_or_b32_sdwa v25, v26, v19 dst_sel:DWORD dst_unused:UNUSED_PAD src0_sel:DWORD src1_sel:WORD_1
	v_or_b32_sdwa v24, v27, v24 dst_sel:DWORD dst_unused:UNUSED_PAD src0_sel:DWORD src1_sel:WORD_1
	global_store_dwordx2 v[56:57], v[24:25], off
	s_nop 0
	s_waitcnt vmcnt(0)
	v_pk_fma_f32 v[26:27], v[70:71], v[82:83], v[200:201]
	v_pk_fma_f32 v[24:25], v[68:69], v[80:81], v[198:199]
	global_store_dwordx4 v[50:51], v[24:27], off offset:64
	v_pk_mul_f32 v[30:31], v[26:27], v[146:147]
	v_pk_mul_f32 v[28:29], v[24:25], v[144:145]
	v_pk_add_f32 v[34:35], v[162:163], 1.0 op_sel_hi:[1,0]
	v_pk_add_f32 v[32:33], v[160:161], 1.0 op_sel_hi:[1,0]
	v_pk_mul_f32 v[30:31], v[30:31], v[34:35]
	v_pk_mul_f32 v[28:29], v[28:29], v[32:33]
	v_and_b32_sdwa v19, v30, v170 dst_sel:DWORD dst_unused:UNUSED_PAD src0_sel:WORD_1 src1_sel:DWORD
	v_and_b32_sdwa v33, v31, v170 dst_sel:DWORD dst_unused:UNUSED_PAD src0_sel:WORD_1 src1_sel:DWORD
	v_and_b32_sdwa v34, v29, v170 dst_sel:DWORD dst_unused:UNUSED_PAD src0_sel:WORD_1 src1_sel:DWORD
	v_and_b32_sdwa v32, v28, v170 dst_sel:DWORD dst_unused:UNUSED_PAD src0_sel:WORD_1 src1_sel:DWORD
	v_add3_u32 v19, v30, v19, s56
	v_add3_u32 v30, v31, v33, s56
	v_add3_u32 v29, v29, v34, s56
	v_add3_u32 v28, v28, v32, s56
	v_and_b32_e32 v30, 0xffff0000, v30
	v_and_b32_e32 v31, 0xffff0000, v29
	v_or_b32_sdwa v29, v30, v19 dst_sel:DWORD dst_unused:UNUSED_PAD src0_sel:DWORD src1_sel:WORD_1
	v_or_b32_sdwa v28, v31, v28 dst_sel:DWORD dst_unused:UNUSED_PAD src0_sel:DWORD src1_sel:WORD_1
	global_store_dwordx2 v[56:57], v[28:29], off offset:32
	s_nop 0
	v_pk_fma_f32 v[30:31], v[54:55], v[90:91], v[204:205]
	v_pk_fma_f32 v[28:29], v[52:53], v[88:89], v[202:203]
	global_store_dwordx4 v[50:51], v[28:31], off offset:128
	v_pk_mul_f32 v[34:35], v[30:31], v[150:151]
	v_pk_mul_f32 v[32:33], v[28:29], v[148:149]
	v_pk_add_f32 v[46:47], v[182:183], 1.0 op_sel_hi:[1,0]
	v_pk_add_f32 v[44:45], v[180:181], 1.0 op_sel_hi:[1,0]
	v_pk_mul_f32 v[34:35], v[34:35], v[46:47]
	v_pk_mul_f32 v[32:33], v[32:33], v[44:45]
	v_and_b32_sdwa v19, v34, v170 dst_sel:DWORD dst_unused:UNUSED_PAD src0_sel:WORD_1 src1_sel:DWORD
	v_and_b32_sdwa v45, v35, v170 dst_sel:DWORD dst_unused:UNUSED_PAD src0_sel:WORD_1 src1_sel:DWORD
	v_and_b32_sdwa v46, v33, v170 dst_sel:DWORD dst_unused:UNUSED_PAD src0_sel:WORD_1 src1_sel:DWORD
	v_and_b32_sdwa v44, v32, v170 dst_sel:DWORD dst_unused:UNUSED_PAD src0_sel:WORD_1 src1_sel:DWORD
	v_add3_u32 v19, v34, v19, s56
	v_add3_u32 v34, v35, v45, s56
	v_add3_u32 v33, v33, v46, s56
	v_add3_u32 v32, v32, v44, s56
	v_and_b32_e32 v34, 0xffff0000, v34
	v_and_b32_e32 v35, 0xffff0000, v33
	v_or_b32_sdwa v33, v34, v19 dst_sel:DWORD dst_unused:UNUSED_PAD src0_sel:DWORD src1_sel:WORD_1
	v_or_b32_sdwa v32, v35, v32 dst_sel:DWORD dst_unused:UNUSED_PAD src0_sel:DWORD src1_sel:WORD_1
	global_store_dwordx2 v[56:57], v[32:33], off offset:64
	s_nop 0
	v_pk_fma_f32 v[34:35], v[42:43], v[138:139], v[208:209]
	v_pk_fma_f32 v[32:33], v[40:41], v[136:137], v[206:207]
	global_store_dwordx4 v[50:51], v[32:35], off offset:192
	v_mul_f32_e32 v14, v21, v21
	v_mul_f32_e32 v15, v25, v25
	v_fmac_f32_e32 v14, v20, v20
	v_fmac_f32_e32 v15, v24, v24
	v_fmac_f32_e32 v14, v22, v22
	v_fmac_f32_e32 v15, v26, v26
	v_fmac_f32_e32 v14, v23, v23
	v_fmac_f32_e32 v15, v27, v27
	v_add_f32_e32 v14, v14, v15
	v_mul_f32_e32 v15, v29, v29
	v_fmac_f32_e32 v15, v28, v28
	v_fmac_f32_e32 v15, v30, v30
	v_fmac_f32_e32 v15, v31, v31
	v_add_f32_e32 v14, v14, v15
	v_mul_f32_e32 v15, v33, v33
	v_fmac_f32_e32 v15, v32, v32
	v_fmac_f32_e32 v15, v34, v34
	v_fmac_f32_e32 v15, v35, v35
	v_add_f32_e32 v14, v14, v15
	ds_bpermute_b32 v15, v105, v14
	s_waitcnt lgkmcnt(0)
	v_add_f32_e32 v14, v14, v15
	ds_bpermute_b32 v15, v104, v14
	v_pk_mul_f32 v[20:21], v[34:35], v[154:155]
	v_pk_mul_f32 v[22:23], v[32:33], v[152:153]
	v_pk_add_f32 v[24:25], v[192:193], 1.0 op_sel_hi:[1,0]
	v_pk_add_f32 v[26:27], v[190:191], 1.0 op_sel_hi:[1,0]
	v_pk_mul_f32 v[20:21], v[20:21], v[24:25]
	v_pk_mul_f32 v[22:23], v[22:23], v[26:27]
	v_and_b32_sdwa v19, v20, v170 dst_sel:DWORD dst_unused:UNUSED_PAD src0_sel:WORD_1 src1_sel:DWORD
	v_and_b32_sdwa v25, v21, v170 dst_sel:DWORD dst_unused:UNUSED_PAD src0_sel:WORD_1 src1_sel:DWORD
	v_and_b32_sdwa v26, v23, v170 dst_sel:DWORD dst_unused:UNUSED_PAD src0_sel:WORD_1 src1_sel:DWORD
	v_and_b32_sdwa v24, v22, v170 dst_sel:DWORD dst_unused:UNUSED_PAD src0_sel:WORD_1 src1_sel:DWORD
	v_add3_u32 v19, v20, v19, s56
	v_add3_u32 v20, v21, v25, s56
	v_add3_u32 v21, v23, v26, s56
	v_add3_u32 v22, v22, v24, s56
	v_and_b32_e32 v20, 0xffff0000, v20
	v_and_b32_e32 v23, 0xffff0000, v21
	v_or_b32_sdwa v21, v20, v19 dst_sel:DWORD dst_unused:UNUSED_PAD src0_sel:DWORD src1_sel:WORD_1
	v_or_b32_sdwa v20, v23, v22 dst_sel:DWORD dst_unused:UNUSED_PAD src0_sel:DWORD src1_sel:WORD_1
	global_store_dwordx2 v[56:57], v[20:21], off offset:96
	s_and_saveexec_b64 s[2:3], vcc
	s_cbranch_execz .LBB0_122
	v_readlane_b32 s16, v253, 20
	s_add_u32 s24, s26, s16
	s_addc_u32 s25, s27, 0
	v_lshl_add_u64 v[20:21], v[12:13], 2, s[24:25]
	s_waitcnt lgkmcnt(0)
	v_add_f32_e32 v13, v14, v15
	global_store_dword v[20:21], v13, off
.LBB0_122:
	s_or_b64 exec, exec, s[2:3]
	v_add_u32_e32 v13, 0xffffe010, v18
	s_waitcnt lgkmcnt(0)
	v_lshl_add_u64 v[14:15], s[0:1], 0, v[128:129]
	v_or_b32_e32 v12, 16, v12
	v_lshrrev_b32_e32 v13, 10, v13
	s_movk_i32 s0, 0x1800
	v_mad_u32_u24 v13, v13, s0, s0
	v_cmp_lt_i32_e64 s[0:1], s13, v12
	s_nop 1
	v_cndmask_b32_e64 v18, 0, v13, s[0:1]
	v_ashrrev_i32_e32 v19, 31, v18
	v_lshlrev_b64 v[34:35], 2, v[18:19]
	v_ashrrev_i32_e32 v13, 31, v12
	v_lshl_add_u64 v[18:19], s[40:41], 0, v[34:35]
	v_readlane_b32 s0, v250, 15
	v_lshl_add_u64 v[20:21], v[18:19], 0, v[128:129]
	v_lshlrev_b64 v[18:19], 12, v[12:13]
	v_readlane_b32 s1, v250, 16
	s_nop 0
	v_lshl_add_u64 v[18:19], s[0:1], 0, v[18:19]
	v_lshl_add_u64 v[18:19], v[18:19], 0, v[128:129]
	v_readlane_b32 s0, v250, 21
	v_readlane_b32 s1, v250, 22
	s_waitcnt vmcnt(16)
	v_pk_fma_f32 v[28:29], v[38:39], v[74:75], v[212:213]
	v_pk_fma_f32 v[26:27], v[36:37], v[72:73], v[210:211]
	v_lshl_add_u64 v[22:23], s[42:43], 0, v[34:35]
	global_store_dwordx4 v[18:19], v[26:29], off
	v_lshl_add_u64 v[22:23], v[22:23], 0, v[128:129]
	v_mul_f32_e32 v38, v27, v27
	v_fmac_f32_e32 v38, v26, v26
	v_fmac_f32_e32 v38, v28, v28
	v_fmac_f32_e32 v38, v29, v29
	v_pk_mul_f32 v[24:25], v[28:29], v[142:143]
	v_pk_add_f32 v[28:29], v[158:159], 1.0 op_sel_hi:[1,0]
	v_pk_mul_f32 v[26:27], v[26:27], v[140:141]
	v_pk_add_f32 v[30:31], v[156:157], 1.0 op_sel_hi:[1,0]
	v_pk_mul_f32 v[24:25], v[24:25], v[28:29]
	v_lshlrev_b64 v[28:29], 11, v[12:13]
	v_pk_mul_f32 v[26:27], v[26:27], v[30:31]
	v_lshl_add_u64 v[28:29], s[0:1], 0, v[28:29]
	v_lshl_add_u64 v[16:17], v[28:29], 0, v[16:17]
	v_and_b32_sdwa v28, v24, v170 dst_sel:DWORD dst_unused:UNUSED_PAD src0_sel:WORD_1 src1_sel:DWORD
	v_and_b32_sdwa v29, v26, v170 dst_sel:DWORD dst_unused:UNUSED_PAD src0_sel:WORD_1 src1_sel:DWORD
	v_add3_u32 v26, v26, v29, s56
	v_add3_u32 v24, v24, v28, s56
	v_and_b32_sdwa v28, v25, v170 dst_sel:DWORD dst_unused:UNUSED_PAD src0_sel:WORD_1 src1_sel:DWORD
	v_and_b32_sdwa v29, v27, v170 dst_sel:DWORD dst_unused:UNUSED_PAD src0_sel:WORD_1 src1_sel:DWORD
	v_add3_u32 v25, v25, v28, s56
	v_add3_u32 v27, v27, v29, s56
	v_and_b32_e32 v25, 0xffff0000, v25
	v_and_b32_e32 v27, 0xffff0000, v27
	v_or_b32_sdwa v25, v25, v24 dst_sel:DWORD dst_unused:UNUSED_PAD src0_sel:DWORD src1_sel:WORD_1
	v_or_b32_sdwa v24, v27, v26 dst_sel:DWORD dst_unused:UNUSED_PAD src0_sel:DWORD src1_sel:WORD_1
	global_store_dwordx2 v[16:17], v[24:25], off
	s_nop 0
	v_pk_fma_f32 v[8:9], v[8:9], v[80:81], v[214:215]
	s_nop 0
	v_mul_f32_e32 v24, v9, v9
	v_pk_fma_f32 v[10:11], v[10:11], v[82:83], v[216:217]
	v_fmac_f32_e32 v24, v8, v8
	v_fmac_f32_e32 v24, v10, v10
	global_store_dwordx4 v[18:19], v[8:11], off offset:64
	v_fmac_f32_e32 v24, v11, v11
	v_add_f32_e32 v32, v38, v24
	v_pk_mul_f32 v[10:11], v[10:11], v[146:147]
	v_pk_mul_f32 v[8:9], v[8:9], v[144:145]
	v_pk_add_f32 v[24:25], v[162:163], 1.0 op_sel_hi:[1,0]
	v_pk_add_f32 v[26:27], v[160:161], 1.0 op_sel_hi:[1,0]
	v_pk_mul_f32 v[10:11], v[10:11], v[24:25]
	v_pk_mul_f32 v[8:9], v[8:9], v[26:27]
	v_and_b32_sdwa v24, v10, v170 dst_sel:DWORD dst_unused:UNUSED_PAD src0_sel:WORD_1 src1_sel:DWORD
	v_and_b32_sdwa v25, v8, v170 dst_sel:DWORD dst_unused:UNUSED_PAD src0_sel:WORD_1 src1_sel:DWORD
	v_add3_u32 v8, v8, v25, s56
	v_add3_u32 v10, v10, v24, s56
	v_and_b32_sdwa v24, v11, v170 dst_sel:DWORD dst_unused:UNUSED_PAD src0_sel:WORD_1 src1_sel:DWORD
	v_and_b32_sdwa v25, v9, v170 dst_sel:DWORD dst_unused:UNUSED_PAD src0_sel:WORD_1 src1_sel:DWORD
	v_add3_u32 v11, v11, v24, s56
	v_add3_u32 v9, v9, v25, s56
	v_and_b32_e32 v11, 0xffff0000, v11
	v_and_b32_e32 v24, 0xffff0000, v9
	v_or_b32_sdwa v9, v11, v10 dst_sel:DWORD dst_unused:UNUSED_PAD src0_sel:DWORD src1_sel:WORD_1
	v_or_b32_sdwa v8, v24, v8 dst_sel:DWORD dst_unused:UNUSED_PAD src0_sel:DWORD src1_sel:WORD_1
	global_store_dwordx2 v[16:17], v[8:9], off offset:32
	s_nop 0
	v_pk_fma_f32 v[4:5], v[4:5], v[88:89], v[218:219]
	s_nop 0
	v_mul_f32_e32 v8, v5, v5
	v_pk_fma_f32 v[6:7], v[6:7], v[90:91], v[220:221]
	v_fmac_f32_e32 v8, v4, v4
	v_fmac_f32_e32 v8, v6, v6
	global_store_dwordx4 v[18:19], v[4:7], off offset:128
	v_fmac_f32_e32 v8, v7, v7
	v_add_f32_e32 v28, v32, v8
	v_pk_mul_f32 v[6:7], v[6:7], v[150:151]
	v_pk_mul_f32 v[4:5], v[4:5], v[148:149]
	v_pk_add_f32 v[8:9], v[182:183], 1.0 op_sel_hi:[1,0]
	v_pk_add_f32 v[10:11], v[180:181], 1.0 op_sel_hi:[1,0]
	v_pk_mul_f32 v[6:7], v[6:7], v[8:9]
	v_pk_mul_f32 v[4:5], v[4:5], v[10:11]
	v_and_b32_sdwa v8, v6, v170 dst_sel:DWORD dst_unused:UNUSED_PAD src0_sel:WORD_1 src1_sel:DWORD
	v_and_b32_sdwa v9, v4, v170 dst_sel:DWORD dst_unused:UNUSED_PAD src0_sel:WORD_1 src1_sel:DWORD
	v_add3_u32 v4, v4, v9, s56
	v_add3_u32 v6, v6, v8, s56
	v_and_b32_sdwa v8, v7, v170 dst_sel:DWORD dst_unused:UNUSED_PAD src0_sel:WORD_1 src1_sel:DWORD
	v_and_b32_sdwa v9, v5, v170 dst_sel:DWORD dst_unused:UNUSED_PAD src0_sel:WORD_1 src1_sel:DWORD
	v_add3_u32 v7, v7, v8, s56
	v_add3_u32 v5, v5, v9, s56
	v_and_b32_e32 v7, 0xffff0000, v7
	v_and_b32_e32 v8, 0xffff0000, v5
	v_or_b32_sdwa v5, v7, v6 dst_sel:DWORD dst_unused:UNUSED_PAD src0_sel:DWORD src1_sel:WORD_1
	v_or_b32_sdwa v4, v8, v4 dst_sel:DWORD dst_unused:UNUSED_PAD src0_sel:DWORD src1_sel:WORD_1
	global_store_dwordx2 v[16:17], v[4:5], off offset:64
	s_nop 0
	v_pk_fma_f32 v[0:1], v[0:1], v[136:137], v[222:223]
	s_nop 0
	v_mul_f32_e32 v4, v1, v1
	v_pk_fma_f32 v[2:3], v[2:3], v[138:139], v[224:225]
	v_fmac_f32_e32 v4, v0, v0
	v_fmac_f32_e32 v4, v2, v2
	global_store_dwordx4 v[18:19], v[0:3], off offset:192
	v_fmac_f32_e32 v4, v3, v3
	v_add_f32_e32 v18, v28, v4
	v_pk_mul_f32 v[2:3], v[2:3], v[154:155]
	v_pk_mul_f32 v[0:1], v[0:1], v[152:153]
	v_pk_add_f32 v[4:5], v[192:193], 1.0 op_sel_hi:[1,0]
	v_pk_add_f32 v[6:7], v[190:191], 1.0 op_sel_hi:[1,0]
	v_pk_mul_f32 v[2:3], v[2:3], v[4:5]
	v_pk_mul_f32 v[0:1], v[0:1], v[6:7]
	v_and_b32_sdwa v4, v2, v170 dst_sel:DWORD dst_unused:UNUSED_PAD src0_sel:WORD_1 src1_sel:DWORD
	v_and_b32_sdwa v5, v0, v170 dst_sel:DWORD dst_unused:UNUSED_PAD src0_sel:WORD_1 src1_sel:DWORD
	v_add3_u32 v0, v0, v5, s56
	v_add3_u32 v2, v2, v4, s56
	v_and_b32_sdwa v4, v3, v170 dst_sel:DWORD dst_unused:UNUSED_PAD src0_sel:WORD_1 src1_sel:DWORD
	v_and_b32_sdwa v5, v1, v170 dst_sel:DWORD dst_unused:UNUSED_PAD src0_sel:WORD_1 src1_sel:DWORD
	v_add3_u32 v3, v3, v4, s56
	v_add3_u32 v1, v1, v5, s56
	v_and_b32_e32 v3, 0xffff0000, v3
	v_and_b32_e32 v4, 0xffff0000, v1
	v_or_b32_sdwa v1, v3, v2 dst_sel:DWORD dst_unused:UNUSED_PAD src0_sel:DWORD src1_sel:WORD_1
	v_or_b32_sdwa v0, v4, v0 dst_sel:DWORD dst_unused:UNUSED_PAD src0_sel:DWORD src1_sel:WORD_1
	global_store_dwordx2 v[16:17], v[0:1], off offset:96
	ds_bpermute_b32 v0, v105, v18
	s_waitcnt lgkmcnt(0)
	v_add_f32_e32 v0, v18, v0
	ds_bpermute_b32 v1, v104, v0
	s_and_saveexec_b64 s[0:1], vcc
	s_movk_i32 s89, 0xff
	s_cbranch_execz .LBB0_124
	v_readlane_b32 s2, v253, 20
	s_add_u32 s2, s26, s2
	s_addc_u32 s3, s27, 0
	v_lshl_add_u64 v[2:3], v[12:13], 2, s[2:3]
	s_waitcnt lgkmcnt(0)
	v_add_f32_e32 v0, v0, v1
	global_store_dword v[2:3], v0, off

.LBB0_236:
	s_add_i32 s24, s25, 2
	s_setprio 1
	v_add_u32_e32 v111, v104, v105
	ds_read_b128 v[136:139], v111 offset:16384
	ds_read_b128 v[140:143], v111 offset:18432
	ds_read_b128 v[144:147], v111 offset:20480
	ds_read_b128 v[148:151], v111 offset:22528
	v_add_u32_e32 v110, v103, v105
	ds_read_b128 v[116:119], v110
	s_add_i32 s25, s25, 4
	ds_read_b128 v[120:123], v110 offset:2048
	s_min_u32 s25, s25, 63
	v_add_u32_e32 v113, v104, v114
	s_lshl_b32 s92, s25, 7
	ds_read_b128 v[124:127], v110 offset:4096
	v_add_u32_e32 v112, v103, v114
	ds_read_b128 v[194:197], v113 offset:16384
	ds_read_b128 v[198:201], v113 offset:18432
	ds_read_b128 v[202:205], v113 offset:20480
	ds_read_b128 v[206:209], v113 offset:22528
	v_lshl_add_u64 v[164:165], v[98:99], 0, s[92:93]
	ds_read_b128 v[132:135], v110 offset:6144
	ds_read_b128 v[152:155], v112
	ds_read_b128 v[156:159], v112 offset:2048
	ds_read_b128 v[160:163], v112 offset:4096
	ds_read_b128 v[190:193], v112 offset:6144
	s_waitcnt lgkmcnt(11)
	v_mfma_f32_16x16x32_bf16 v[92:95], v[136:139], v[116:119], v[92:95]
	v_mfma_f32_16x16x32_bf16 v[56:59], v[140:143], v[116:119], v[56:59]
	v_mfma_f32_16x16x32_bf16 v[52:55], v[144:147], v[116:119], v[52:55]
	v_mfma_f32_16x16x32_bf16 v[48:51], v[148:151], v[116:119], v[48:51]
	global_load_dwordx4 v[116:119], v[164:165], off
	s_waitcnt vmcnt(6)
	ds_write_b128 v109, v[60:63] offset:32768
	v_add_co_u32_e32 v60, vcc, s7, v164
	s_waitcnt lgkmcnt(11)
	v_mfma_f32_16x16x32_bf16 v[44:47], v[136:139], v[120:123], v[44:47]
	v_addc_co_u32_e32 v61, vcc, 0, v165, vcc
	v_mfma_f32_16x16x32_bf16 v[40:43], v[140:143], v[120:123], v[40:43]
	v_mfma_f32_16x16x32_bf16 v[36:39], v[144:147], v[120:123], v[36:39]
	v_mfma_f32_16x16x32_bf16 v[32:35], v[148:151], v[120:123], v[32:35]
	global_load_dwordx4 v[120:123], v[60:61], off
	v_add_co_u32_e32 v60, vcc, s52, v164
	ds_write_b128 v109, v[64:67] offset:36864
	s_nop 0
	v_addc_co_u32_e32 v61, vcc, 0, v165, vcc
	s_waitcnt lgkmcnt(11)
	v_mfma_f32_16x16x32_bf16 v[28:31], v[136:139], v[124:127], v[28:31]
	v_lshl_add_u64 v[64:65], v[100:101], 0, s[92:93]
	v_mfma_f32_16x16x32_bf16 v[24:27], v[140:143], v[124:127], v[24:27]
	v_mfma_f32_16x16x32_bf16 v[20:23], v[144:147], v[124:127], v[20:23]
	v_mfma_f32_16x16x32_bf16 v[16:19], v[148:151], v[124:127], v[16:19]
	global_load_dwordx4 v[124:127], v[60:61], off
	v_add_co_u32_e32 v60, vcc, s34, v164
	ds_write_b128 v109, v[68:71] offset:40960
	s_nop 0
	v_addc_co_u32_e32 v61, vcc, 0, v165, vcc
	v_add_co_u32_e32 v66, vcc, s7, v64
	s_waitcnt lgkmcnt(7)
	v_mfma_f32_16x16x32_bf16 v[12:15], v[136:139], v[132:135], v[12:15]
	v_addc_co_u32_e32 v67, vcc, 0, v65, vcc
	v_mfma_f32_16x16x32_bf16 v[8:11], v[140:143], v[132:135], v[8:11]
	v_mfma_f32_16x16x32_bf16 v[4:7], v[144:147], v[132:135], v[4:7]
	v_mfma_f32_16x16x32_bf16 v[0:3], v[148:151], v[132:135], v[0:3]
	global_load_dwordx4 v[132:135], v[60:61], off
	s_waitcnt vmcnt(7)
	ds_write_b128 v109, v[76:79] offset:45056
	s_waitcnt lgkmcnt(7)
	v_mfma_f32_16x16x32_bf16 v[60:63], v[194:197], v[152:155], v[92:95]
	v_mfma_f32_16x16x32_bf16 v[56:59], v[198:201], v[152:155], v[56:59]
	v_mfma_f32_16x16x32_bf16 v[52:55], v[202:205], v[152:155], v[52:55]
	v_mfma_f32_16x16x32_bf16 v[48:51], v[206:209], v[152:155], v[48:51]
	global_load_dwordx4 v[136:139], v[64:65], off
	ds_write_b128 v109, v[72:75] offset:49152
	s_waitcnt lgkmcnt(7)
	v_mfma_f32_16x16x32_bf16 v[44:47], v[194:197], v[156:159], v[44:47]
	v_mfma_f32_16x16x32_bf16 v[40:43], v[198:201], v[156:159], v[40:43]
	v_mfma_f32_16x16x32_bf16 v[36:39], v[202:205], v[156:159], v[36:39]
	v_mfma_f32_16x16x32_bf16 v[32:35], v[206:209], v[156:159], v[32:35]
	global_load_dwordx4 v[140:143], v[66:67], off
	v_add_co_u32_e32 v66, vcc, s52, v64
	s_waitcnt vmcnt(8)
	ds_write_b128 v109, v[80:83] offset:53248
	v_addc_co_u32_e32 v67, vcc, 0, v65, vcc
	v_add_co_u32_e32 v64, vcc, s34, v64
	s_waitcnt lgkmcnt(7)
	v_mfma_f32_16x16x32_bf16 v[28:31], v[194:197], v[160:163], v[28:31]
	v_addc_co_u32_e32 v65, vcc, 0, v65, vcc
	v_mfma_f32_16x16x32_bf16 v[24:27], v[198:201], v[160:163], v[24:27]
	v_mfma_f32_16x16x32_bf16 v[20:23], v[202:205], v[160:163], v[20:23]
	v_mfma_f32_16x16x32_bf16 v[16:19], v[206:209], v[160:163], v[16:19]
	global_load_dwordx4 v[144:147], v[66:67], off
	s_waitcnt vmcnt(8)
	ds_write_b128 v109, v[84:87] offset:57344
	s_waitcnt lgkmcnt(7)
	v_mfma_f32_16x16x32_bf16 v[12:15], v[194:197], v[190:193], v[12:15]
	v_mfma_f32_16x16x32_bf16 v[8:11], v[198:201], v[190:193], v[8:11]
	v_mfma_f32_16x16x32_bf16 v[4:7], v[202:205], v[190:193], v[4:7]
	v_mfma_f32_16x16x32_bf16 v[0:3], v[206:209], v[190:193], v[0:3]
	global_load_dwordx4 v[148:151], v[64:65], off
	s_waitcnt vmcnt(8)
	ds_write_b128 v109, v[88:91] offset:61440
	s_setprio 0
	s_waitcnt lgkmcnt(0)
	s_barrier
	s_setprio 1
	ds_read_b128 v[80:83], v111 offset:49152
	ds_read_b128 v[84:87], v111 offset:51200
	ds_read_b128 v[88:91], v111 offset:53248
	ds_read_b128 v[92:95], v111 offset:55296
	ds_read_b128 v[64:67], v110 offset:32768
	ds_read_b128 v[68:71], v110 offset:34816
	s_min_u32 s25, s24, 60
	s_lshl_b32 s92, s25, 7
	ds_read_b128 v[72:75], v110 offset:36864
	v_lshl_add_u64 v[164:165], v[98:99], 0, s[92:93]
	ds_read_b128 v[76:79], v110 offset:38912
	ds_read_b128 v[152:155], v112 offset:32768
	ds_read_b128 v[156:159], v112 offset:34816
	ds_read_b128 v[160:163], v112 offset:36864
	ds_read_b128 v[190:193], v112 offset:38912
	ds_read_b128 v[194:197], v113 offset:49152
	ds_read_b128 v[198:201], v113 offset:51200
	ds_read_b128 v[202:205], v113 offset:53248
	ds_read_b128 v[206:209], v113 offset:55296
	s_waitcnt lgkmcnt(11)
	v_mfma_f32_16x16x32_bf16 v[210:213], v[80:83], v[64:67], v[60:63]
	v_mfma_f32_16x16x32_bf16 v[56:59], v[84:87], v[64:67], v[56:59]
	v_mfma_f32_16x16x32_bf16 v[52:55], v[88:91], v[64:67], v[52:55]
	v_mfma_f32_16x16x32_bf16 v[48:51], v[92:95], v[64:67], v[48:51]
	v_add_co_u32_e32 v64, vcc, s7, v164
	global_load_dwordx4 v[60:63], v[164:165], off offset:384
	s_nop 0
	v_addc_co_u32_e32 v65, vcc, 0, v165, vcc
	s_waitcnt vmcnt(8)
	ds_write_b128 v109, v[116:119]
	s_waitcnt lgkmcnt(11)
	v_mfma_f32_16x16x32_bf16 v[44:47], v[80:83], v[68:71], v[44:47]
	v_mfma_f32_16x16x32_bf16 v[40:43], v[84:87], v[68:71], v[40:43]
	v_mfma_f32_16x16x32_bf16 v[36:39], v[88:91], v[68:71], v[36:39]
	v_mfma_f32_16x16x32_bf16 v[32:35], v[92:95], v[68:71], v[32:35]
	v_add_co_u32_e32 v68, vcc, s52, v164
	global_load_dwordx4 v[64:67], v[64:65], off offset:384
	s_nop 0
	v_addc_co_u32_e32 v69, vcc, 0, v165, vcc
	s_waitcnt vmcnt(8)
	ds_write_b128 v109, v[120:123] offset:4096
	s_waitcnt lgkmcnt(11)
	v_mfma_f32_16x16x32_bf16 v[28:31], v[80:83], v[72:75], v[28:31]
	v_mfma_f32_16x16x32_bf16 v[24:27], v[84:87], v[72:75], v[24:27]
	v_mfma_f32_16x16x32_bf16 v[20:23], v[88:91], v[72:75], v[20:23]
	v_mfma_f32_16x16x32_bf16 v[16:19], v[92:95], v[72:75], v[16:19]
	v_add_co_u32_e32 v72, vcc, s34, v164
	global_load_dwordx4 v[68:71], v[68:69], off offset:384
	s_waitcnt vmcnt(8)
	ds_write_b128 v109, v[124:127] offset:8192
	s_waitcnt lgkmcnt(11)
	v_mfma_f32_16x16x32_bf16 v[4:7], v[88:91], v[76:79], v[4:7]
	v_addc_co_u32_e32 v73, vcc, 0, v165, vcc
	v_lshl_add_u64 v[88:89], v[100:101], 0, s[92:93]
	v_mfma_f32_16x16x32_bf16 v[12:15], v[80:83], v[76:79], v[12:15]
	v_add_co_u32_e32 v80, vcc, s7, v88
	v_mfma_f32_16x16x32_bf16 v[8:11], v[84:87], v[76:79], v[8:11]
	s_nop 0
	v_addc_co_u32_e32 v81, vcc, 0, v89, vcc
	v_add_co_u32_e32 v84, vcc, s52, v88
	v_mfma_f32_16x16x32_bf16 v[0:3], v[92:95], v[76:79], v[0:3]
	s_nop 0
	v_addc_co_u32_e32 v85, vcc, 0, v89, vcc
	global_load_dwordx4 v[76:79], v[72:73], off offset:384
	s_waitcnt vmcnt(8)
	ds_write_b128 v109, v[132:135] offset:12288
	s_waitcnt lgkmcnt(7)
	v_mfma_f32_16x16x32_bf16 v[92:95], v[194:197], v[152:155], v[210:213]
	s_waitcnt lgkmcnt(6)
	v_mfma_f32_16x16x32_bf16 v[56:59], v[198:201], v[152:155], v[56:59]
	s_waitcnt lgkmcnt(5)
	v_mfma_f32_16x16x32_bf16 v[52:55], v[202:205], v[152:155], v[52:55]
	s_waitcnt lgkmcnt(4)
	v_mfma_f32_16x16x32_bf16 v[48:51], v[206:209], v[152:155], v[48:51]
	global_load_dwordx4 v[72:75], v[88:89], off offset:384
	v_add_co_u32_e32 v88, vcc, s34, v88
	s_waitcnt vmcnt(8)
	ds_write_b128 v109, v[136:139] offset:16384
	v_addc_co_u32_e32 v89, vcc, 0, v89, vcc
	v_mfma_f32_16x16x32_bf16 v[44:47], v[194:197], v[156:159], v[44:47]
	v_mfma_f32_16x16x32_bf16 v[40:43], v[198:201], v[156:159], v[40:43]
	v_mfma_f32_16x16x32_bf16 v[36:39], v[202:205], v[156:159], v[36:39]
	v_mfma_f32_16x16x32_bf16 v[32:35], v[206:209], v[156:159], v[32:35]
	global_load_dwordx4 v[80:83], v[80:81], off offset:384
	s_waitcnt vmcnt(8)
	ds_write_b128 v109, v[140:143] offset:20480
	v_mfma_f32_16x16x32_bf16 v[28:31], v[194:197], v[160:163], v[28:31]
	v_mfma_f32_16x16x32_bf16 v[24:27], v[198:201], v[160:163], v[24:27]
	v_mfma_f32_16x16x32_bf16 v[20:23], v[202:205], v[160:163], v[20:23]
	v_mfma_f32_16x16x32_bf16 v[16:19], v[206:209], v[160:163], v[16:19]
	global_load_dwordx4 v[84:87], v[84:85], off offset:384
	s_waitcnt vmcnt(8)
	ds_write_b128 v109, v[144:147] offset:24576
	v_mfma_f32_16x16x32_bf16 v[12:15], v[194:197], v[190:193], v[12:15]
	v_mfma_f32_16x16x32_bf16 v[8:11], v[198:201], v[190:193], v[8:11]
	v_mfma_f32_16x16x32_bf16 v[4:7], v[202:205], v[190:193], v[4:7]
	v_mfma_f32_16x16x32_bf16 v[0:3], v[206:209], v[190:193], v[0:3]
	global_load_dwordx4 v[88:91], v[88:89], off offset:384
	s_waitcnt vmcnt(8)
	ds_write_b128 v109, v[148:151] offset:28672
	s_setprio 0
	s_cmp_lt_u32 s24, 62
	s_mov_b32 s25, s24
	s_waitcnt lgkmcnt(0)
	s_barrier
	s_cbranch_scc1 .LBB0_236
	s_add_i32 s26, s69, 1
	v_readlane_b32 s16, v251, 5
	s_and_b64 s[24:25], s[8:9], exec
	s_mul_i32 s25, s69, 0x12000
	s_waitcnt vmcnt(2)
	v_add_u32_e32 v80, s16, v108
	v_readlane_b32 s28, v250, 25
	v_add_u32_e32 v60, 0xffffe000, v80
	s_cselect_b32 s24, 3, s26
	v_readlane_b32 s29, v250, 26
	s_add_u32 s25, s28, s25
	v_or_b32_e32 v70, v80, v107
	v_lshlrev_b32_e32 v114, 6, v102
	v_readlane_b32 s16, v251, 6
	v_lshrrev_b32_e32 v60, 10, v60
	s_movk_i32 s5, 0x1800
	s_addc_u32 s26, s29, 0
	v_or_b32_e32 v81, s16, v114
	v_lshlrev_b32_e32 v115, 2, v97
	v_mad_u32_u24 v60, v60, s5, s5
	v_cmp_lt_i32_e32 vcc, s13, v70
	s_add_u32 s40, s25, 0x5000
	v_or_b32_e32 v64, v81, v115
	v_cndmask_b32_e32 v76, 0, v60, vcc
	s_addc_u32 s41, s26, 0
	v_ashrrev_i32_e32 v77, 31, v76
	v_ashrrev_i32_e32 v65, 31, v64
	v_ashrrev_i32_e32 v71, 31, v70
	v_lshl_add_u64 v[60:61], v[76:77], 2, s[40:41]
	v_lshlrev_b64 v[66:67], 2, v[64:65]
	v_readlane_b32 s16, v250, 15
	v_lshl_add_u64 v[74:75], v[60:61], 0, v[66:67]
	v_lshlrev_b64 v[60:61], 12, v[70:71]
	v_readlane_b32 s17, v250, 16
	v_readlane_b32 s68, v250, 41
	s_mul_i32 s25, s24, 0x12000
	v_lshl_add_u64 v[60:61], s[16:17], 0, v[60:61]
	v_lshl_add_u64 v[72:73], v[60:61], 0, v[66:67]
	global_load_dwordx4 v[116:119], v[74:75], off
	global_load_dwordx4 v[120:123], v[74:75], off offset:64
	global_load_dwordx4 v[124:127], v[74:75], off offset:128
	global_load_dwordx4 v[132:135], v[74:75], off offset:192
	global_load_dwordx4 v[190:193], v[72:73], off
	global_load_dwordx4 v[194:197], v[72:73], off offset:64
	global_load_dwordx4 v[198:201], v[72:73], off offset:128
	global_load_dwordx4 v[202:205], v[72:73], off offset:192
	v_add_co_u32_e32 v164, vcc, 0x10000, v72
	s_nop 1
	v_addc_co_u32_e32 v165, vcc, 0, v73, vcc
	v_add_co_u32_e32 v222, vcc, 0x20000, v72
	s_nop 1
	v_addc_co_u32_e32 v223, vcc, 0, v73, vcc
	v_add_co_u32_e32 v224, vcc, 0x30000, v72
	s_nop 1
	v_addc_co_u32_e32 v225, vcc, 0, v73, vcc
	global_load_dwordx4 v[206:209], v[164:165], off
	global_load_dwordx4 v[210:213], v[164:165], off offset:64
	global_load_dwordx4 v[214:217], v[164:165], off offset:128
	global_load_dwordx4 v[218:221], v[164:165], off offset:192
	s_lshl_b32 s24, s24, 12
	v_readlane_b32 s70, v250, 43
	v_readlane_b32 s71, v250, 44
	s_add_u32 s26, s70, s24
	s_addc_u32 s27, s71, 0
	s_add_u32 s24, s28, s25
	s_addc_u32 s25, s29, 0
	s_add_u32 s42, s24, 0x1000
	v_cndmask_b32_e64 v68, 0, 1, s[2:3]
	s_addc_u32 s43, s25, 0
	s_andn2_b64 vcc, exec, s[2:3]
	v_readlane_b32 s2, v250, 21
	s_waitcnt vmcnt(3)
	v_lshlrev_b64 v[86:87], 10, v[70:71]
	v_readlane_b32 s3, v250, 22
	v_cmp_ne_u32_e64 s[36:37], 1, v68
	v_lshl_add_u64 v[68:69], s[26:27], 0, v[66:67]
	v_lshl_add_u64 v[78:79], v[76:77], 2, s[42:43]
	v_lshl_add_u64 v[76:77], v[86:87], 1, s[2:3]
	v_readlane_b32 s69, v250, 42
	v_readlane_b32 s72, v250, 45
	v_readlane_b32 s73, v250, 46
	v_readlane_b32 s74, v250, 47
	v_readlane_b32 s75, v250, 48
	v_readlane_b32 s76, v250, 49
	v_readlane_b32 s77, v250, 50
	v_readlane_b32 s78, v250, 51
	v_readlane_b32 s79, v250, 52
	v_readlane_b32 s80, v250, 53
	v_readlane_b32 s81, v250, 54
	v_readlane_b32 s82, v250, 55
	v_readlane_b32 s83, v250, 56
	s_waitcnt vmcnt(4)
	v_pk_fma_f32 v[62:63], v[94:95], v[118:119], v[192:193]
	v_pk_fma_f32 v[60:61], v[92:93], v[116:117], v[190:191]
	global_store_dwordx4 v[72:73], v[60:63], off
	s_cbranch_vccnz .LBB0_239
	v_lshl_add_u64 v[86:87], v[78:79], 0, v[66:67]
	global_load_dwordx4 v[136:139], v[68:69], off
	global_load_dwordx4 v[140:143], v[68:69], off offset:64
	global_load_dwordx4 v[144:147], v[68:69], off offset:128
	global_load_dwordx4 v[148:151], v[68:69], off offset:192
	s_waitcnt vmcnt(0)
	v_pk_mul_f32 v[84:85], v[62:63], v[138:139]
	global_load_dwordx4 v[152:155], v[86:87], off
	global_load_dwordx4 v[156:159], v[86:87], off offset:64
	global_load_dwordx4 v[160:163], v[86:87], off offset:128
	global_load_dwordx4 v[180:183], v[86:87], off offset:192
	v_pk_mul_f32 v[82:83], v[60:61], v[136:137]
	s_waitcnt vmcnt(0)
	v_pk_add_f32 v[88:89], v[154:155], 1.0 op_sel_hi:[1,0]
	v_pk_add_f32 v[86:87], v[152:153], 1.0 op_sel_hi:[1,0]
	v_pk_mul_f32 v[84:85], v[84:85], v[88:89]
	v_pk_mul_f32 v[82:83], v[82:83], v[86:87]
	v_and_b32_sdwa v88, v84, v170 dst_sel:DWORD dst_unused:UNUSED_PAD src0_sel:WORD_1 src1_sel:DWORD
	v_and_b32_sdwa v89, v82, v170 dst_sel:DWORD dst_unused:UNUSED_PAD src0_sel:WORD_1 src1_sel:DWORD
	v_add3_u32 v82, v82, v89, s56
	v_add3_u32 v84, v84, v88, s56
	v_and_b32_sdwa v88, v85, v170 dst_sel:DWORD dst_unused:UNUSED_PAD src0_sel:WORD_1 src1_sel:DWORD
	v_and_b32_sdwa v89, v83, v170 dst_sel:DWORD dst_unused:UNUSED_PAD src0_sel:WORD_1 src1_sel:DWORD
	v_add3_u32 v85, v85, v88, s56
	v_add3_u32 v83, v83, v89, s56
	v_and_b32_e32 v85, 0xffff0000, v85
	v_and_b32_e32 v88, 0xffff0000, v83
	v_lshl_add_u64 v[86:87], v[64:65], 1, v[76:77]
	v_or_b32_sdwa v83, v85, v84 dst_sel:DWORD dst_unused:UNUSED_PAD src0_sel:DWORD src1_sel:WORD_1
	v_or_b32_sdwa v82, v88, v82 dst_sel:DWORD dst_unused:UNUSED_PAD src0_sel:DWORD src1_sel:WORD_1
	global_store_dwordx2 v[86:87], v[82:83], off
.LBB0_239:
	s_nop 0
	s_and_b64 vcc, exec, s[36:37]
	s_waitcnt vmcnt(0)
	v_pk_fma_f32 v[58:59], v[58:59], v[122:123], v[196:197]
	v_pk_fma_f32 v[56:57], v[56:57], v[120:121], v[194:195]
	global_store_dwordx4 v[72:73], v[56:59], off offset:64
	s_cbranch_vccnz .LBB0_241
	v_lshl_add_u64 v[86:87], v[78:79], 0, v[66:67]
	v_pk_mul_f32 v[84:85], v[58:59], v[142:143]
	v_pk_mul_f32 v[82:83], v[56:57], v[140:141]
	v_pk_add_f32 v[88:89], v[158:159], 1.0 op_sel_hi:[1,0]
	v_pk_add_f32 v[86:87], v[156:157], 1.0 op_sel_hi:[1,0]
	v_pk_mul_f32 v[84:85], v[84:85], v[88:89]
	v_pk_mul_f32 v[82:83], v[82:83], v[86:87]
	v_and_b32_sdwa v88, v84, v170 dst_sel:DWORD dst_unused:UNUSED_PAD src0_sel:WORD_1 src1_sel:DWORD
	v_and_b32_sdwa v89, v82, v170 dst_sel:DWORD dst_unused:UNUSED_PAD src0_sel:WORD_1 src1_sel:DWORD
	v_add3_u32 v82, v82, v89, s56
	v_add3_u32 v84, v84, v88, s56
	v_and_b32_sdwa v88, v85, v170 dst_sel:DWORD dst_unused:UNUSED_PAD src0_sel:WORD_1 src1_sel:DWORD
	v_and_b32_sdwa v89, v83, v170 dst_sel:DWORD dst_unused:UNUSED_PAD src0_sel:WORD_1 src1_sel:DWORD
	v_add3_u32 v85, v85, v88, s56
	v_add3_u32 v83, v83, v89, s56
	v_and_b32_e32 v85, 0xffff0000, v85
	v_and_b32_e32 v88, 0xffff0000, v83
	v_lshl_add_u64 v[86:87], v[64:65], 1, v[76:77]
	v_or_b32_sdwa v83, v85, v84 dst_sel:DWORD dst_unused:UNUSED_PAD src0_sel:DWORD src1_sel:WORD_1
	v_or_b32_sdwa v82, v88, v82 dst_sel:DWORD dst_unused:UNUSED_PAD src0_sel:DWORD src1_sel:WORD_1
	global_store_dwordx2 v[86:87], v[82:83], off offset:32
.LBB0_241:
	s_nop 0
	s_and_b64 vcc, exec, s[36:37]
	s_movk_i32 s8, 0x400
	s_movk_i32 s13, 0x1fff
	s_mov_b32 s5, 0xffff0000
	s_mov_b32 s9, 0x12000
	s_movk_i32 s89, 0xff
	v_readlane_b32 s69, v254, 49
	v_pk_fma_f32 v[54:55], v[54:55], v[126:127], v[200:201]
	v_pk_fma_f32 v[52:53], v[52:53], v[124:125], v[198:199]
	global_store_dwordx4 v[72:73], v[52:55], off offset:128
	s_cbranch_vccnz .LBB0_243
	v_lshl_add_u64 v[86:87], v[78:79], 0, v[66:67]
	v_pk_mul_f32 v[84:85], v[54:55], v[146:147]
	v_pk_mul_f32 v[82:83], v[52:53], v[144:145]
	v_pk_add_f32 v[88:89], v[162:163], 1.0 op_sel_hi:[1,0]
	v_pk_add_f32 v[86:87], v[160:161], 1.0 op_sel_hi:[1,0]
	v_pk_mul_f32 v[84:85], v[84:85], v[88:89]
	v_pk_mul_f32 v[82:83], v[82:83], v[86:87]
	v_and_b32_sdwa v88, v84, v170 dst_sel:DWORD dst_unused:UNUSED_PAD src0_sel:WORD_1 src1_sel:DWORD
	v_and_b32_sdwa v89, v82, v170 dst_sel:DWORD dst_unused:UNUSED_PAD src0_sel:WORD_1 src1_sel:DWORD
	v_add3_u32 v82, v82, v89, s56
	v_add3_u32 v84, v84, v88, s56
	v_and_b32_sdwa v88, v85, v170 dst_sel:DWORD dst_unused:UNUSED_PAD src0_sel:WORD_1 src1_sel:DWORD
	v_and_b32_sdwa v89, v83, v170 dst_sel:DWORD dst_unused:UNUSED_PAD src0_sel:WORD_1 src1_sel:DWORD
	v_add3_u32 v85, v85, v88, s56
	v_add3_u32 v83, v83, v89, s56
	v_and_b32_e32 v85, 0xffff0000, v85
	v_and_b32_e32 v88, 0xffff0000, v83
	v_lshl_add_u64 v[86:87], v[64:65], 1, v[76:77]
	v_or_b32_sdwa v83, v85, v84 dst_sel:DWORD dst_unused:UNUSED_PAD src0_sel:DWORD src1_sel:WORD_1
	v_or_b32_sdwa v82, v88, v82 dst_sel:DWORD dst_unused:UNUSED_PAD src0_sel:DWORD src1_sel:WORD_1
	global_store_dwordx2 v[86:87], v[82:83], off offset:64
.LBB0_243:
	s_nop 0
	s_and_b64 vcc, exec, s[36:37]
	v_pk_fma_f32 v[50:51], v[50:51], v[134:135], v[204:205]
	v_pk_fma_f32 v[48:49], v[48:49], v[132:133], v[202:203]
	global_store_dwordx4 v[72:73], v[48:51], off offset:192
	s_cbranch_vccnz .LBB0_245
	v_lshl_add_u64 v[78:79], v[78:79], 0, v[66:67]
	v_lshl_add_u64 v[76:77], v[64:65], 1, v[76:77]
	v_pk_mul_f32 v[74:75], v[50:51], v[150:151]
	v_pk_mul_f32 v[72:73], v[48:49], v[148:149]
	v_pk_add_f32 v[78:79], v[182:183], 1.0 op_sel_hi:[1,0]
	v_pk_add_f32 v[82:83], v[180:181], 1.0 op_sel_hi:[1,0]
	v_pk_mul_f32 v[74:75], v[74:75], v[78:79]
	v_pk_mul_f32 v[72:73], v[72:73], v[82:83]
	v_and_b32_sdwa v82, v75, v170 dst_sel:DWORD dst_unused:UNUSED_PAD src0_sel:WORD_1 src1_sel:DWORD
	v_and_b32_sdwa v83, v73, v170 dst_sel:DWORD dst_unused:UNUSED_PAD src0_sel:WORD_1 src1_sel:DWORD
	v_and_b32_sdwa v78, v74, v170 dst_sel:DWORD dst_unused:UNUSED_PAD src0_sel:WORD_1 src1_sel:DWORD
	v_and_b32_sdwa v79, v72, v170 dst_sel:DWORD dst_unused:UNUSED_PAD src0_sel:WORD_1 src1_sel:DWORD
	v_add3_u32 v75, v75, v82, s56
	v_add3_u32 v73, v73, v83, s56
	v_add3_u32 v72, v72, v79, s56
	v_add3_u32 v74, v74, v78, s56
	v_and_b32_e32 v75, 0xffff0000, v75
	v_and_b32_e32 v78, 0xffff0000, v73
	v_or_b32_sdwa v73, v75, v74 dst_sel:DWORD dst_unused:UNUSED_PAD src0_sel:DWORD src1_sel:WORD_1
	v_or_b32_sdwa v72, v78, v72 dst_sel:DWORD dst_unused:UNUSED_PAD src0_sel:DWORD src1_sel:WORD_1
	global_store_dwordx2 v[76:77], v[72:73], off offset:96

.LBB0_247:
	s_or_b64 exec, exec, s[2:3]
	v_add_u32_e32 v50, 0xffffe010, v80
	v_or_b32_e32 v52, 16, v70
	v_lshrrev_b32_e32 v50, 10, v50
	s_movk_i32 s2, 0x1800
	v_mad_u32_u24 v50, v50, s2, s2
	v_cmp_lt_i32_e32 vcc, s13, v52
	v_ashrrev_i32_e32 v53, 31, v52
	v_readlane_b32 s2, v250, 15
	v_cndmask_b32_e32 v56, 0, v50, vcc
	v_ashrrev_i32_e32 v57, 31, v56
	s_waitcnt lgkmcnt(0)
	v_lshl_add_u64 v[50:51], v[56:57], 2, s[40:41]
	v_lshl_add_u64 v[54:55], v[50:51], 0, v[66:67]
	v_lshlrev_b64 v[50:51], 12, v[52:53]
	v_readlane_b32 s3, v250, 16
	v_lshlrev_b64 v[52:53], 10, v[52:53]
	s_and_b64 vcc, exec, s[36:37]
	v_lshl_add_u64 v[50:51], s[2:3], 0, v[50:51]
	v_lshl_add_u64 v[50:51], v[50:51], 0, v[66:67]
	v_readlane_b32 s2, v250, 21
	v_readlane_b32 s3, v250, 22
	v_lshl_add_u64 v[56:57], v[56:57], 2, s[42:43]
	global_load_dwordx4 v[190:193], v[222:223], off
	global_load_dwordx4 v[194:197], v[222:223], off offset:64
	global_load_dwordx4 v[198:201], v[222:223], off offset:128
	global_load_dwordx4 v[202:205], v[222:223], off offset:192
	s_waitcnt vmcnt(8)
	v_pk_fma_f32 v[46:47], v[46:47], v[118:119], v[208:209]
	v_pk_fma_f32 v[44:45], v[44:45], v[116:117], v[206:207]
	v_lshl_add_u64 v[52:53], v[52:53], 1, s[2:3]
	global_store_dwordx4 v[50:51], v[44:47], off
	s_cbranch_vccnz .LBB0_249
	v_lshl_add_u64 v[62:63], v[56:57], 0, v[66:67]
	v_pk_mul_f32 v[60:61], v[46:47], v[138:139]
	v_pk_mul_f32 v[58:59], v[44:45], v[136:137]
	v_pk_add_f32 v[62:63], v[154:155], 1.0 op_sel_hi:[1,0]
	v_pk_add_f32 v[72:73], v[152:153], 1.0 op_sel_hi:[1,0]
	v_pk_mul_f32 v[60:61], v[60:61], v[62:63]
	v_pk_mul_f32 v[58:59], v[58:59], v[72:73]
	v_and_b32_sdwa v71, v60, v170 dst_sel:DWORD dst_unused:UNUSED_PAD src0_sel:WORD_1 src1_sel:DWORD
	v_and_b32_sdwa v72, v58, v170 dst_sel:DWORD dst_unused:UNUSED_PAD src0_sel:WORD_1 src1_sel:DWORD
	v_add3_u32 v58, v58, v72, s56
	v_add3_u32 v60, v60, v71, s56
	v_and_b32_sdwa v71, v61, v170 dst_sel:DWORD dst_unused:UNUSED_PAD src0_sel:WORD_1 src1_sel:DWORD
	v_and_b32_sdwa v72, v59, v170 dst_sel:DWORD dst_unused:UNUSED_PAD src0_sel:WORD_1 src1_sel:DWORD
	v_add3_u32 v61, v61, v71, s56
	v_add3_u32 v59, v59, v72, s56
	v_and_b32_e32 v61, 0xffff0000, v61
	v_and_b32_e32 v71, 0xffff0000, v59
	v_lshl_add_u64 v[62:63], v[64:65], 1, v[52:53]
	v_or_b32_sdwa v59, v61, v60 dst_sel:DWORD dst_unused:UNUSED_PAD src0_sel:DWORD src1_sel:WORD_1
	v_or_b32_sdwa v58, v71, v58 dst_sel:DWORD dst_unused:UNUSED_PAD src0_sel:DWORD src1_sel:WORD_1
	global_store_dwordx2 v[62:63], v[58:59], off
.LBB0_249:
	s_nop 0
	s_and_b64 vcc, exec, s[36:37]
	v_pk_fma_f32 v[42:43], v[42:43], v[122:123], v[212:213]
	v_pk_fma_f32 v[40:41], v[40:41], v[120:121], v[210:211]
	global_store_dwordx4 v[50:51], v[40:43], off offset:64
	s_cbranch_vccnz .LBB0_251
	v_lshl_add_u64 v[62:63], v[56:57], 0, v[66:67]
	v_pk_mul_f32 v[60:61], v[42:43], v[142:143]
	v_pk_mul_f32 v[58:59], v[40:41], v[140:141]
	v_pk_add_f32 v[62:63], v[158:159], 1.0 op_sel_hi:[1,0]
	v_pk_add_f32 v[72:73], v[156:157], 1.0 op_sel_hi:[1,0]
	v_pk_mul_f32 v[60:61], v[60:61], v[62:63]
	v_pk_mul_f32 v[58:59], v[58:59], v[72:73]
	v_and_b32_sdwa v71, v60, v170 dst_sel:DWORD dst_unused:UNUSED_PAD src0_sel:WORD_1 src1_sel:DWORD
	v_and_b32_sdwa v72, v58, v170 dst_sel:DWORD dst_unused:UNUSED_PAD src0_sel:WORD_1 src1_sel:DWORD
	v_add3_u32 v58, v58, v72, s56
	v_add3_u32 v60, v60, v71, s56
	v_and_b32_sdwa v71, v61, v170 dst_sel:DWORD dst_unused:UNUSED_PAD src0_sel:WORD_1 src1_sel:DWORD
	v_and_b32_sdwa v72, v59, v170 dst_sel:DWORD dst_unused:UNUSED_PAD src0_sel:WORD_1 src1_sel:DWORD
	v_add3_u32 v61, v61, v71, s56
	v_add3_u32 v59, v59, v72, s56
	v_and_b32_e32 v61, 0xffff0000, v61
	v_and_b32_e32 v71, 0xffff0000, v59
	v_lshl_add_u64 v[62:63], v[64:65], 1, v[52:53]
	v_or_b32_sdwa v59, v61, v60 dst_sel:DWORD dst_unused:UNUSED_PAD src0_sel:DWORD src1_sel:WORD_1
	v_or_b32_sdwa v58, v71, v58 dst_sel:DWORD dst_unused:UNUSED_PAD src0_sel:DWORD src1_sel:WORD_1
	global_store_dwordx2 v[62:63], v[58:59], off offset:32
.LBB0_251:
	s_nop 0
	s_and_b64 vcc, exec, s[36:37]
	v_pk_fma_f32 v[38:39], v[38:39], v[126:127], v[216:217]
	v_pk_fma_f32 v[36:37], v[36:37], v[124:125], v[214:215]
	global_store_dwordx4 v[50:51], v[36:39], off offset:128
	s_cbranch_vccnz .LBB0_253
	v_lshl_add_u64 v[62:63], v[56:57], 0, v[66:67]
	v_pk_mul_f32 v[60:61], v[38:39], v[146:147]
	v_pk_mul_f32 v[58:59], v[36:37], v[144:145]
	v_pk_add_f32 v[62:63], v[162:163], 1.0 op_sel_hi:[1,0]
	v_pk_add_f32 v[72:73], v[160:161], 1.0 op_sel_hi:[1,0]
	v_pk_mul_f32 v[60:61], v[60:61], v[62:63]
	v_pk_mul_f32 v[58:59], v[58:59], v[72:73]
	v_and_b32_sdwa v71, v60, v170 dst_sel:DWORD dst_unused:UNUSED_PAD src0_sel:WORD_1 src1_sel:DWORD
	v_and_b32_sdwa v72, v58, v170 dst_sel:DWORD dst_unused:UNUSED_PAD src0_sel:WORD_1 src1_sel:DWORD
	v_add3_u32 v58, v58, v72, s56
	v_add3_u32 v60, v60, v71, s56
	v_and_b32_sdwa v71, v61, v170 dst_sel:DWORD dst_unused:UNUSED_PAD src0_sel:WORD_1 src1_sel:DWORD
	v_and_b32_sdwa v72, v59, v170 dst_sel:DWORD dst_unused:UNUSED_PAD src0_sel:WORD_1 src1_sel:DWORD
	v_add3_u32 v61, v61, v71, s56
	v_add3_u32 v59, v59, v72, s56
	v_and_b32_e32 v61, 0xffff0000, v61
	v_and_b32_e32 v71, 0xffff0000, v59
	v_lshl_add_u64 v[62:63], v[64:65], 1, v[52:53]
	v_or_b32_sdwa v59, v61, v60 dst_sel:DWORD dst_unused:UNUSED_PAD src0_sel:DWORD src1_sel:WORD_1
	v_or_b32_sdwa v58, v71, v58 dst_sel:DWORD dst_unused:UNUSED_PAD src0_sel:DWORD src1_sel:WORD_1
	global_store_dwordx2 v[62:63], v[58:59], off offset:64
.LBB0_253:
	s_nop 0
	s_and_b64 vcc, exec, s[36:37]
	v_pk_fma_f32 v[34:35], v[34:35], v[134:135], v[220:221]
	v_pk_fma_f32 v[32:33], v[32:33], v[132:133], v[218:219]
	global_store_dwordx4 v[50:51], v[32:35], off offset:192
	s_cbranch_vccnz .LBB0_255
	v_lshl_add_u64 v[50:51], v[56:57], 0, v[66:67]
	v_lshl_add_u64 v[50:51], v[64:65], 1, v[52:53]
	v_pk_mul_f32 v[52:53], v[34:35], v[150:151]
	v_pk_mul_f32 v[58:59], v[32:33], v[148:149]
	v_pk_add_f32 v[56:57], v[182:183], 1.0 op_sel_hi:[1,0]
	v_pk_add_f32 v[54:55], v[180:181], 1.0 op_sel_hi:[1,0]
	v_pk_mul_f32 v[52:53], v[52:53], v[56:57]
	v_pk_mul_f32 v[54:55], v[58:59], v[54:55]
	v_and_b32_sdwa v58, v53, v170 dst_sel:DWORD dst_unused:UNUSED_PAD src0_sel:WORD_1 src1_sel:DWORD
	v_and_b32_sdwa v59, v55, v170 dst_sel:DWORD dst_unused:UNUSED_PAD src0_sel:WORD_1 src1_sel:DWORD
	v_and_b32_sdwa v56, v52, v170 dst_sel:DWORD dst_unused:UNUSED_PAD src0_sel:WORD_1 src1_sel:DWORD
	v_and_b32_sdwa v57, v54, v170 dst_sel:DWORD dst_unused:UNUSED_PAD src0_sel:WORD_1 src1_sel:DWORD
	v_add3_u32 v53, v53, v58, s56
	v_add3_u32 v55, v55, v59, s56
	v_add3_u32 v54, v54, v57, s56
	v_add3_u32 v52, v52, v56, s56
	v_and_b32_e32 v53, 0xffff0000, v53
	v_and_b32_e32 v55, 0xffff0000, v55
	v_or_b32_sdwa v53, v53, v52 dst_sel:DWORD dst_unused:UNUSED_PAD src0_sel:DWORD src1_sel:WORD_1
	v_or_b32_sdwa v52, v55, v54 dst_sel:DWORD dst_unused:UNUSED_PAD src0_sel:DWORD src1_sel:WORD_1
	global_store_dwordx2 v[50:51], v[52:53], off offset:96

.LBB0_257:
	s_or_b64 exec, exec, s[2:3]
	v_add_u32_e32 v32, 0xffffe020, v80
	v_or_b32_e32 v34, 32, v70
	v_lshrrev_b32_e32 v32, 10, v32
	s_movk_i32 s2, 0x1800
	v_mad_u32_u24 v32, v32, s2, s2
	v_cmp_lt_i32_e32 vcc, s13, v34
	v_ashrrev_i32_e32 v35, 31, v34
	v_readlane_b32 s2, v250, 15
	v_cndmask_b32_e32 v38, 0, v32, vcc
	v_ashrrev_i32_e32 v39, 31, v38
	s_waitcnt lgkmcnt(0)
	v_lshl_add_u64 v[32:33], v[38:39], 2, s[40:41]
	v_lshl_add_u64 v[36:37], v[32:33], 0, v[66:67]
	v_lshlrev_b64 v[32:33], 12, v[34:35]
	v_readlane_b32 s3, v250, 16
	v_lshlrev_b64 v[34:35], 10, v[34:35]
	s_and_b64 vcc, exec, s[36:37]
	v_lshl_add_u64 v[32:33], s[2:3], 0, v[32:33]
	v_lshl_add_u64 v[32:33], v[32:33], 0, v[66:67]
	v_readlane_b32 s2, v250, 21
	v_readlane_b32 s3, v250, 22
	v_lshl_add_u64 v[38:39], v[38:39], 2, s[42:43]
	global_load_dwordx4 v[206:209], v[224:225], off
	global_load_dwordx4 v[210:213], v[224:225], off offset:64
	global_load_dwordx4 v[214:217], v[224:225], off offset:128
	global_load_dwordx4 v[218:221], v[224:225], off offset:192
	s_waitcnt vmcnt(8)
	v_pk_fma_f32 v[30:31], v[30:31], v[118:119], v[192:193]
	v_pk_fma_f32 v[28:29], v[28:29], v[116:117], v[190:191]
	v_lshl_add_u64 v[34:35], v[34:35], 1, s[2:3]
	global_store_dwordx4 v[32:33], v[28:31], off
	s_cbranch_vccnz .LBB0_259
	v_lshl_add_u64 v[44:45], v[38:39], 0, v[66:67]
	v_pk_mul_f32 v[42:43], v[30:31], v[138:139]
	v_pk_mul_f32 v[40:41], v[28:29], v[136:137]
	v_pk_add_f32 v[46:47], v[154:155], 1.0 op_sel_hi:[1,0]
	v_pk_add_f32 v[44:45], v[152:153], 1.0 op_sel_hi:[1,0]
	v_pk_mul_f32 v[42:43], v[42:43], v[46:47]
	v_pk_mul_f32 v[40:41], v[40:41], v[44:45]
	v_and_b32_sdwa v46, v42, v170 dst_sel:DWORD dst_unused:UNUSED_PAD src0_sel:WORD_1 src1_sel:DWORD
	v_and_b32_sdwa v47, v40, v170 dst_sel:DWORD dst_unused:UNUSED_PAD src0_sel:WORD_1 src1_sel:DWORD
	v_add3_u32 v40, v40, v47, s56
	v_add3_u32 v42, v42, v46, s56
	v_and_b32_sdwa v46, v43, v170 dst_sel:DWORD dst_unused:UNUSED_PAD src0_sel:WORD_1 src1_sel:DWORD
	v_and_b32_sdwa v47, v41, v170 dst_sel:DWORD dst_unused:UNUSED_PAD src0_sel:WORD_1 src1_sel:DWORD
	v_add3_u32 v43, v43, v46, s56
	v_add3_u32 v41, v41, v47, s56
	v_and_b32_e32 v43, 0xffff0000, v43
	v_and_b32_e32 v46, 0xffff0000, v41
	v_lshl_add_u64 v[44:45], v[64:65], 1, v[34:35]
	v_or_b32_sdwa v41, v43, v42 dst_sel:DWORD dst_unused:UNUSED_PAD src0_sel:DWORD src1_sel:WORD_1
	v_or_b32_sdwa v40, v46, v40 dst_sel:DWORD dst_unused:UNUSED_PAD src0_sel:DWORD src1_sel:WORD_1
	global_store_dwordx2 v[44:45], v[40:41], off
.LBB0_259:
	s_nop 0
	s_and_b64 vcc, exec, s[36:37]
	v_pk_fma_f32 v[26:27], v[26:27], v[122:123], v[196:197]
	v_pk_fma_f32 v[24:25], v[24:25], v[120:121], v[194:195]
	global_store_dwordx4 v[32:33], v[24:27], off offset:64
	s_cbranch_vccnz .LBB0_261
	v_lshl_add_u64 v[44:45], v[38:39], 0, v[66:67]
	v_pk_mul_f32 v[42:43], v[26:27], v[142:143]
	v_pk_mul_f32 v[40:41], v[24:25], v[140:141]
	v_pk_add_f32 v[46:47], v[158:159], 1.0 op_sel_hi:[1,0]
	v_pk_add_f32 v[44:45], v[156:157], 1.0 op_sel_hi:[1,0]
	v_pk_mul_f32 v[42:43], v[42:43], v[46:47]
	v_pk_mul_f32 v[40:41], v[40:41], v[44:45]
	v_and_b32_sdwa v46, v42, v170 dst_sel:DWORD dst_unused:UNUSED_PAD src0_sel:WORD_1 src1_sel:DWORD
	v_and_b32_sdwa v47, v40, v170 dst_sel:DWORD dst_unused:UNUSED_PAD src0_sel:WORD_1 src1_sel:DWORD
	v_add3_u32 v40, v40, v47, s56
	v_add3_u32 v42, v42, v46, s56
	v_and_b32_sdwa v46, v43, v170 dst_sel:DWORD dst_unused:UNUSED_PAD src0_sel:WORD_1 src1_sel:DWORD
	v_and_b32_sdwa v47, v41, v170 dst_sel:DWORD dst_unused:UNUSED_PAD src0_sel:WORD_1 src1_sel:DWORD
	v_add3_u32 v43, v43, v46, s56
	v_add3_u32 v41, v41, v47, s56
	v_and_b32_e32 v43, 0xffff0000, v43
	v_and_b32_e32 v46, 0xffff0000, v41
	v_lshl_add_u64 v[44:45], v[64:65], 1, v[34:35]
	v_or_b32_sdwa v41, v43, v42 dst_sel:DWORD dst_unused:UNUSED_PAD src0_sel:DWORD src1_sel:WORD_1
	v_or_b32_sdwa v40, v46, v40 dst_sel:DWORD dst_unused:UNUSED_PAD src0_sel:DWORD src1_sel:WORD_1
	global_store_dwordx2 v[44:45], v[40:41], off offset:32
.LBB0_261:
	s_nop 0
	s_and_b64 vcc, exec, s[36:37]
	v_pk_fma_f32 v[22:23], v[22:23], v[126:127], v[200:201]
	v_pk_fma_f32 v[20:21], v[20:21], v[124:125], v[198:199]
	global_store_dwordx4 v[32:33], v[20:23], off offset:128
	s_cbranch_vccnz .LBB0_263
	v_lshl_add_u64 v[44:45], v[38:39], 0, v[66:67]
	v_pk_mul_f32 v[42:43], v[22:23], v[146:147]
	v_pk_mul_f32 v[40:41], v[20:21], v[144:145]
	v_pk_add_f32 v[46:47], v[162:163], 1.0 op_sel_hi:[1,0]
	v_pk_add_f32 v[44:45], v[160:161], 1.0 op_sel_hi:[1,0]
	v_pk_mul_f32 v[42:43], v[42:43], v[46:47]
	v_pk_mul_f32 v[40:41], v[40:41], v[44:45]
	v_and_b32_sdwa v46, v42, v170 dst_sel:DWORD dst_unused:UNUSED_PAD src0_sel:WORD_1 src1_sel:DWORD
	v_and_b32_sdwa v47, v40, v170 dst_sel:DWORD dst_unused:UNUSED_PAD src0_sel:WORD_1 src1_sel:DWORD
	v_add3_u32 v40, v40, v47, s56
	v_add3_u32 v42, v42, v46, s56
	v_and_b32_sdwa v46, v43, v170 dst_sel:DWORD dst_unused:UNUSED_PAD src0_sel:WORD_1 src1_sel:DWORD
	v_and_b32_sdwa v47, v41, v170 dst_sel:DWORD dst_unused:UNUSED_PAD src0_sel:WORD_1 src1_sel:DWORD
	v_add3_u32 v43, v43, v46, s56
	v_add3_u32 v41, v41, v47, s56
	v_and_b32_e32 v43, 0xffff0000, v43
	v_and_b32_e32 v46, 0xffff0000, v41
	v_lshl_add_u64 v[44:45], v[64:65], 1, v[34:35]
	v_or_b32_sdwa v41, v43, v42 dst_sel:DWORD dst_unused:UNUSED_PAD src0_sel:DWORD src1_sel:WORD_1
	v_or_b32_sdwa v40, v46, v40 dst_sel:DWORD dst_unused:UNUSED_PAD src0_sel:DWORD src1_sel:WORD_1
	global_store_dwordx2 v[44:45], v[40:41], off offset:64
.LBB0_263:
	s_nop 0
	s_and_b64 vcc, exec, s[36:37]
	v_pk_fma_f32 v[18:19], v[18:19], v[134:135], v[204:205]
	v_pk_fma_f32 v[16:17], v[16:17], v[132:133], v[202:203]
	global_store_dwordx4 v[32:33], v[16:19], off offset:192
	s_cbranch_vccnz .LBB0_265
	v_lshl_add_u64 v[32:33], v[38:39], 0, v[66:67]
	v_lshl_add_u64 v[32:33], v[64:65], 1, v[34:35]
	v_pk_mul_f32 v[34:35], v[18:19], v[150:151]
	v_pk_mul_f32 v[40:41], v[16:17], v[148:149]
	v_pk_add_f32 v[38:39], v[182:183], 1.0 op_sel_hi:[1,0]
	v_pk_add_f32 v[36:37], v[180:181], 1.0 op_sel_hi:[1,0]
	v_pk_mul_f32 v[34:35], v[34:35], v[38:39]
	v_pk_mul_f32 v[36:37], v[40:41], v[36:37]
	v_and_b32_sdwa v40, v35, v170 dst_sel:DWORD dst_unused:UNUSED_PAD src0_sel:WORD_1 src1_sel:DWORD
	v_and_b32_sdwa v41, v37, v170 dst_sel:DWORD dst_unused:UNUSED_PAD src0_sel:WORD_1 src1_sel:DWORD
	v_and_b32_sdwa v38, v34, v170 dst_sel:DWORD dst_unused:UNUSED_PAD src0_sel:WORD_1 src1_sel:DWORD
	v_and_b32_sdwa v39, v36, v170 dst_sel:DWORD dst_unused:UNUSED_PAD src0_sel:WORD_1 src1_sel:DWORD
	v_add3_u32 v35, v35, v40, s56
	v_add3_u32 v37, v37, v41, s56
	v_add3_u32 v36, v36, v39, s56
	v_add3_u32 v34, v34, v38, s56
	v_and_b32_e32 v35, 0xffff0000, v35
	v_and_b32_e32 v37, 0xffff0000, v37
	v_or_b32_sdwa v35, v35, v34 dst_sel:DWORD dst_unused:UNUSED_PAD src0_sel:DWORD src1_sel:WORD_1
	v_or_b32_sdwa v34, v37, v36 dst_sel:DWORD dst_unused:UNUSED_PAD src0_sel:DWORD src1_sel:WORD_1
	global_store_dwordx2 v[32:33], v[34:35], off offset:96

.LBB0_267:
	s_or_b64 exec, exec, s[2:3]
	v_add_u32_e32 v16, 0xffffe030, v80
	v_or_b32_e32 v18, 48, v70
	v_lshrrev_b32_e32 v16, 10, v16
	s_movk_i32 s2, 0x1800
	v_mad_u32_u24 v16, v16, s2, s2
	v_cmp_lt_i32_e32 vcc, s13, v18
	v_ashrrev_i32_e32 v19, 31, v18
	v_readlane_b32 s2, v250, 15
	v_cndmask_b32_e32 v22, 0, v16, vcc
	v_ashrrev_i32_e32 v23, 31, v22
	s_waitcnt lgkmcnt(0)
	v_lshl_add_u64 v[16:17], v[22:23], 2, s[40:41]
	v_lshl_add_u64 v[20:21], v[16:17], 0, v[66:67]
	v_lshlrev_b64 v[16:17], 12, v[18:19]
	v_readlane_b32 s3, v250, 16
	v_lshlrev_b64 v[18:19], 10, v[18:19]
	s_and_b64 vcc, exec, s[36:37]
	v_lshl_add_u64 v[16:17], s[2:3], 0, v[16:17]
	v_lshl_add_u64 v[16:17], v[16:17], 0, v[66:67]
	v_readlane_b32 s2, v250, 21
	v_readlane_b32 s3, v250, 22
	v_lshl_add_u64 v[22:23], v[22:23], 2, s[42:43]
	s_waitcnt vmcnt(4)
	v_pk_fma_f32 v[14:15], v[14:15], v[118:119], v[208:209]
	v_pk_fma_f32 v[12:13], v[12:13], v[116:117], v[206:207]
	v_lshl_add_u64 v[18:19], v[18:19], 1, s[2:3]
	global_store_dwordx4 v[16:17], v[12:15], off
	s_cbranch_vccnz .LBB0_269
	v_lshl_add_u64 v[28:29], v[22:23], 0, v[66:67]
	v_pk_mul_f32 v[26:27], v[14:15], v[138:139]
	v_pk_mul_f32 v[24:25], v[12:13], v[136:137]
	v_pk_add_f32 v[30:31], v[154:155], 1.0 op_sel_hi:[1,0]
	v_pk_add_f32 v[28:29], v[152:153], 1.0 op_sel_hi:[1,0]
	v_pk_mul_f32 v[26:27], v[26:27], v[30:31]
	v_pk_mul_f32 v[24:25], v[24:25], v[28:29]
	v_and_b32_sdwa v30, v26, v170 dst_sel:DWORD dst_unused:UNUSED_PAD src0_sel:WORD_1 src1_sel:DWORD
	v_and_b32_sdwa v31, v24, v170 dst_sel:DWORD dst_unused:UNUSED_PAD src0_sel:WORD_1 src1_sel:DWORD
	v_add3_u32 v24, v24, v31, s56
	v_add3_u32 v26, v26, v30, s56
	v_and_b32_sdwa v30, v27, v170 dst_sel:DWORD dst_unused:UNUSED_PAD src0_sel:WORD_1 src1_sel:DWORD
	v_and_b32_sdwa v31, v25, v170 dst_sel:DWORD dst_unused:UNUSED_PAD src0_sel:WORD_1 src1_sel:DWORD
	v_add3_u32 v27, v27, v30, s56
	v_add3_u32 v25, v25, v31, s56
	v_and_b32_e32 v27, 0xffff0000, v27
	v_and_b32_e32 v30, 0xffff0000, v25
	v_lshl_add_u64 v[28:29], v[64:65], 1, v[18:19]
	v_or_b32_sdwa v25, v27, v26 dst_sel:DWORD dst_unused:UNUSED_PAD src0_sel:DWORD src1_sel:WORD_1
	v_or_b32_sdwa v24, v30, v24 dst_sel:DWORD dst_unused:UNUSED_PAD src0_sel:DWORD src1_sel:WORD_1
	global_store_dwordx2 v[28:29], v[24:25], off
.LBB0_269:
	s_nop 0
	s_and_b64 vcc, exec, s[36:37]
	v_pk_fma_f32 v[10:11], v[10:11], v[122:123], v[212:213]
	v_pk_fma_f32 v[8:9], v[8:9], v[120:121], v[210:211]
	global_store_dwordx4 v[16:17], v[8:11], off offset:64
	s_cbranch_vccnz .LBB0_271
	v_lshl_add_u64 v[28:29], v[22:23], 0, v[66:67]
	v_pk_mul_f32 v[26:27], v[10:11], v[142:143]
	v_pk_mul_f32 v[24:25], v[8:9], v[140:141]
	v_pk_add_f32 v[30:31], v[158:159], 1.0 op_sel_hi:[1,0]
	v_pk_add_f32 v[28:29], v[156:157], 1.0 op_sel_hi:[1,0]
	v_pk_mul_f32 v[26:27], v[26:27], v[30:31]
	v_pk_mul_f32 v[24:25], v[24:25], v[28:29]
	v_and_b32_sdwa v30, v26, v170 dst_sel:DWORD dst_unused:UNUSED_PAD src0_sel:WORD_1 src1_sel:DWORD
	v_and_b32_sdwa v31, v24, v170 dst_sel:DWORD dst_unused:UNUSED_PAD src0_sel:WORD_1 src1_sel:DWORD
	v_add3_u32 v24, v24, v31, s56
	v_add3_u32 v26, v26, v30, s56
	v_and_b32_sdwa v30, v27, v170 dst_sel:DWORD dst_unused:UNUSED_PAD src0_sel:WORD_1 src1_sel:DWORD
	v_and_b32_sdwa v31, v25, v170 dst_sel:DWORD dst_unused:UNUSED_PAD src0_sel:WORD_1 src1_sel:DWORD
	v_add3_u32 v27, v27, v30, s56
	v_add3_u32 v25, v25, v31, s56
	v_and_b32_e32 v27, 0xffff0000, v27
	v_and_b32_e32 v30, 0xffff0000, v25
	v_lshl_add_u64 v[28:29], v[64:65], 1, v[18:19]
	v_or_b32_sdwa v25, v27, v26 dst_sel:DWORD dst_unused:UNUSED_PAD src0_sel:DWORD src1_sel:WORD_1
	v_or_b32_sdwa v24, v30, v24 dst_sel:DWORD dst_unused:UNUSED_PAD src0_sel:DWORD src1_sel:WORD_1
	global_store_dwordx2 v[28:29], v[24:25], off offset:32
.LBB0_271:
	s_nop 0
	s_and_b64 vcc, exec, s[36:37]
	v_pk_fma_f32 v[6:7], v[6:7], v[126:127], v[216:217]
	v_pk_fma_f32 v[4:5], v[4:5], v[124:125], v[214:215]
	global_store_dwordx4 v[16:17], v[4:7], off offset:128
	s_cbranch_vccnz .LBB0_273
	v_lshl_add_u64 v[28:29], v[22:23], 0, v[66:67]
	v_pk_mul_f32 v[26:27], v[6:7], v[146:147]
	v_pk_mul_f32 v[24:25], v[4:5], v[144:145]
	v_pk_add_f32 v[30:31], v[162:163], 1.0 op_sel_hi:[1,0]
	v_pk_add_f32 v[28:29], v[160:161], 1.0 op_sel_hi:[1,0]
	v_pk_mul_f32 v[26:27], v[26:27], v[30:31]
	v_pk_mul_f32 v[24:25], v[24:25], v[28:29]
	v_and_b32_sdwa v30, v26, v170 dst_sel:DWORD dst_unused:UNUSED_PAD src0_sel:WORD_1 src1_sel:DWORD
	v_and_b32_sdwa v31, v24, v170 dst_sel:DWORD dst_unused:UNUSED_PAD src0_sel:WORD_1 src1_sel:DWORD
	v_add3_u32 v24, v24, v31, s56
	v_add3_u32 v26, v26, v30, s56
	v_and_b32_sdwa v30, v27, v170 dst_sel:DWORD dst_unused:UNUSED_PAD src0_sel:WORD_1 src1_sel:DWORD
	v_and_b32_sdwa v31, v25, v170 dst_sel:DWORD dst_unused:UNUSED_PAD src0_sel:WORD_1 src1_sel:DWORD
	v_add3_u32 v27, v27, v30, s56
	v_add3_u32 v25, v25, v31, s56
	v_and_b32_e32 v27, 0xffff0000, v27
	v_and_b32_e32 v30, 0xffff0000, v25
	v_lshl_add_u64 v[28:29], v[64:65], 1, v[18:19]
	v_or_b32_sdwa v25, v27, v26 dst_sel:DWORD dst_unused:UNUSED_PAD src0_sel:DWORD src1_sel:WORD_1
	v_or_b32_sdwa v24, v30, v24 dst_sel:DWORD dst_unused:UNUSED_PAD src0_sel:DWORD src1_sel:WORD_1
	global_store_dwordx2 v[28:29], v[24:25], off offset:64
.LBB0_273:
	s_nop 0
	s_and_b64 vcc, exec, s[36:37]
	v_pk_fma_f32 v[2:3], v[2:3], v[134:135], v[220:221]
	v_pk_fma_f32 v[0:1], v[0:1], v[132:133], v[218:219]
	global_store_dwordx4 v[16:17], v[0:3], off offset:192
	s_cbranch_vccnz .LBB0_275
	v_lshl_add_u64 v[16:17], v[22:23], 0, v[66:67]
	v_lshl_add_u64 v[16:17], v[64:65], 1, v[18:19]
	v_pk_mul_f32 v[18:19], v[2:3], v[150:151]
	v_pk_mul_f32 v[24:25], v[0:1], v[148:149]
	v_pk_add_f32 v[22:23], v[182:183], 1.0 op_sel_hi:[1,0]
	v_pk_add_f32 v[20:21], v[180:181], 1.0 op_sel_hi:[1,0]
	v_pk_mul_f32 v[18:19], v[18:19], v[22:23]
	v_pk_mul_f32 v[20:21], v[24:25], v[20:21]
	v_and_b32_sdwa v24, v19, v170 dst_sel:DWORD dst_unused:UNUSED_PAD src0_sel:WORD_1 src1_sel:DWORD
	v_and_b32_sdwa v25, v21, v170 dst_sel:DWORD dst_unused:UNUSED_PAD src0_sel:WORD_1 src1_sel:DWORD
	v_and_b32_sdwa v22, v18, v170 dst_sel:DWORD dst_unused:UNUSED_PAD src0_sel:WORD_1 src1_sel:DWORD
	v_and_b32_sdwa v23, v20, v170 dst_sel:DWORD dst_unused:UNUSED_PAD src0_sel:WORD_1 src1_sel:DWORD
	v_add3_u32 v19, v19, v24, s56
	v_add3_u32 v21, v21, v25, s56
	v_add3_u32 v20, v20, v23, s56
	v_add3_u32 v18, v18, v22, s56
	v_and_b32_e32 v19, 0xffff0000, v19
	v_and_b32_e32 v21, 0xffff0000, v21
	v_or_b32_sdwa v19, v19, v18 dst_sel:DWORD dst_unused:UNUSED_PAD src0_sel:DWORD src1_sel:WORD_1
	v_or_b32_sdwa v18, v21, v20 dst_sel:DWORD dst_unused:UNUSED_PAD src0_sel:DWORD src1_sel:WORD_1
	global_store_dwordx2 v[16:17], v[18:19], off offset:96

.LBB0_327:
	s_add_i32 s0, s1, 2
	s_setprio 1
	v_add_u32_e32 v127, v89, v90
	ds_read_b128 v[100:103], v127 offset:16384
	ds_read_b128 v[106:109], v127 offset:18432
	ds_read_b128 v[110:113], v127 offset:20480
	ds_read_b128 v[114:117], v127 offset:22528
	v_add_u32_e32 v126, v88, v90
	ds_read_b128 v[92:95], v126
	ds_read_b128 v[96:99], v126 offset:2048
	s_add_i32 s1, s1, 4
	s_min_u32 s1, s1, 63
	v_add_u32_e32 v128, v88, v91
	v_add_u32_e32 v130, v89, v91
	s_lshl_b32 s92, s1, 7
	ds_read_b128 v[118:121], v130 offset:18432
	ds_read_b128 v[122:125], v130 offset:20480
	ds_read_b128 v[132:135], v130 offset:22528
	s_waitcnt lgkmcnt(4)
	v_mfma_f32_16x16x32_bf16 v[76:79], v[100:103], v[92:95], v[76:79]
	v_lshl_add_u64 v[48:49], v[80:81], 0, s[92:93]
	v_add_co_u32_e32 v50, vcc, s7, v48
	v_mfma_f32_16x16x32_bf16 v[56:59], v[106:109], v[92:95], v[56:59]
	s_nop 0
	v_addc_co_u32_e32 v51, vcc, 0, v49, vcc
	v_mfma_f32_16x16x32_bf16 v[44:47], v[110:113], v[92:95], v[44:47]
	v_mfma_f32_16x16x32_bf16 v[24:27], v[114:117], v[92:95], v[24:27]
	s_waitcnt lgkmcnt(3)
	v_mfma_f32_16x16x32_bf16 v[92:95], v[100:103], v[96:99], v[12:15]
	s_nop 2
	ds_read_b128 v[12:15], v128
	v_mfma_f32_16x16x32_bf16 v[100:103], v[106:109], v[96:99], v[8:11]
	v_mfma_f32_16x16x32_bf16 v[106:109], v[110:113], v[96:99], v[4:7]
	ds_read_b128 v[110:113], v128 offset:2048
	v_mfma_f32_16x16x32_bf16 v[96:99], v[114:117], v[96:99], v[0:3]
	ds_read_b128 v[114:117], v130 offset:16384
	global_load_dwordx4 v[72:75], v[48:49], off
	s_waitcnt vmcnt(1)
	ds_write_b128 v87, v[16:19] offset:53248
	global_load_dwordx4 v[68:71], v[50:51], off
	v_add_co_u32_e32 v50, vcc, s52, v48
	ds_write_b128 v87, v[20:23] offset:49152
	s_nop 0
	v_addc_co_u32_e32 v51, vcc, 0, v49, vcc
	v_add_co_u32_e32 v48, vcc, s34, v48
	global_load_dwordx4 v[64:67], v[50:51], off
	s_nop 0
	v_addc_co_u32_e32 v49, vcc, 0, v49, vcc
	ds_write_b128 v87, v[28:31] offset:45056
	global_load_dwordx4 v[60:63], v[48:49], off
	v_lshl_add_u64 v[48:49], v[82:83], 0, s[92:93]
	ds_write_b128 v87, v[36:39] offset:32768
	s_waitcnt lgkmcnt(4)
	v_mfma_f32_16x16x32_bf16 v[0:3], v[114:117], v[12:15], v[76:79]
	v_mfma_f32_16x16x32_bf16 v[4:7], v[118:121], v[12:15], v[56:59]
	global_load_dwordx4 v[52:55], v[48:49], off
	v_add_co_u32_e32 v48, vcc, s7, v48
	ds_write_b128 v87, v[40:43] offset:36864
	s_nop 0
	v_addc_co_u32_e32 v49, vcc, 0, v49, vcc
	v_mfma_f32_16x16x32_bf16 v[8:11], v[122:125], v[12:15], v[44:47]
	v_mfma_f32_16x16x32_bf16 v[12:15], v[132:135], v[12:15], v[24:27]
	global_load_dwordx4 v[48:51], v[48:49], off
	ds_write_b128 v87, v[32:35] offset:40960
	v_mfma_f32_16x16x32_bf16 v[24:27], v[114:117], v[110:113], v[92:95]
	v_mfma_f32_16x16x32_bf16 v[44:47], v[118:121], v[110:113], v[100:103]
	v_mfma_f32_16x16x32_bf16 v[56:59], v[122:125], v[110:113], v[106:109]
	v_mfma_f32_16x16x32_bf16 v[76:79], v[132:135], v[110:113], v[96:99]
	s_setprio 0
	s_waitcnt lgkmcnt(0)
	s_barrier
	s_setprio 1
	ds_read_b128 v[100:103], v127 offset:49152
	ds_read_b128 v[106:109], v127 offset:51200
	ds_read_b128 v[110:113], v127 offset:53248
	ds_read_b128 v[114:117], v127 offset:55296
	ds_read_b128 v[92:95], v126 offset:32768
	ds_read_b128 v[96:99], v126 offset:34816
	s_min_u32 s1, s0, 60
	s_lshl_b32 s92, s1, 7
	ds_read_b128 v[118:121], v130 offset:51200
	ds_read_b128 v[122:125], v130 offset:53248
	ds_read_b128 v[132:135], v130 offset:55296
	s_waitcnt lgkmcnt(4)
	v_mfma_f32_16x16x32_bf16 v[0:3], v[100:103], v[92:95], v[0:3]
	v_lshl_add_u64 v[16:17], v[80:81], 0, s[92:93]
	v_add_co_u32_e32 v18, vcc, s7, v16
	v_mfma_f32_16x16x32_bf16 v[4:7], v[106:109], v[92:95], v[4:7]
	s_nop 0
	v_addc_co_u32_e32 v19, vcc, 0, v17, vcc
	v_mfma_f32_16x16x32_bf16 v[8:11], v[110:113], v[92:95], v[8:11]
	v_mfma_f32_16x16x32_bf16 v[12:15], v[114:117], v[92:95], v[12:15]
	s_waitcnt lgkmcnt(3)
	v_mfma_f32_16x16x32_bf16 v[92:95], v[100:103], v[96:99], v[24:27]
	s_nop 2
	ds_read_b128 v[24:27], v128 offset:32768
	v_mfma_f32_16x16x32_bf16 v[100:103], v[106:109], v[96:99], v[44:47]
	v_mfma_f32_16x16x32_bf16 v[106:109], v[110:113], v[96:99], v[56:59]
	ds_read_b128 v[110:113], v128 offset:34816
	v_mfma_f32_16x16x32_bf16 v[96:99], v[114:117], v[96:99], v[76:79]
	ds_read_b128 v[114:117], v130 offset:49152
	global_load_dwordx4 v[36:39], v[16:17], off offset:384
	s_waitcnt vmcnt(1)
	ds_write_b128 v87, v[48:51] offset:20480
	global_load_dwordx4 v[40:43], v[18:19], off offset:384
	v_add_co_u32_e32 v18, vcc, s52, v16
	ds_write_b128 v87, v[52:55] offset:16384
	s_nop 0
	v_addc_co_u32_e32 v19, vcc, 0, v17, vcc
	v_add_co_u32_e32 v16, vcc, s34, v16
	global_load_dwordx4 v[32:35], v[18:19], off offset:384
	s_nop 0
	v_addc_co_u32_e32 v17, vcc, 0, v17, vcc
	ds_write_b128 v87, v[60:63] offset:12288
	global_load_dwordx4 v[28:31], v[16:17], off offset:384
	v_lshl_add_u64 v[16:17], v[82:83], 0, s[92:93]
	ds_write_b128 v87, v[72:75]
	s_waitcnt lgkmcnt(4)
	v_mfma_f32_16x16x32_bf16 v[76:79], v[114:117], v[24:27], v[0:3]
	v_mfma_f32_16x16x32_bf16 v[56:59], v[118:121], v[24:27], v[4:7]
	global_load_dwordx4 v[20:23], v[16:17], off offset:384
	v_add_co_u32_e32 v16, vcc, s7, v16
	ds_write_b128 v87, v[68:71] offset:4096
	s_nop 0
	v_addc_co_u32_e32 v17, vcc, 0, v17, vcc
	v_mfma_f32_16x16x32_bf16 v[44:47], v[122:125], v[24:27], v[8:11]
	v_mfma_f32_16x16x32_bf16 v[24:27], v[132:135], v[24:27], v[12:15]
	global_load_dwordx4 v[16:19], v[16:17], off offset:384
	ds_write_b128 v87, v[64:67] offset:8192
	v_mfma_f32_16x16x32_bf16 v[12:15], v[114:117], v[110:113], v[92:95]
	v_mfma_f32_16x16x32_bf16 v[8:11], v[118:121], v[110:113], v[100:103]
	v_mfma_f32_16x16x32_bf16 v[4:7], v[122:125], v[110:113], v[106:109]
	v_mfma_f32_16x16x32_bf16 v[0:3], v[132:135], v[110:113], v[96:99]
	s_setprio 0
	s_cmp_lt_u32 s0, 62
	s_mov_b32 s1, s0
	s_waitcnt lgkmcnt(0)
	s_barrier
	s_cbranch_scc1 .LBB0_327
	v_readlane_b32 s0, v251, 18
	s_nop 1
	v_add_u32_e32 v48, s0, v86
	v_readlane_b32 s0, v251, 19
	s_waitcnt vmcnt(0)
	v_add_u32_e32 v16, 0xffffe000, v48
	v_or_b32_e32 v34, v48, v85
	v_lshl_or_b32 v32, v84, 2, s0
	v_lshrrev_b32_e32 v16, 10, v16
	s_movk_i32 s0, 0x1800
	v_mad_u32_u24 v16, v16, s0, s0
	v_cmp_lt_i32_e32 vcc, s13, v34
	v_ashrrev_i32_e32 v35, 31, v34
	v_lshlrev_b32_e32 v128, 2, v32
	v_cndmask_b32_e32 v28, 0, v16, vcc
	v_ashrrev_i32_e32 v29, 31, v28
	v_lshl_add_u64 v[16:17], v[28:29], 2, s[40:41]
	v_readlane_b32 s0, v250, 15
	v_lshl_add_u64 v[40:41], v[16:17], 0, v[128:129]
	v_lshlrev_b64 v[16:17], 12, v[34:35]
	v_readlane_b32 s1, v250, 16
	v_lshlrev_b64 v[30:31], 10, v[34:35]
	s_and_b64 vcc, exec, s[36:37]
	v_lshl_add_u64 v[16:17], s[0:1], 0, v[16:17]
	v_lshl_add_u64 v[38:39], v[16:17], 0, v[128:129]
	global_load_dwordx4 v[60:63], v[40:41], off
	global_load_dwordx4 v[72:75], v[40:41], off offset:64
	global_load_dwordx4 v[80:83], v[40:41], off offset:128
	global_load_dwordx4 v[88:91], v[40:41], off offset:192
	global_load_dwordx4 v[190:193], v[38:39], off
	global_load_dwordx4 v[194:197], v[38:39], off offset:64
	global_load_dwordx4 v[198:201], v[38:39], off offset:128
	global_load_dwordx4 v[202:205], v[38:39], off offset:192
	v_add_co_u32_e32 v54, vcc, 0x10000, v38
	s_nop 1
	v_addc_co_u32_e32 v55, vcc, 0, v39, vcc
	global_load_dwordx4 v[206:209], v[54:55], off
	global_load_dwordx4 v[210:213], v[54:55], off offset:64
	global_load_dwordx4 v[214:217], v[54:55], off offset:128
	global_load_dwordx4 v[218:221], v[54:55], off offset:192
	v_readlane_b32 s0, v250, 21
	v_readlane_b32 s1, v250, 22
	v_lshl_add_u64 v[42:43], v[28:29], 2, s[42:43]
	v_lshlrev_b32_e32 v32, 1, v32
	v_lshl_add_u64 v[36:37], v[30:31], 1, s[0:1]
	s_waitcnt vmcnt(4)
	v_pk_fma_f32 v[18:19], v[78:79], v[62:63], v[192:193]
	v_pk_fma_f32 v[16:17], v[76:77], v[60:61], v[190:191]
	global_store_dwordx4 v[38:39], v[16:19], off
	s_cbranch_vccnz .LBB0_330
	v_lshl_add_u64 v[28:29], v[42:43], 0, v[128:129]
	global_load_dwordx4 v[136:139], v128, s[26:27]
	global_load_dwordx4 v[140:143], v128, s[26:27] offset:64
	global_load_dwordx4 v[144:147], v128, s[26:27] offset:128
	global_load_dwordx4 v[148:151], v128, s[26:27] offset:192
	v_mov_b32_e32 v33, v129
	global_load_dwordx4 v[152:155], v[28:29], off
	global_load_dwordx4 v[156:159], v[28:29], off offset:64
	global_load_dwordx4 v[160:163], v[28:29], off offset:128
	global_load_dwordx4 v[180:183], v[28:29], off offset:192
	s_waitcnt vmcnt(0)
	v_pk_mul_f32 v[22:23], v[18:19], v[138:139]
	v_pk_mul_f32 v[20:21], v[16:17], v[136:137]
	s_waitcnt vmcnt(0)
	v_pk_add_f32 v[30:31], v[154:155], 1.0 op_sel_hi:[1,0]
	v_pk_add_f32 v[28:29], v[152:153], 1.0 op_sel_hi:[1,0]
	v_pk_mul_f32 v[22:23], v[22:23], v[30:31]
	v_pk_mul_f32 v[20:21], v[20:21], v[28:29]
	v_and_b32_sdwa v30, v22, v170 dst_sel:DWORD dst_unused:UNUSED_PAD src0_sel:WORD_1 src1_sel:DWORD
	v_and_b32_sdwa v31, v20, v170 dst_sel:DWORD dst_unused:UNUSED_PAD src0_sel:WORD_1 src1_sel:DWORD
	v_add3_u32 v20, v20, v31, s56
	v_add3_u32 v22, v22, v30, s56
	v_and_b32_sdwa v30, v23, v170 dst_sel:DWORD dst_unused:UNUSED_PAD src0_sel:WORD_1 src1_sel:DWORD
	v_and_b32_sdwa v31, v21, v170 dst_sel:DWORD dst_unused:UNUSED_PAD src0_sel:WORD_1 src1_sel:DWORD
	v_add3_u32 v23, v23, v30, s56
	v_add3_u32 v21, v21, v31, s56
	v_and_b32_e32 v23, 0xffff0000, v23
	v_and_b32_e32 v30, 0xffff0000, v21
	v_lshl_add_u64 v[28:29], v[36:37], 0, v[32:33]
	v_or_b32_sdwa v21, v23, v22 dst_sel:DWORD dst_unused:UNUSED_PAD src0_sel:DWORD src1_sel:WORD_1
	v_or_b32_sdwa v20, v30, v20 dst_sel:DWORD dst_unused:UNUSED_PAD src0_sel:DWORD src1_sel:WORD_1
	global_store_dwordx2 v[28:29], v[20:21], off
.LBB0_330:
	s_nop 0
	s_and_b64 vcc, exec, s[36:37]
	s_waitcnt vmcnt(0)
	v_pk_fma_f32 v[22:23], v[58:59], v[74:75], v[196:197]
	v_pk_fma_f32 v[20:21], v[56:57], v[72:73], v[194:195]
	global_store_dwordx4 v[38:39], v[20:23], off offset:64
	s_cbranch_vccnz .LBB0_332
	v_lshl_add_u64 v[50:51], v[42:43], 0, v[128:129]
	v_mov_b32_e32 v33, v129
	v_pk_mul_f32 v[30:31], v[22:23], v[142:143]
	v_pk_mul_f32 v[28:29], v[20:21], v[140:141]
	v_pk_add_f32 v[52:53], v[158:159], 1.0 op_sel_hi:[1,0]
	v_pk_add_f32 v[50:51], v[156:157], 1.0 op_sel_hi:[1,0]
	v_pk_mul_f32 v[30:31], v[30:31], v[52:53]
	v_pk_mul_f32 v[28:29], v[28:29], v[50:51]
	v_lshl_add_u64 v[50:51], v[36:37], 0, v[32:33]
	v_and_b32_sdwa v33, v30, v170 dst_sel:DWORD dst_unused:UNUSED_PAD src0_sel:WORD_1 src1_sel:DWORD
	v_and_b32_sdwa v49, v28, v170 dst_sel:DWORD dst_unused:UNUSED_PAD src0_sel:WORD_1 src1_sel:DWORD
	v_add3_u32 v28, v28, v49, s56
	v_add3_u32 v30, v30, v33, s56
	v_and_b32_sdwa v33, v31, v170 dst_sel:DWORD dst_unused:UNUSED_PAD src0_sel:WORD_1 src1_sel:DWORD
	v_and_b32_sdwa v49, v29, v170 dst_sel:DWORD dst_unused:UNUSED_PAD src0_sel:WORD_1 src1_sel:DWORD
	v_add3_u32 v31, v31, v33, s56
	v_add3_u32 v29, v29, v49, s56
	v_and_b32_e32 v31, 0xffff0000, v31
	v_and_b32_e32 v33, 0xffff0000, v29
	v_or_b32_sdwa v29, v31, v30 dst_sel:DWORD dst_unused:UNUSED_PAD src0_sel:DWORD src1_sel:WORD_1
	v_or_b32_sdwa v28, v33, v28 dst_sel:DWORD dst_unused:UNUSED_PAD src0_sel:DWORD src1_sel:WORD_1
	global_store_dwordx2 v[50:51], v[28:29], off offset:32
.LBB0_332:
	s_nop 0
	s_and_b64 vcc, exec, s[36:37]
	v_pk_fma_f32 v[30:31], v[46:47], v[82:83], v[200:201]
	v_pk_fma_f32 v[28:29], v[44:45], v[80:81], v[198:199]
	global_store_dwordx4 v[38:39], v[28:31], off offset:128
	s_cbranch_vccnz .LBB0_334
	v_lshl_add_u64 v[50:51], v[42:43], 0, v[128:129]
	v_mov_b32_e32 v33, v129
	v_pk_mul_f32 v[46:47], v[30:31], v[146:147]
	v_pk_mul_f32 v[44:45], v[28:29], v[144:145]
	v_pk_add_f32 v[52:53], v[162:163], 1.0 op_sel_hi:[1,0]
	v_pk_add_f32 v[50:51], v[160:161], 1.0 op_sel_hi:[1,0]
	v_pk_mul_f32 v[46:47], v[46:47], v[52:53]
	v_pk_mul_f32 v[44:45], v[44:45], v[50:51]
	v_lshl_add_u64 v[50:51], v[36:37], 0, v[32:33]
	v_and_b32_sdwa v33, v46, v170 dst_sel:DWORD dst_unused:UNUSED_PAD src0_sel:WORD_1 src1_sel:DWORD
	v_and_b32_sdwa v49, v44, v170 dst_sel:DWORD dst_unused:UNUSED_PAD src0_sel:WORD_1 src1_sel:DWORD
	v_add3_u32 v44, v44, v49, s56
	v_add3_u32 v33, v46, v33, s56
	v_and_b32_sdwa v46, v47, v170 dst_sel:DWORD dst_unused:UNUSED_PAD src0_sel:WORD_1 src1_sel:DWORD
	v_and_b32_sdwa v49, v45, v170 dst_sel:DWORD dst_unused:UNUSED_PAD src0_sel:WORD_1 src1_sel:DWORD
	v_add3_u32 v46, v47, v46, s56
	v_add3_u32 v45, v45, v49, s56
	v_and_b32_e32 v46, 0xffff0000, v46
	v_and_b32_e32 v47, 0xffff0000, v45
	v_or_b32_sdwa v45, v46, v33 dst_sel:DWORD dst_unused:UNUSED_PAD src0_sel:DWORD src1_sel:WORD_1
	v_or_b32_sdwa v44, v47, v44 dst_sel:DWORD dst_unused:UNUSED_PAD src0_sel:DWORD src1_sel:WORD_1
	global_store_dwordx2 v[50:51], v[44:45], off offset:64
.LBB0_334:
	s_nop 0
	s_and_b64 vcc, exec, s[36:37]
	s_movk_i32 s89, 0xff
	v_pk_fma_f32 v[26:27], v[26:27], v[90:91], v[204:205]
	v_pk_fma_f32 v[24:25], v[24:25], v[88:89], v[202:203]
	global_store_dwordx4 v[38:39], v[24:27], off offset:192
	s_cbranch_vccnz .LBB0_336
	v_lshl_add_u64 v[42:43], v[42:43], 0, v[128:129]
	v_mov_b32_e32 v33, v129
	v_lshl_add_u64 v[36:37], v[36:37], 0, v[32:33]
	v_pk_mul_f32 v[40:41], v[26:27], v[150:151]
	v_pk_mul_f32 v[38:39], v[24:25], v[148:149]
	v_pk_add_f32 v[44:45], v[182:183], 1.0 op_sel_hi:[1,0]
	v_pk_add_f32 v[42:43], v[180:181], 1.0 op_sel_hi:[1,0]
	v_pk_mul_f32 v[40:41], v[40:41], v[44:45]
	v_pk_mul_f32 v[38:39], v[38:39], v[42:43]
	v_and_b32_sdwa v33, v40, v170 dst_sel:DWORD dst_unused:UNUSED_PAD src0_sel:WORD_1 src1_sel:DWORD
	v_and_b32_sdwa v42, v38, v170 dst_sel:DWORD dst_unused:UNUSED_PAD src0_sel:WORD_1 src1_sel:DWORD
	v_add3_u32 v38, v38, v42, s56
	v_add3_u32 v33, v40, v33, s56
	v_and_b32_sdwa v40, v41, v170 dst_sel:DWORD dst_unused:UNUSED_PAD src0_sel:WORD_1 src1_sel:DWORD
	v_and_b32_sdwa v42, v39, v170 dst_sel:DWORD dst_unused:UNUSED_PAD src0_sel:WORD_1 src1_sel:DWORD
	v_add3_u32 v40, v41, v40, s56
	v_add3_u32 v39, v39, v42, s56
	v_and_b32_e32 v40, 0xffff0000, v40
	v_and_b32_e32 v41, 0xffff0000, v39
	v_or_b32_sdwa v39, v40, v33 dst_sel:DWORD dst_unused:UNUSED_PAD src0_sel:DWORD src1_sel:WORD_1
	v_or_b32_sdwa v38, v41, v38 dst_sel:DWORD dst_unused:UNUSED_PAD src0_sel:DWORD src1_sel:WORD_1
	global_store_dwordx2 v[36:37], v[38:39], off offset:96

.LBB0_338:
	s_or_b64 exec, exec, s[2:3]
	s_waitcnt lgkmcnt(0)
	v_add_u32_e32 v17, 0xffffe010, v48
	v_or_b32_e32 v16, 16, v34
	v_lshrrev_b32_e32 v17, 10, v17
	s_movk_i32 s2, 0x1800
	v_mad_u32_u24 v17, v17, s2, s2
	v_cmp_lt_i32_e32 vcc, s13, v16
	v_readlane_b32 s2, v250, 15
	v_readlane_b32 s3, v250, 16
	v_cndmask_b32_e32 v20, 0, v17, vcc
	v_ashrrev_i32_e32 v21, 31, v20
	v_ashrrev_i32_e32 v17, 31, v16
	v_lshl_add_u64 v[18:19], v[20:21], 2, s[40:41]
	v_lshl_add_u64 v[22:23], v[18:19], 0, v[128:129]
	v_lshlrev_b64 v[18:19], 12, v[16:17]
	v_lshl_add_u64 v[18:19], s[2:3], 0, v[18:19]
	v_lshl_add_u64 v[18:19], v[18:19], 0, v[128:129]
	v_readlane_b32 s2, v250, 21
	v_lshlrev_b64 v[30:31], 10, v[16:17]
	v_readlane_b32 s3, v250, 22
	s_and_b64 vcc, exec, s[36:37]
	v_lshl_add_u64 v[24:25], v[20:21], 2, s[42:43]
	v_lshl_add_u64 v[20:21], v[30:31], 1, s[2:3]
	s_waitcnt vmcnt(4)
	v_pk_fma_f32 v[14:15], v[14:15], v[62:63], v[208:209]
	v_pk_fma_f32 v[12:13], v[12:13], v[60:61], v[206:207]
	global_store_dwordx4 v[18:19], v[12:15], off
	s_cbranch_vccnz .LBB0_340
	v_lshl_add_u64 v[30:31], v[24:25], 0, v[128:129]
	v_mov_b32_e32 v33, v129
	v_pk_mul_f32 v[28:29], v[14:15], v[138:139]
	v_pk_mul_f32 v[26:27], v[12:13], v[136:137]
	v_pk_add_f32 v[30:31], v[154:155], 1.0 op_sel_hi:[1,0]
	v_pk_add_f32 v[34:35], v[152:153], 1.0 op_sel_hi:[1,0]
	v_pk_mul_f32 v[28:29], v[28:29], v[30:31]
	v_pk_mul_f32 v[26:27], v[26:27], v[34:35]
	v_lshl_add_u64 v[30:31], v[20:21], 0, v[32:33]
	v_and_b32_sdwa v33, v28, v170 dst_sel:DWORD dst_unused:UNUSED_PAD src0_sel:WORD_1 src1_sel:DWORD
	v_and_b32_sdwa v34, v26, v170 dst_sel:DWORD dst_unused:UNUSED_PAD src0_sel:WORD_1 src1_sel:DWORD
	v_add3_u32 v26, v26, v34, s56
	v_add3_u32 v28, v28, v33, s56
	v_and_b32_sdwa v33, v29, v170 dst_sel:DWORD dst_unused:UNUSED_PAD src0_sel:WORD_1 src1_sel:DWORD
	v_and_b32_sdwa v34, v27, v170 dst_sel:DWORD dst_unused:UNUSED_PAD src0_sel:WORD_1 src1_sel:DWORD
	v_add3_u32 v29, v29, v33, s56
	v_add3_u32 v27, v27, v34, s56
	v_and_b32_e32 v29, 0xffff0000, v29
	v_and_b32_e32 v33, 0xffff0000, v27
	v_or_b32_sdwa v27, v29, v28 dst_sel:DWORD dst_unused:UNUSED_PAD src0_sel:DWORD src1_sel:WORD_1
	v_or_b32_sdwa v26, v33, v26 dst_sel:DWORD dst_unused:UNUSED_PAD src0_sel:DWORD src1_sel:WORD_1
	global_store_dwordx2 v[30:31], v[26:27], off
.LBB0_340:
	s_nop 0
	s_and_b64 vcc, exec, s[36:37]
	v_pk_fma_f32 v[10:11], v[10:11], v[74:75], v[212:213]
	v_pk_fma_f32 v[8:9], v[8:9], v[72:73], v[210:211]
	global_store_dwordx4 v[18:19], v[8:11], off offset:64
	s_cbranch_vccnz .LBB0_342
	v_lshl_add_u64 v[30:31], v[24:25], 0, v[128:129]
	v_mov_b32_e32 v33, v129
	v_pk_mul_f32 v[28:29], v[10:11], v[142:143]
	v_pk_mul_f32 v[26:27], v[8:9], v[140:141]
	v_pk_add_f32 v[30:31], v[158:159], 1.0 op_sel_hi:[1,0]
	v_pk_add_f32 v[34:35], v[156:157], 1.0 op_sel_hi:[1,0]
	v_pk_mul_f32 v[28:29], v[28:29], v[30:31]
	v_pk_mul_f32 v[26:27], v[26:27], v[34:35]
	v_lshl_add_u64 v[30:31], v[20:21], 0, v[32:33]
	v_and_b32_sdwa v33, v28, v170 dst_sel:DWORD dst_unused:UNUSED_PAD src0_sel:WORD_1 src1_sel:DWORD
	v_and_b32_sdwa v34, v26, v170 dst_sel:DWORD dst_unused:UNUSED_PAD src0_sel:WORD_1 src1_sel:DWORD
	v_add3_u32 v26, v26, v34, s56
	v_add3_u32 v28, v28, v33, s56
	v_and_b32_sdwa v33, v29, v170 dst_sel:DWORD dst_unused:UNUSED_PAD src0_sel:WORD_1 src1_sel:DWORD
	v_and_b32_sdwa v34, v27, v170 dst_sel:DWORD dst_unused:UNUSED_PAD src0_sel:WORD_1 src1_sel:DWORD
	v_add3_u32 v29, v29, v33, s56
	v_add3_u32 v27, v27, v34, s56
	v_and_b32_e32 v29, 0xffff0000, v29
	v_and_b32_e32 v33, 0xffff0000, v27
	v_or_b32_sdwa v27, v29, v28 dst_sel:DWORD dst_unused:UNUSED_PAD src0_sel:DWORD src1_sel:WORD_1
	v_or_b32_sdwa v26, v33, v26 dst_sel:DWORD dst_unused:UNUSED_PAD src0_sel:DWORD src1_sel:WORD_1
	global_store_dwordx2 v[30:31], v[26:27], off offset:32
.LBB0_342:
	s_nop 0
	s_and_b64 vcc, exec, s[36:37]
	v_pk_fma_f32 v[6:7], v[6:7], v[82:83], v[216:217]
	v_pk_fma_f32 v[4:5], v[4:5], v[80:81], v[214:215]
	global_store_dwordx4 v[18:19], v[4:7], off offset:128
	s_cbranch_vccnz .LBB0_344
	v_lshl_add_u64 v[30:31], v[24:25], 0, v[128:129]
	v_mov_b32_e32 v33, v129
	v_pk_mul_f32 v[28:29], v[6:7], v[146:147]
	v_pk_mul_f32 v[26:27], v[4:5], v[144:145]
	v_pk_add_f32 v[30:31], v[162:163], 1.0 op_sel_hi:[1,0]
	v_pk_add_f32 v[34:35], v[160:161], 1.0 op_sel_hi:[1,0]
	v_pk_mul_f32 v[28:29], v[28:29], v[30:31]
	v_pk_mul_f32 v[26:27], v[26:27], v[34:35]
	v_lshl_add_u64 v[30:31], v[20:21], 0, v[32:33]
	v_and_b32_sdwa v33, v28, v170 dst_sel:DWORD dst_unused:UNUSED_PAD src0_sel:WORD_1 src1_sel:DWORD
	v_and_b32_sdwa v34, v26, v170 dst_sel:DWORD dst_unused:UNUSED_PAD src0_sel:WORD_1 src1_sel:DWORD
	v_add3_u32 v26, v26, v34, s56
	v_add3_u32 v28, v28, v33, s56
	v_and_b32_sdwa v33, v29, v170 dst_sel:DWORD dst_unused:UNUSED_PAD src0_sel:WORD_1 src1_sel:DWORD
	v_and_b32_sdwa v34, v27, v170 dst_sel:DWORD dst_unused:UNUSED_PAD src0_sel:WORD_1 src1_sel:DWORD
	v_add3_u32 v29, v29, v33, s56
	v_add3_u32 v27, v27, v34, s56
	v_and_b32_e32 v29, 0xffff0000, v29
	v_and_b32_e32 v33, 0xffff0000, v27
	v_or_b32_sdwa v27, v29, v28 dst_sel:DWORD dst_unused:UNUSED_PAD src0_sel:DWORD src1_sel:WORD_1
	v_or_b32_sdwa v26, v33, v26 dst_sel:DWORD dst_unused:UNUSED_PAD src0_sel:DWORD src1_sel:WORD_1
	global_store_dwordx2 v[30:31], v[26:27], off offset:64
.LBB0_344:
	s_nop 0
	s_and_b64 vcc, exec, s[36:37]
	v_pk_fma_f32 v[2:3], v[2:3], v[90:91], v[220:221]
	v_pk_fma_f32 v[0:1], v[0:1], v[88:89], v[218:219]
	global_store_dwordx4 v[18:19], v[0:3], off offset:192
	s_cbranch_vccnz .LBB0_346
	v_lshl_add_u64 v[18:19], v[24:25], 0, v[128:129]
	v_mov_b32_e32 v33, v129
	v_lshl_add_u64 v[18:19], v[20:21], 0, v[32:33]
	v_pk_mul_f32 v[20:21], v[2:3], v[150:151]
	v_pk_mul_f32 v[26:27], v[0:1], v[148:149]
	v_pk_add_f32 v[24:25], v[182:183], 1.0 op_sel_hi:[1,0]
	v_pk_add_f32 v[22:23], v[180:181], 1.0 op_sel_hi:[1,0]
	v_pk_mul_f32 v[20:21], v[20:21], v[24:25]
	v_pk_mul_f32 v[22:23], v[26:27], v[22:23]
	v_and_b32_sdwa v26, v21, v170 dst_sel:DWORD dst_unused:UNUSED_PAD src0_sel:WORD_1 src1_sel:DWORD
	v_and_b32_sdwa v27, v23, v170 dst_sel:DWORD dst_unused:UNUSED_PAD src0_sel:WORD_1 src1_sel:DWORD
	v_and_b32_sdwa v24, v20, v170 dst_sel:DWORD dst_unused:UNUSED_PAD src0_sel:WORD_1 src1_sel:DWORD
	v_and_b32_sdwa v25, v22, v170 dst_sel:DWORD dst_unused:UNUSED_PAD src0_sel:WORD_1 src1_sel:DWORD
	v_add3_u32 v21, v21, v26, s56
	v_add3_u32 v23, v23, v27, s56
	v_add3_u32 v22, v22, v25, s56
	v_add3_u32 v20, v20, v24, s56
	v_and_b32_e32 v21, 0xffff0000, v21
	v_and_b32_e32 v23, 0xffff0000, v23
	v_or_b32_sdwa v21, v21, v20 dst_sel:DWORD dst_unused:UNUSED_PAD src0_sel:DWORD src1_sel:WORD_1
	v_or_b32_sdwa v20, v23, v22 dst_sel:DWORD dst_unused:UNUSED_PAD src0_sel:DWORD src1_sel:WORD_1
	global_store_dwordx2 v[18:19], v[20:21], off offset:96

.LBB0_392:
	s_add_i32 s0, s1, 2
	s_setprio 1
	v_add_u32_e32 v111, v104, v105
	ds_read_b128 v[136:139], v111 offset:16384
	ds_read_b128 v[140:143], v111 offset:18432
	ds_read_b128 v[144:147], v111 offset:20480
	ds_read_b128 v[148:151], v111 offset:22528
	v_add_u32_e32 v110, v103, v105
	ds_read_b128 v[116:119], v110
	s_add_i32 s1, s1, 4
	ds_read_b128 v[120:123], v110 offset:2048
	s_min_u32 s1, s1, 15
	v_add_u32_e32 v113, v104, v114
	s_lshl_b32 s92, s1, 7
	ds_read_b128 v[124:127], v110 offset:4096
	v_add_u32_e32 v112, v103, v114
	ds_read_b128 v[194:197], v113 offset:16384
	ds_read_b128 v[198:201], v113 offset:18432
	ds_read_b128 v[202:205], v113 offset:20480
	ds_read_b128 v[206:209], v113 offset:22528
	v_lshl_add_u64 v[164:165], v[98:99], 0, s[92:93]
	ds_read_b128 v[132:135], v110 offset:6144
	ds_read_b128 v[152:155], v112
	ds_read_b128 v[156:159], v112 offset:2048
	ds_read_b128 v[160:163], v112 offset:4096
	ds_read_b128 v[190:193], v112 offset:6144
	s_waitcnt lgkmcnt(11)
	v_mfma_f32_16x16x32_bf16 v[92:95], v[136:139], v[116:119], v[92:95]
	v_mfma_f32_16x16x32_bf16 v[88:91], v[140:143], v[116:119], v[88:91]
	v_mfma_f32_16x16x32_bf16 v[52:55], v[144:147], v[116:119], v[52:55]
	v_mfma_f32_16x16x32_bf16 v[48:51], v[148:151], v[116:119], v[48:51]
	global_load_dwordx4 v[116:119], v[164:165], off
	s_waitcnt vmcnt(6)
	ds_write_b128 v109, v[56:59] offset:32768
	v_add_co_u32_e32 v56, vcc, s11, v164
	s_waitcnt lgkmcnt(11)
	v_mfma_f32_16x16x32_bf16 v[44:47], v[136:139], v[120:123], v[44:47]
	v_addc_co_u32_e32 v57, vcc, 0, v165, vcc
	v_mfma_f32_16x16x32_bf16 v[40:43], v[140:143], v[120:123], v[40:43]
	v_mfma_f32_16x16x32_bf16 v[36:39], v[144:147], v[120:123], v[36:39]
	v_mfma_f32_16x16x32_bf16 v[32:35], v[148:151], v[120:123], v[32:35]
	global_load_dwordx4 v[120:123], v[56:57], off
	v_add_co_u32_e32 v56, vcc, s33, v164
	ds_write_b128 v109, v[60:63] offset:36864
	s_nop 0
	v_addc_co_u32_e32 v57, vcc, 0, v165, vcc
	s_waitcnt lgkmcnt(11)
	v_mfma_f32_16x16x32_bf16 v[28:31], v[136:139], v[124:127], v[28:31]
	v_mfma_f32_16x16x32_bf16 v[24:27], v[140:143], v[124:127], v[24:27]
	v_mfma_f32_16x16x32_bf16 v[20:23], v[144:147], v[124:127], v[20:23]
	v_mfma_f32_16x16x32_bf16 v[16:19], v[148:151], v[124:127], v[16:19]
	global_load_dwordx4 v[124:127], v[56:57], off
	v_add_co_u32_e32 v56, vcc, s59, v164
	ds_write_b128 v109, v[64:67] offset:40960
	s_nop 0
	v_addc_co_u32_e32 v57, vcc, 0, v165, vcc
	v_lshl_add_u64 v[64:65], v[100:101], 0, s[92:93]
	v_add_co_u32_e32 v66, vcc, s11, v64
	s_waitcnt lgkmcnt(7)
	v_mfma_f32_16x16x32_bf16 v[12:15], v[136:139], v[132:135], v[12:15]
	v_addc_co_u32_e32 v67, vcc, 0, v65, vcc
	v_mfma_f32_16x16x32_bf16 v[8:11], v[140:143], v[132:135], v[8:11]
	v_mfma_f32_16x16x32_bf16 v[4:7], v[144:147], v[132:135], v[4:7]
	v_mfma_f32_16x16x32_bf16 v[0:3], v[148:151], v[132:135], v[0:3]
	global_load_dwordx4 v[132:135], v[56:57], off
	s_waitcnt vmcnt(7)
	ds_write_b128 v109, v[72:75] offset:45056
	s_waitcnt lgkmcnt(7)
	v_mfma_f32_16x16x32_bf16 v[56:59], v[194:197], v[152:155], v[92:95]
	v_mfma_f32_16x16x32_bf16 v[60:63], v[198:201], v[152:155], v[88:91]
	v_mfma_f32_16x16x32_bf16 v[52:55], v[202:205], v[152:155], v[52:55]
	v_mfma_f32_16x16x32_bf16 v[48:51], v[206:209], v[152:155], v[48:51]
	global_load_dwordx4 v[136:139], v[64:65], off
	ds_write_b128 v109, v[68:71] offset:49152
	s_waitcnt lgkmcnt(7)
	v_mfma_f32_16x16x32_bf16 v[44:47], v[194:197], v[156:159], v[44:47]
	v_mfma_f32_16x16x32_bf16 v[40:43], v[198:201], v[156:159], v[40:43]
	v_mfma_f32_16x16x32_bf16 v[36:39], v[202:205], v[156:159], v[36:39]
	v_mfma_f32_16x16x32_bf16 v[32:35], v[206:209], v[156:159], v[32:35]
	global_load_dwordx4 v[140:143], v[66:67], off
	v_add_co_u32_e32 v66, vcc, s33, v64
	s_waitcnt vmcnt(8)
	ds_write_b128 v109, v[76:79] offset:53248
	v_addc_co_u32_e32 v67, vcc, 0, v65, vcc
	v_add_co_u32_e32 v64, vcc, s59, v64
	s_waitcnt lgkmcnt(7)
	v_mfma_f32_16x16x32_bf16 v[28:31], v[194:197], v[160:163], v[28:31]
	v_addc_co_u32_e32 v65, vcc, 0, v65, vcc
	v_mfma_f32_16x16x32_bf16 v[24:27], v[198:201], v[160:163], v[24:27]
	v_mfma_f32_16x16x32_bf16 v[20:23], v[202:205], v[160:163], v[20:23]
	v_mfma_f32_16x16x32_bf16 v[16:19], v[206:209], v[160:163], v[16:19]
	global_load_dwordx4 v[144:147], v[66:67], off
	s_waitcnt vmcnt(8)
	ds_write_b128 v109, v[80:83] offset:57344
	s_waitcnt lgkmcnt(7)
	v_mfma_f32_16x16x32_bf16 v[12:15], v[194:197], v[190:193], v[12:15]
	v_mfma_f32_16x16x32_bf16 v[8:11], v[198:201], v[190:193], v[8:11]
	v_mfma_f32_16x16x32_bf16 v[4:7], v[202:205], v[190:193], v[4:7]
	v_mfma_f32_16x16x32_bf16 v[0:3], v[206:209], v[190:193], v[0:3]
	global_load_dwordx4 v[148:151], v[64:65], off
	s_waitcnt vmcnt(8)
	ds_write_b128 v109, v[84:87] offset:61440
	s_setprio 0
	s_waitcnt lgkmcnt(0)
	s_barrier
	s_setprio 1
	ds_read_b128 v[84:87], v111 offset:51200
	ds_read_b128 v[80:83], v111 offset:49152
	ds_read_b128 v[88:91], v111 offset:53248
	ds_read_b128 v[92:95], v111 offset:55296
	ds_read_b128 v[64:67], v110 offset:32768
	s_min_u32 s1, s0, 12
	s_lshl_b32 s92, s1, 7
	ds_read_b128 v[68:71], v110 offset:34816
	v_lshl_add_u64 v[164:165], v[98:99], 0, s[92:93]
	ds_read_b128 v[72:75], v110 offset:36864
	ds_read_b128 v[76:79], v110 offset:38912
	ds_read_b128 v[152:155], v112 offset:32768
	ds_read_b128 v[156:159], v112 offset:34816
	ds_read_b128 v[160:163], v112 offset:36864
	ds_read_b128 v[190:193], v112 offset:38912
	ds_read_b128 v[194:197], v113 offset:49152
	ds_read_b128 v[198:201], v113 offset:51200
	ds_read_b128 v[202:205], v113 offset:53248
	ds_read_b128 v[206:209], v113 offset:55296
	s_waitcnt lgkmcnt(11)
	v_mfma_f32_16x16x32_bf16 v[214:217], v[84:87], v[64:67], v[60:63]
	v_mfma_f32_16x16x32_bf16 v[210:213], v[80:83], v[64:67], v[56:59]
	s_nop 1
	v_add_co_u32_e32 v60, vcc, s11, v164
	s_nop 1
	v_addc_co_u32_e32 v61, vcc, 0, v165, vcc
	v_mfma_f32_16x16x32_bf16 v[52:55], v[88:91], v[64:67], v[52:55]
	v_mfma_f32_16x16x32_bf16 v[48:51], v[92:95], v[64:67], v[48:51]
	v_add_co_u32_e32 v64, vcc, s33, v164
	global_load_dwordx4 v[56:59], v[164:165], off offset:384
	s_nop 0
	v_addc_co_u32_e32 v65, vcc, 0, v165, vcc
	s_waitcnt vmcnt(8)
	ds_write_b128 v109, v[116:119]
	s_waitcnt lgkmcnt(11)
	v_mfma_f32_16x16x32_bf16 v[44:47], v[80:83], v[68:71], v[44:47]
	v_mfma_f32_16x16x32_bf16 v[40:43], v[84:87], v[68:71], v[40:43]
	v_mfma_f32_16x16x32_bf16 v[36:39], v[88:91], v[68:71], v[36:39]
	v_mfma_f32_16x16x32_bf16 v[32:35], v[92:95], v[68:71], v[32:35]
	v_add_co_u32_e32 v68, vcc, s59, v164
	global_load_dwordx4 v[60:63], v[60:61], off offset:384
	s_waitcnt vmcnt(8)
	ds_write_b128 v109, v[120:123] offset:4096
	s_waitcnt lgkmcnt(11)
	v_mfma_f32_16x16x32_bf16 v[28:31], v[80:83], v[72:75], v[28:31]
	v_addc_co_u32_e32 v69, vcc, 0, v165, vcc
	v_mfma_f32_16x16x32_bf16 v[24:27], v[84:87], v[72:75], v[24:27]
	v_mfma_f32_16x16x32_bf16 v[20:23], v[88:91], v[72:75], v[20:23]
	v_mfma_f32_16x16x32_bf16 v[16:19], v[92:95], v[72:75], v[16:19]
	global_load_dwordx4 v[64:67], v[64:65], off offset:384
	s_waitcnt vmcnt(8)
	ds_write_b128 v109, v[124:127] offset:8192
	s_waitcnt lgkmcnt(11)
	v_mfma_f32_16x16x32_bf16 v[8:11], v[84:87], v[76:79], v[8:11]
	v_lshl_add_u64 v[84:85], v[100:101], 0, s[92:93]
	v_mfma_f32_16x16x32_bf16 v[12:15], v[80:83], v[76:79], v[12:15]
	v_mfma_f32_16x16x32_bf16 v[4:7], v[88:91], v[76:79], v[4:7]
	v_mfma_f32_16x16x32_bf16 v[0:3], v[92:95], v[76:79], v[0:3]
	v_add_co_u32_e32 v76, vcc, s11, v84
	global_load_dwordx4 v[72:75], v[68:69], off offset:384
	s_nop 0
	v_addc_co_u32_e32 v77, vcc, 0, v85, vcc
	v_add_co_u32_e32 v80, vcc, s33, v84
	s_waitcnt vmcnt(8)
	ds_write_b128 v109, v[132:135] offset:12288
	v_addc_co_u32_e32 v81, vcc, 0, v85, vcc
	s_waitcnt lgkmcnt(7)
	v_mfma_f32_16x16x32_bf16 v[92:95], v[194:197], v[152:155], v[210:213]
	s_waitcnt lgkmcnt(6)
	v_mfma_f32_16x16x32_bf16 v[88:91], v[198:201], v[152:155], v[214:217]
	s_waitcnt lgkmcnt(5)
	v_mfma_f32_16x16x32_bf16 v[52:55], v[202:205], v[152:155], v[52:55]
	s_waitcnt lgkmcnt(4)
	v_mfma_f32_16x16x32_bf16 v[48:51], v[206:209], v[152:155], v[48:51]
	global_load_dwordx4 v[68:71], v[84:85], off offset:384
	v_add_co_u32_e32 v84, vcc, s59, v84
	s_waitcnt vmcnt(8)
	ds_write_b128 v109, v[136:139] offset:16384
	v_addc_co_u32_e32 v85, vcc, 0, v85, vcc
	v_mfma_f32_16x16x32_bf16 v[44:47], v[194:197], v[156:159], v[44:47]
	v_mfma_f32_16x16x32_bf16 v[40:43], v[198:201], v[156:159], v[40:43]
	v_mfma_f32_16x16x32_bf16 v[36:39], v[202:205], v[156:159], v[36:39]
	v_mfma_f32_16x16x32_bf16 v[32:35], v[206:209], v[156:159], v[32:35]
	global_load_dwordx4 v[76:79], v[76:77], off offset:384
	s_waitcnt vmcnt(8)
	ds_write_b128 v109, v[140:143] offset:20480
	v_mfma_f32_16x16x32_bf16 v[28:31], v[194:197], v[160:163], v[28:31]
	v_mfma_f32_16x16x32_bf16 v[24:27], v[198:201], v[160:163], v[24:27]
	v_mfma_f32_16x16x32_bf16 v[20:23], v[202:205], v[160:163], v[20:23]
	v_mfma_f32_16x16x32_bf16 v[16:19], v[206:209], v[160:163], v[16:19]
	global_load_dwordx4 v[80:83], v[80:81], off offset:384
	s_waitcnt vmcnt(8)
	ds_write_b128 v109, v[144:147] offset:24576
	v_mfma_f32_16x16x32_bf16 v[12:15], v[194:197], v[190:193], v[12:15]
	v_mfma_f32_16x16x32_bf16 v[8:11], v[198:201], v[190:193], v[8:11]
	v_mfma_f32_16x16x32_bf16 v[4:7], v[202:205], v[190:193], v[4:7]
	v_mfma_f32_16x16x32_bf16 v[0:3], v[206:209], v[190:193], v[0:3]
	global_load_dwordx4 v[84:87], v[84:85], off offset:384
	s_waitcnt vmcnt(8)
	ds_write_b128 v109, v[148:151] offset:28672
	s_setprio 0
	s_cmp_lt_u32 s0, 14
	s_mov_b32 s1, s0
	s_waitcnt lgkmcnt(0)
	s_barrier
	s_cbranch_scc1 .LBB0_392
	s_mul_i32 s0, s69, 0x12000
	v_readlane_b32 s16, v250, 25
	s_add_u32 s24, s16, s0
	v_readlane_b32 s0, v251, 5
	v_lshlrev_b32_e32 v114, 6, v102
	v_readlane_b32 s17, v250, 26
	s_waitcnt vmcnt(5)
	v_add_u32_e32 v64, s0, v108
	v_readlane_b32 s0, v251, 6
	v_add_u32_e32 v56, 0xffffe000, v64
	v_or_b32_e32 v62, v64, v107
	v_or_b32_e32 v65, s0, v114
	v_lshrrev_b32_e32 v56, 10, v56
	s_movk_i32 s0, 0x1800
	v_mad_u32_u24 v56, v56, s0, s0
	v_cmp_lt_i32_e32 vcc, s13, v62
	s_addc_u32 s25, s17, 0
	v_lshlrev_b32_e32 v115, 2, v97
	v_cndmask_b32_e32 v56, 0, v56, vcc
	s_add_u32 s40, s24, 0x2000
	v_or_b32_e32 v58, v65, v115
	v_ashrrev_i32_e32 v57, 31, v56
	s_addc_u32 s41, s25, 0
	s_waitcnt vmcnt(4)
	v_lshlrev_b64 v[74:75], 2, v[56:57]
	v_ashrrev_i32_e32 v59, 31, v58
	v_ashrrev_i32_e32 v63, 31, v62
	v_lshl_add_u64 v[56:57], s[40:41], 0, v[74:75]
	v_lshlrev_b64 v[60:61], 2, v[58:59]
	v_readlane_b32 s0, v250, 15
	s_waitcnt vmcnt(1)
	v_lshl_add_u64 v[82:83], v[56:57], 0, v[60:61]
	v_lshlrev_b64 v[56:57], 12, v[62:63]
	v_readlane_b32 s1, v250, 16
	v_readlane_b32 s16, v250, 21
	v_lshlrev_b64 v[78:79], 11, v[62:63]
	v_lshl_add_u64 v[56:57], s[0:1], 0, v[56:57]
	s_waitcnt vmcnt(0)
	v_lshl_add_u64 v[84:85], v[56:57], 0, v[60:61]
	global_load_dwordx4 v[116:119], v[82:83], off
	global_load_dwordx4 v[120:123], v[82:83], off offset:64
	global_load_dwordx4 v[124:127], v[82:83], off offset:128
	global_load_dwordx4 v[132:135], v[82:83], off offset:192
	global_load_dwordx4 v[190:193], v[84:85], off
	global_load_dwordx4 v[194:197], v[84:85], off offset:64
	global_load_dwordx4 v[198:201], v[84:85], off offset:128
	global_load_dwordx4 v[202:205], v[84:85], off offset:192
	v_add_co_u32_e32 v164, vcc, 0x10000, v84
	s_nop 1
	v_addc_co_u32_e32 v165, vcc, 0, v85, vcc
	v_add_co_u32_e32 v222, vcc, 0x20000, v84
	s_nop 1
	v_addc_co_u32_e32 v223, vcc, 0, v85, vcc
	v_add_co_u32_e32 v224, vcc, 0x30000, v84
	s_nop 1
	v_addc_co_u32_e32 v225, vcc, 0, v85, vcc
	global_load_dwordx4 v[206:209], v[164:165], off
	global_load_dwordx4 v[210:213], v[164:165], off offset:64
	global_load_dwordx4 v[214:217], v[164:165], off offset:128
	global_load_dwordx4 v[218:221], v[164:165], off offset:192
	s_lshl_b32 s0, s69, 12
	v_readlane_b32 s68, v250, 41
	v_readlane_b32 s72, v250, 45
	v_readlane_b32 s73, v250, 46
	s_add_u32 s0, s72, s0
	s_addc_u32 s1, s73, 0
	s_add_u32 s42, s24, 0x4000
	s_addc_u32 s43, s25, 0
	v_lshl_add_u64 v[74:75], s[42:43], 0, v[74:75]
	v_lshl_add_u64 v[56:57], s[0:1], 0, v[60:61]
	v_lshl_add_u64 v[86:87], v[74:75], 0, v[60:61]
	v_readlane_b32 s17, v250, 22
	v_readlane_b32 s69, v250, 42
	v_readlane_b32 s69, v254, 49
	v_lshl_add_u64 v[78:79], s[16:17], 0, v[78:79]
	s_mul_i32 s24, s69, 0x140000
	s_add_u32 s24, s86, s24
	v_lshrrev_b32_e32 v65, 6, v65
	s_mov_b32 s16, 0xa000
	s_addc_u32 s25, s87, 0
	s_add_u32 s38, s24, 0xaf1a000
	s_addc_u32 s39, s25, 0
	v_cmp_eq_u32_e64 s[36:37], 0, v97
	v_readlane_b32 s70, v250, 43
	v_readlane_b32 s71, v250, 44
	v_readlane_b32 s74, v250, 47
	v_readlane_b32 s75, v250, 48
	v_readlane_b32 s76, v250, 49
	v_readlane_b32 s77, v250, 50
	v_readlane_b32 s78, v250, 51
	v_readlane_b32 s79, v250, 52
	v_readlane_b32 s80, v250, 53
	v_readlane_b32 s81, v250, 54
	v_readlane_b32 s82, v250, 55
	v_readlane_b32 s83, v250, 56
	s_waitcnt vmcnt(4)
	v_pk_fma_f32 v[68:69], v[94:95], v[118:119], v[192:193]
	v_pk_fma_f32 v[66:67], v[92:93], v[116:117], v[190:191]
	global_store_dwordx4 v[84:85], v[66:69], off
	global_load_dwordx4 v[136:139], v[56:57], off
	global_load_dwordx4 v[140:143], v[56:57], off offset:64
	global_load_dwordx4 v[144:147], v[56:57], off offset:128
	global_load_dwordx4 v[148:151], v[56:57], off offset:192
	global_load_dwordx4 v[152:155], v[86:87], off
	global_load_dwordx4 v[156:159], v[86:87], off offset:64
	global_load_dwordx4 v[160:163], v[86:87], off offset:128
	global_load_dwordx4 v[180:183], v[86:87], off offset:192
	v_lshl_add_u64 v[92:93], v[58:59], 1, v[78:79]
	s_waitcnt vmcnt(0)
	v_pk_mul_f32 v[72:73], v[68:69], v[138:139]
	v_pk_mul_f32 v[70:71], v[66:67], v[136:137]
	s_waitcnt vmcnt(0)
	v_pk_add_f32 v[76:77], v[154:155], 1.0 op_sel_hi:[1,0]
	v_pk_add_f32 v[74:75], v[152:153], 1.0 op_sel_hi:[1,0]
	v_pk_mul_f32 v[72:73], v[72:73], v[76:77]
	v_pk_mul_f32 v[70:71], v[70:71], v[74:75]
	v_and_b32_sdwa v76, v73, v170 dst_sel:DWORD dst_unused:UNUSED_PAD src0_sel:WORD_1 src1_sel:DWORD
	v_and_b32_sdwa v77, v71, v170 dst_sel:DWORD dst_unused:UNUSED_PAD src0_sel:WORD_1 src1_sel:DWORD
	v_and_b32_sdwa v74, v72, v170 dst_sel:DWORD dst_unused:UNUSED_PAD src0_sel:WORD_1 src1_sel:DWORD
	v_and_b32_sdwa v75, v70, v170 dst_sel:DWORD dst_unused:UNUSED_PAD src0_sel:WORD_1 src1_sel:DWORD
	v_add3_u32 v73, v73, v76, s56
	v_add3_u32 v71, v71, v77, s56
	v_add3_u32 v70, v70, v75, s56
	v_add3_u32 v72, v72, v74, s56
	v_and_b32_e32 v73, 0xffff0000, v73
	v_and_b32_e32 v74, 0xffff0000, v71
	v_or_b32_sdwa v71, v73, v72 dst_sel:DWORD dst_unused:UNUSED_PAD src0_sel:DWORD src1_sel:WORD_1
	v_or_b32_sdwa v70, v74, v70 dst_sel:DWORD dst_unused:UNUSED_PAD src0_sel:DWORD src1_sel:WORD_1
	global_store_dwordx2 v[92:93], v[70:71], off
	s_nop 0
	s_waitcnt vmcnt(0)
	v_pk_fma_f32 v[72:73], v[90:91], v[122:123], v[196:197]
	v_pk_fma_f32 v[70:71], v[88:89], v[120:121], v[194:195]
	global_store_dwordx4 v[84:85], v[70:73], off offset:64
	v_pk_mul_f32 v[76:77], v[72:73], v[142:143]
	v_pk_mul_f32 v[74:75], v[70:71], v[140:141]
	v_pk_add_f32 v[80:81], v[158:159], 1.0 op_sel_hi:[1,0]
	v_pk_add_f32 v[78:79], v[156:157], 1.0 op_sel_hi:[1,0]
	v_pk_mul_f32 v[76:77], v[76:77], v[80:81]
	v_pk_mul_f32 v[74:75], v[74:75], v[78:79]
	v_and_b32_sdwa v80, v77, v170 dst_sel:DWORD dst_unused:UNUSED_PAD src0_sel:WORD_1 src1_sel:DWORD
	v_and_b32_sdwa v81, v75, v170 dst_sel:DWORD dst_unused:UNUSED_PAD src0_sel:WORD_1 src1_sel:DWORD
	v_and_b32_sdwa v78, v76, v170 dst_sel:DWORD dst_unused:UNUSED_PAD src0_sel:WORD_1 src1_sel:DWORD
	v_and_b32_sdwa v79, v74, v170 dst_sel:DWORD dst_unused:UNUSED_PAD src0_sel:WORD_1 src1_sel:DWORD
	v_add3_u32 v77, v77, v80, s56
	v_add3_u32 v75, v75, v81, s56
	v_add3_u32 v74, v74, v79, s56
	v_add3_u32 v76, v76, v78, s56
	v_and_b32_e32 v77, 0xffff0000, v77
	v_and_b32_e32 v78, 0xffff0000, v75
	v_or_b32_sdwa v75, v77, v76 dst_sel:DWORD dst_unused:UNUSED_PAD src0_sel:DWORD src1_sel:WORD_1
	v_or_b32_sdwa v74, v78, v74 dst_sel:DWORD dst_unused:UNUSED_PAD src0_sel:DWORD src1_sel:WORD_1
	global_store_dwordx2 v[92:93], v[74:75], off offset:32
	s_nop 0
	v_pk_fma_f32 v[54:55], v[54:55], v[126:127], v[200:201]
	v_pk_fma_f32 v[52:53], v[52:53], v[124:125], v[198:199]
	global_store_dwordx4 v[84:85], v[52:55], off offset:128
	v_pk_mul_f32 v[76:77], v[54:55], v[146:147]
	v_pk_mul_f32 v[74:75], v[52:53], v[144:145]
	v_pk_add_f32 v[80:81], v[162:163], 1.0 op_sel_hi:[1,0]
	v_pk_add_f32 v[78:79], v[160:161], 1.0 op_sel_hi:[1,0]
	v_pk_mul_f32 v[76:77], v[76:77], v[80:81]
	v_pk_mul_f32 v[74:75], v[74:75], v[78:79]
	v_and_b32_sdwa v80, v77, v170 dst_sel:DWORD dst_unused:UNUSED_PAD src0_sel:WORD_1 src1_sel:DWORD
	v_and_b32_sdwa v81, v75, v170 dst_sel:DWORD dst_unused:UNUSED_PAD src0_sel:WORD_1 src1_sel:DWORD
	v_and_b32_sdwa v78, v76, v170 dst_sel:DWORD dst_unused:UNUSED_PAD src0_sel:WORD_1 src1_sel:DWORD
	v_and_b32_sdwa v79, v74, v170 dst_sel:DWORD dst_unused:UNUSED_PAD src0_sel:WORD_1 src1_sel:DWORD
	v_add3_u32 v77, v77, v80, s56
	v_add3_u32 v75, v75, v81, s56
	v_add3_u32 v74, v74, v79, s56
	v_add3_u32 v76, v76, v78, s56
	v_and_b32_e32 v77, 0xffff0000, v77
	v_and_b32_e32 v78, 0xffff0000, v75
	v_or_b32_sdwa v75, v77, v76 dst_sel:DWORD dst_unused:UNUSED_PAD src0_sel:DWORD src1_sel:WORD_1
	v_or_b32_sdwa v74, v78, v74 dst_sel:DWORD dst_unused:UNUSED_PAD src0_sel:DWORD src1_sel:WORD_1
	global_store_dwordx2 v[92:93], v[74:75], off offset:64
	s_nop 0
	v_pk_fma_f32 v[76:77], v[50:51], v[134:135], v[204:205]
	v_pk_fma_f32 v[74:75], v[48:49], v[132:133], v[202:203]
	global_store_dwordx4 v[84:85], v[74:77], off offset:192
	s_nop 0
	v_mbcnt_lo_u32_b32 v48, -1, 0
	v_mbcnt_hi_u32_b32 v48, -1, v48
	v_and_b32_e32 v50, 64, v48
	v_xor_b32_e32 v49, 16, v48
	v_add_u32_e32 v50, 64, v50
	v_xor_b32_e32 v51, 32, v48
	v_cmp_lt_i32_e32 vcc, v49, v50
	s_nop 1
	v_cndmask_b32_e32 v49, v48, v49, vcc
	v_cmp_lt_i32_e32 vcc, v51, v50
	v_lshlrev_b32_e32 v105, 2, v49
	s_nop 0
	v_cndmask_b32_e32 v50, v48, v51, vcc
	v_lshlrev_b32_e32 v104, 2, v50
	v_mul_f32_e32 v50, v67, v67
	v_mul_f32_e32 v51, v71, v71
	v_fmac_f32_e32 v50, v66, v66
	v_fmac_f32_e32 v51, v70, v70
	v_fmac_f32_e32 v50, v68, v68
	v_fmac_f32_e32 v51, v72, v72
	v_fmac_f32_e32 v50, v69, v69
	v_fmac_f32_e32 v51, v73, v73
	v_add_f32_e32 v50, v50, v51
	v_mul_f32_e32 v51, v53, v53
	v_fmac_f32_e32 v51, v52, v52
	v_fmac_f32_e32 v51, v54, v54
	v_fmac_f32_e32 v51, v55, v55
	v_add_f32_e32 v50, v50, v51
	v_mul_f32_e32 v51, v75, v75
	v_fmac_f32_e32 v51, v74, v74
	v_fmac_f32_e32 v51, v76, v76
	v_fmac_f32_e32 v51, v77, v77
	v_add_f32_e32 v50, v50, v51
	ds_bpermute_b32 v51, v105, v50
	v_mul_lo_u32 v48, v65, s16
	v_ashrrev_i32_e32 v49, 31, v48
	v_lshl_add_u64 v[48:49], s[38:39], 0, v[48:49]
	v_lshl_add_u64 v[48:49], v[62:63], 2, v[48:49]
	s_waitcnt lgkmcnt(0)
	v_add_f32_e32 v50, v50, v51
	ds_bpermute_b32 v51, v104, v50
	v_pk_mul_f32 v[52:53], v[76:77], v[150:151]
	v_pk_mul_f32 v[54:55], v[74:75], v[148:149]
	v_pk_add_f32 v[66:67], v[182:183], 1.0 op_sel_hi:[1,0]
	v_pk_add_f32 v[68:69], v[180:181], 1.0 op_sel_hi:[1,0]
	v_pk_mul_f32 v[52:53], v[52:53], v[66:67]
	v_pk_mul_f32 v[54:55], v[54:55], v[68:69]
	v_and_b32_sdwa v67, v53, v170 dst_sel:DWORD dst_unused:UNUSED_PAD src0_sel:WORD_1 src1_sel:DWORD
	v_and_b32_sdwa v68, v55, v170 dst_sel:DWORD dst_unused:UNUSED_PAD src0_sel:WORD_1 src1_sel:DWORD
	v_and_b32_sdwa v65, v52, v170 dst_sel:DWORD dst_unused:UNUSED_PAD src0_sel:WORD_1 src1_sel:DWORD
	v_and_b32_sdwa v66, v54, v170 dst_sel:DWORD dst_unused:UNUSED_PAD src0_sel:WORD_1 src1_sel:DWORD
	v_add3_u32 v53, v53, v67, s56
	v_add3_u32 v55, v55, v68, s56
	v_add3_u32 v54, v54, v66, s56
	v_add3_u32 v52, v52, v65, s56
	v_and_b32_e32 v53, 0xffff0000, v53
	v_and_b32_e32 v55, 0xffff0000, v55
	v_or_b32_sdwa v53, v53, v52 dst_sel:DWORD dst_unused:UNUSED_PAD src0_sel:DWORD src1_sel:WORD_1
	v_or_b32_sdwa v52, v55, v54 dst_sel:DWORD dst_unused:UNUSED_PAD src0_sel:DWORD src1_sel:WORD_1
	global_store_dwordx2 v[92:93], v[52:53], off offset:96
	s_and_saveexec_b64 s[24:25], s[36:37]
	s_cbranch_execz .LBB0_395
	s_waitcnt lgkmcnt(0)
	v_add_f32_e32 v50, v50, v51
	global_store_dword v[48:49], v50, off

.LBB0_397:
	s_or_b64 exec, exec, s[24:25]
	v_add_u32_e32 v32, 0xffffe020, v64
	v_or_b32_e32 v40, 32, v62
	v_lshrrev_b32_e32 v32, 10, v32
	v_mad_u32_u24 v32, v32, s5, s5
	v_cmp_lt_i32_e32 vcc, s13, v40
	v_ashrrev_i32_e32 v41, 31, v40
	v_readlane_b32 s16, v250, 15
	v_cndmask_b32_e32 v32, 0, v32, vcc
	s_waitcnt lgkmcnt(0)
	v_ashrrev_i32_e32 v33, 31, v32
	v_lshlrev_b64 v[42:43], 2, v[32:33]
	v_lshl_add_u64 v[32:33], s[40:41], 0, v[42:43]
	v_lshl_add_u64 v[44:45], v[32:33], 0, v[60:61]
	v_lshlrev_b64 v[32:33], 12, v[40:41]
	v_readlane_b32 s17, v250, 16
	v_lshl_add_u64 v[42:43], s[42:43], 0, v[42:43]
	v_lshl_add_u64 v[42:43], v[42:43], 0, v[60:61]
	v_lshl_add_u64 v[32:33], s[16:17], 0, v[32:33]
	v_lshl_add_u64 v[46:47], v[32:33], 0, v[60:61]
	v_readlane_b32 s16, v250, 21
	v_lshlrev_b64 v[40:41], 11, v[40:41]
	v_readlane_b32 s17, v250, 22
	global_load_dwordx4 v[206:209], v[224:225], off
	global_load_dwordx4 v[210:213], v[224:225], off offset:64
	global_load_dwordx4 v[214:217], v[224:225], off offset:128
	global_load_dwordx4 v[218:221], v[224:225], off offset:192
	s_waitcnt vmcnt(12)
	v_pk_fma_f32 v[30:31], v[30:31], v[118:119], v[192:193]
	v_pk_fma_f32 v[28:29], v[28:29], v[116:117], v[190:191]
	global_store_dwordx4 v[46:47], v[28:31], off
	v_lshl_add_u64 v[40:41], s[16:17], 0, v[40:41]
	v_lshl_add_u64 v[50:51], v[58:59], 1, v[40:41]
	v_pk_mul_f32 v[34:35], v[30:31], v[138:139]
	v_pk_mul_f32 v[32:33], v[28:29], v[136:137]
	v_pk_add_f32 v[38:39], v[154:155], 1.0 op_sel_hi:[1,0]
	v_pk_add_f32 v[36:37], v[152:153], 1.0 op_sel_hi:[1,0]
	v_pk_mul_f32 v[34:35], v[34:35], v[38:39]
	v_pk_mul_f32 v[32:33], v[32:33], v[36:37]
	v_and_b32_sdwa v38, v35, v170 dst_sel:DWORD dst_unused:UNUSED_PAD src0_sel:WORD_1 src1_sel:DWORD
	v_and_b32_sdwa v39, v33, v170 dst_sel:DWORD dst_unused:UNUSED_PAD src0_sel:WORD_1 src1_sel:DWORD
	v_and_b32_sdwa v36, v34, v170 dst_sel:DWORD dst_unused:UNUSED_PAD src0_sel:WORD_1 src1_sel:DWORD
	v_and_b32_sdwa v37, v32, v170 dst_sel:DWORD dst_unused:UNUSED_PAD src0_sel:WORD_1 src1_sel:DWORD
	v_add3_u32 v35, v35, v38, s56
	v_add3_u32 v33, v33, v39, s56
	v_add3_u32 v32, v32, v37, s56
	v_add3_u32 v34, v34, v36, s56
	v_and_b32_e32 v35, 0xffff0000, v35
	v_and_b32_e32 v36, 0xffff0000, v33
	v_or_b32_sdwa v33, v35, v34 dst_sel:DWORD dst_unused:UNUSED_PAD src0_sel:DWORD src1_sel:WORD_1
	v_or_b32_sdwa v32, v36, v32 dst_sel:DWORD dst_unused:UNUSED_PAD src0_sel:DWORD src1_sel:WORD_1
	global_store_dwordx2 v[50:51], v[32:33], off
	s_nop 0
	v_pk_fma_f32 v[26:27], v[26:27], v[122:123], v[196:197]
	v_pk_fma_f32 v[24:25], v[24:25], v[120:121], v[194:195]
	global_store_dwordx4 v[46:47], v[24:27], off offset:64
	v_pk_mul_f32 v[34:35], v[26:27], v[142:143]
	v_pk_mul_f32 v[32:33], v[24:25], v[140:141]
	v_pk_add_f32 v[38:39], v[158:159], 1.0 op_sel_hi:[1,0]
	v_pk_add_f32 v[36:37], v[156:157], 1.0 op_sel_hi:[1,0]
	v_pk_mul_f32 v[34:35], v[34:35], v[38:39]
	v_pk_mul_f32 v[32:33], v[32:33], v[36:37]
	v_and_b32_sdwa v38, v35, v170 dst_sel:DWORD dst_unused:UNUSED_PAD src0_sel:WORD_1 src1_sel:DWORD
	v_and_b32_sdwa v39, v33, v170 dst_sel:DWORD dst_unused:UNUSED_PAD src0_sel:WORD_1 src1_sel:DWORD
	v_and_b32_sdwa v36, v34, v170 dst_sel:DWORD dst_unused:UNUSED_PAD src0_sel:WORD_1 src1_sel:DWORD
	v_and_b32_sdwa v37, v32, v170 dst_sel:DWORD dst_unused:UNUSED_PAD src0_sel:WORD_1 src1_sel:DWORD
	v_add3_u32 v35, v35, v38, s56
	v_add3_u32 v33, v33, v39, s56
	v_add3_u32 v32, v32, v37, s56
	v_add3_u32 v34, v34, v36, s56
	v_and_b32_e32 v35, 0xffff0000, v35
	v_and_b32_e32 v36, 0xffff0000, v33
	v_or_b32_sdwa v33, v35, v34 dst_sel:DWORD dst_unused:UNUSED_PAD src0_sel:DWORD src1_sel:WORD_1
	v_or_b32_sdwa v32, v36, v32 dst_sel:DWORD dst_unused:UNUSED_PAD src0_sel:DWORD src1_sel:WORD_1
	global_store_dwordx2 v[50:51], v[32:33], off offset:32
	s_nop 0
	v_pk_fma_f32 v[22:23], v[22:23], v[126:127], v[200:201]
	v_pk_fma_f32 v[20:21], v[20:21], v[124:125], v[198:199]
	global_store_dwordx4 v[46:47], v[20:23], off offset:128
	v_pk_mul_f32 v[34:35], v[22:23], v[146:147]
	v_pk_mul_f32 v[32:33], v[20:21], v[144:145]
	v_pk_add_f32 v[38:39], v[162:163], 1.0 op_sel_hi:[1,0]
	v_pk_add_f32 v[36:37], v[160:161], 1.0 op_sel_hi:[1,0]
	v_pk_mul_f32 v[34:35], v[34:35], v[38:39]
	v_pk_mul_f32 v[32:33], v[32:33], v[36:37]
	v_and_b32_sdwa v38, v35, v170 dst_sel:DWORD dst_unused:UNUSED_PAD src0_sel:WORD_1 src1_sel:DWORD
	v_and_b32_sdwa v39, v33, v170 dst_sel:DWORD dst_unused:UNUSED_PAD src0_sel:WORD_1 src1_sel:DWORD
	v_and_b32_sdwa v36, v34, v170 dst_sel:DWORD dst_unused:UNUSED_PAD src0_sel:WORD_1 src1_sel:DWORD
	v_and_b32_sdwa v37, v32, v170 dst_sel:DWORD dst_unused:UNUSED_PAD src0_sel:WORD_1 src1_sel:DWORD
	v_add3_u32 v35, v35, v38, s56
	v_add3_u32 v33, v33, v39, s56
	v_add3_u32 v32, v32, v37, s56
	v_add3_u32 v34, v34, v36, s56
	v_and_b32_e32 v35, 0xffff0000, v35
	v_and_b32_e32 v36, 0xffff0000, v33
	v_or_b32_sdwa v33, v35, v34 dst_sel:DWORD dst_unused:UNUSED_PAD src0_sel:DWORD src1_sel:WORD_1
	v_or_b32_sdwa v32, v36, v32 dst_sel:DWORD dst_unused:UNUSED_PAD src0_sel:DWORD src1_sel:WORD_1
	global_store_dwordx2 v[50:51], v[32:33], off offset:64
	s_nop 0
	v_pk_fma_f32 v[34:35], v[18:19], v[134:135], v[204:205]
	v_pk_fma_f32 v[32:33], v[16:17], v[132:133], v[202:203]
	global_store_dwordx4 v[46:47], v[32:35], off offset:192
	s_nop 0
	v_mul_f32_e32 v16, v29, v29
	v_mul_f32_e32 v17, v25, v25
	v_fmac_f32_e32 v16, v28, v28
	v_fmac_f32_e32 v17, v24, v24
	v_fmac_f32_e32 v16, v30, v30
	v_fmac_f32_e32 v17, v26, v26
	v_fmac_f32_e32 v16, v31, v31
	v_fmac_f32_e32 v17, v27, v27
	v_add_f32_e32 v16, v16, v17
	v_mul_f32_e32 v17, v21, v21
	v_fmac_f32_e32 v17, v20, v20
	v_fmac_f32_e32 v17, v22, v22
	v_fmac_f32_e32 v17, v23, v23
	v_add_f32_e32 v16, v16, v17
	v_mul_f32_e32 v17, v33, v33
	v_fmac_f32_e32 v17, v32, v32
	v_fmac_f32_e32 v17, v34, v34
	v_fmac_f32_e32 v17, v35, v35
	v_add_f32_e32 v16, v16, v17
	ds_bpermute_b32 v17, v105, v16
	s_waitcnt lgkmcnt(0)
	v_add_f32_e32 v16, v16, v17
	ds_bpermute_b32 v17, v104, v16
	v_pk_mul_f32 v[18:19], v[34:35], v[150:151]
	v_pk_mul_f32 v[20:21], v[32:33], v[148:149]
	v_pk_add_f32 v[22:23], v[182:183], 1.0 op_sel_hi:[1,0]
	v_pk_add_f32 v[24:25], v[180:181], 1.0 op_sel_hi:[1,0]
	v_pk_mul_f32 v[18:19], v[18:19], v[22:23]
	v_pk_mul_f32 v[20:21], v[20:21], v[24:25]
	v_and_b32_sdwa v24, v19, v170 dst_sel:DWORD dst_unused:UNUSED_PAD src0_sel:WORD_1 src1_sel:DWORD
	v_and_b32_sdwa v25, v21, v170 dst_sel:DWORD dst_unused:UNUSED_PAD src0_sel:WORD_1 src1_sel:DWORD
	v_and_b32_sdwa v22, v18, v170 dst_sel:DWORD dst_unused:UNUSED_PAD src0_sel:WORD_1 src1_sel:DWORD
	v_and_b32_sdwa v23, v20, v170 dst_sel:DWORD dst_unused:UNUSED_PAD src0_sel:WORD_1 src1_sel:DWORD
	v_add3_u32 v19, v19, v24, s56
	v_add3_u32 v21, v21, v25, s56
	v_add3_u32 v20, v20, v23, s56
	v_add3_u32 v18, v18, v22, s56
	v_and_b32_e32 v19, 0xffff0000, v19
	v_and_b32_e32 v21, 0xffff0000, v21
	v_or_b32_sdwa v19, v19, v18 dst_sel:DWORD dst_unused:UNUSED_PAD src0_sel:DWORD src1_sel:WORD_1
	v_or_b32_sdwa v18, v21, v20 dst_sel:DWORD dst_unused:UNUSED_PAD src0_sel:DWORD src1_sel:WORD_1
	global_store_dwordx2 v[50:51], v[18:19], off offset:96
	s_and_saveexec_b64 s[24:25], s[36:37]
	s_movk_i32 s8, 0x400
	s_mov_b32 s5, 0xffff0000
	s_mov_b32 s9, 0x12000
	s_movk_i32 s89, 0xff
	s_cbranch_execz .LBB0_399
	s_waitcnt lgkmcnt(0)
	v_add_f32_e32 v16, v16, v17
	global_store_dword v[48:49], v16, off offset:128

.LBB0_419:
	s_add_i32 s2, s3, 2
	s_setprio 1
	v_add_u32_e32 v127, v89, v90
	ds_read_b128 v[100:103], v127 offset:16384
	ds_read_b128 v[106:109], v127 offset:18432
	ds_read_b128 v[110:113], v127 offset:20480
	ds_read_b128 v[114:117], v127 offset:22528
	v_add_u32_e32 v126, v88, v90
	ds_read_b128 v[92:95], v126
	ds_read_b128 v[96:99], v126 offset:2048
	s_add_i32 s3, s3, 4
	s_min_u32 s3, s3, 15
	v_add_u32_e32 v128, v88, v91
	v_add_u32_e32 v130, v89, v91
	s_lshl_b32 s92, s3, 7
	ds_read_b128 v[118:121], v130 offset:18432
	ds_read_b128 v[122:125], v130 offset:20480
	ds_read_b128 v[132:135], v130 offset:22528
	s_waitcnt lgkmcnt(4)
	v_mfma_f32_16x16x32_bf16 v[76:79], v[100:103], v[92:95], v[76:79]
	v_lshl_add_u64 v[44:45], v[80:81], 0, s[92:93]
	v_add_co_u32_e32 v46, vcc, s11, v44
	v_mfma_f32_16x16x32_bf16 v[68:71], v[106:109], v[92:95], v[68:71]
	s_nop 0
	v_addc_co_u32_e32 v47, vcc, 0, v45, vcc
	v_mfma_f32_16x16x32_bf16 v[52:55], v[110:113], v[92:95], v[52:55]
	v_mfma_f32_16x16x32_bf16 v[40:43], v[114:117], v[92:95], v[40:43]
	s_waitcnt lgkmcnt(3)
	v_mfma_f32_16x16x32_bf16 v[92:95], v[100:103], v[96:99], v[36:39]
	s_nop 2
	ds_read_b128 v[36:39], v128
	v_mfma_f32_16x16x32_bf16 v[100:103], v[106:109], v[96:99], v[8:11]
	v_mfma_f32_16x16x32_bf16 v[106:109], v[110:113], v[96:99], v[4:7]
	ds_read_b128 v[110:113], v128 offset:2048
	v_mfma_f32_16x16x32_bf16 v[96:99], v[114:117], v[96:99], v[0:3]
	ds_read_b128 v[114:117], v130 offset:16384
	global_load_dwordx4 v[72:75], v[44:45], off
	s_waitcnt vmcnt(1)
	ds_write_b128 v87, v[12:15] offset:53248
	global_load_dwordx4 v[64:67], v[46:47], off
	v_add_co_u32_e32 v46, vcc, s33, v44
	ds_write_b128 v87, v[16:19] offset:49152
	s_nop 0
	v_addc_co_u32_e32 v47, vcc, 0, v45, vcc
	v_add_co_u32_e32 v44, vcc, s59, v44
	global_load_dwordx4 v[60:63], v[46:47], off
	s_nop 0
	v_addc_co_u32_e32 v45, vcc, 0, v45, vcc
	ds_write_b128 v87, v[20:23] offset:45056
	global_load_dwordx4 v[56:59], v[44:45], off
	v_lshl_add_u64 v[44:45], v[82:83], 0, s[92:93]
	ds_write_b128 v87, v[28:31] offset:32768
	s_waitcnt lgkmcnt(4)
	v_mfma_f32_16x16x32_bf16 v[0:3], v[114:117], v[36:39], v[76:79]
	v_mfma_f32_16x16x32_bf16 v[4:7], v[118:121], v[36:39], v[68:71]
	global_load_dwordx4 v[48:51], v[44:45], off
	v_add_co_u32_e32 v44, vcc, s11, v44
	ds_write_b128 v87, v[32:35] offset:36864
	s_nop 0
	v_addc_co_u32_e32 v45, vcc, 0, v45, vcc
	v_mfma_f32_16x16x32_bf16 v[8:11], v[122:125], v[36:39], v[52:55]
	v_mfma_f32_16x16x32_bf16 v[36:39], v[132:135], v[36:39], v[40:43]
	global_load_dwordx4 v[44:47], v[44:45], off
	ds_write_b128 v87, v[24:27] offset:40960
	v_mfma_f32_16x16x32_bf16 v[40:43], v[114:117], v[110:113], v[92:95]
	v_mfma_f32_16x16x32_bf16 v[52:55], v[118:121], v[110:113], v[100:103]
	v_mfma_f32_16x16x32_bf16 v[68:71], v[122:125], v[110:113], v[106:109]
	v_mfma_f32_16x16x32_bf16 v[76:79], v[132:135], v[110:113], v[96:99]
	s_setprio 0
	s_waitcnt lgkmcnt(0)
	s_barrier
	s_setprio 1
	ds_read_b128 v[100:103], v127 offset:49152
	ds_read_b128 v[106:109], v127 offset:51200
	ds_read_b128 v[110:113], v127 offset:53248
	ds_read_b128 v[114:117], v127 offset:55296
	ds_read_b128 v[92:95], v126 offset:32768
	ds_read_b128 v[96:99], v126 offset:34816
	s_min_u32 s3, s2, 12
	s_lshl_b32 s92, s3, 7
	ds_read_b128 v[118:121], v130 offset:51200
	ds_read_b128 v[122:125], v130 offset:53248
	ds_read_b128 v[132:135], v130 offset:55296
	s_waitcnt lgkmcnt(4)
	v_mfma_f32_16x16x32_bf16 v[0:3], v[100:103], v[92:95], v[0:3]
	v_lshl_add_u64 v[12:13], v[80:81], 0, s[92:93]
	v_add_co_u32_e32 v14, vcc, s11, v12
	v_mfma_f32_16x16x32_bf16 v[4:7], v[106:109], v[92:95], v[4:7]
	s_nop 0
	v_addc_co_u32_e32 v15, vcc, 0, v13, vcc
	v_mfma_f32_16x16x32_bf16 v[8:11], v[110:113], v[92:95], v[8:11]
	v_mfma_f32_16x16x32_bf16 v[36:39], v[114:117], v[92:95], v[36:39]
	s_waitcnt lgkmcnt(3)
	v_mfma_f32_16x16x32_bf16 v[92:95], v[100:103], v[96:99], v[40:43]
	s_nop 2
	ds_read_b128 v[40:43], v128 offset:32768
	v_mfma_f32_16x16x32_bf16 v[100:103], v[106:109], v[96:99], v[52:55]
	v_mfma_f32_16x16x32_bf16 v[106:109], v[110:113], v[96:99], v[68:71]
	ds_read_b128 v[110:113], v128 offset:34816
	v_mfma_f32_16x16x32_bf16 v[96:99], v[114:117], v[96:99], v[76:79]
	ds_read_b128 v[114:117], v130 offset:49152
	global_load_dwordx4 v[28:31], v[12:13], off offset:384
	s_waitcnt vmcnt(1)
	ds_write_b128 v87, v[44:47] offset:20480
	global_load_dwordx4 v[32:35], v[14:15], off offset:384
	v_add_co_u32_e32 v14, vcc, s33, v12
	ds_write_b128 v87, v[48:51] offset:16384
	s_nop 0
	v_addc_co_u32_e32 v15, vcc, 0, v13, vcc
	v_add_co_u32_e32 v12, vcc, s59, v12
	global_load_dwordx4 v[24:27], v[14:15], off offset:384
	s_nop 0
	v_addc_co_u32_e32 v13, vcc, 0, v13, vcc
	ds_write_b128 v87, v[56:59] offset:12288
	global_load_dwordx4 v[20:23], v[12:13], off offset:384
	v_lshl_add_u64 v[12:13], v[82:83], 0, s[92:93]
	ds_write_b128 v87, v[72:75]
	s_waitcnt lgkmcnt(4)
	v_mfma_f32_16x16x32_bf16 v[76:79], v[114:117], v[40:43], v[0:3]
	v_mfma_f32_16x16x32_bf16 v[68:71], v[118:121], v[40:43], v[4:7]
	global_load_dwordx4 v[16:19], v[12:13], off offset:384
	v_add_co_u32_e32 v12, vcc, s11, v12
	ds_write_b128 v87, v[64:67] offset:4096
	s_nop 0
	v_addc_co_u32_e32 v13, vcc, 0, v13, vcc
	v_mfma_f32_16x16x32_bf16 v[52:55], v[122:125], v[40:43], v[8:11]
	v_mfma_f32_16x16x32_bf16 v[40:43], v[132:135], v[40:43], v[36:39]
	global_load_dwordx4 v[12:15], v[12:13], off offset:384
	ds_write_b128 v87, v[60:63] offset:8192
	v_mfma_f32_16x16x32_bf16 v[36:39], v[114:117], v[110:113], v[92:95]
	v_mfma_f32_16x16x32_bf16 v[8:11], v[118:121], v[110:113], v[100:103]
	v_mfma_f32_16x16x32_bf16 v[4:7], v[122:125], v[110:113], v[106:109]
	v_mfma_f32_16x16x32_bf16 v[0:3], v[132:135], v[110:113], v[96:99]
	s_setprio 0
	s_cmp_lt_u32 s2, 14
	s_mov_b32 s3, s2
	s_waitcnt lgkmcnt(0)
	s_barrier
	s_cbranch_scc1 .LBB0_419
	v_readlane_b32 s2, v251, 18
	s_waitcnt vmcnt(1)
	s_nop 0
	v_add_u32_e32 v18, s2, v86
	v_readlane_b32 s2, v251, 19
	s_waitcnt vmcnt(0)
	v_add_u32_e32 v13, 0xffffe000, v18
	v_or_b32_e32 v12, v18, v85
	v_lshl_or_b32 v19, v84, 2, s2
	v_lshrrev_b32_e32 v13, 10, v13
	s_movk_i32 s2, 0x1800
	v_mad_u32_u24 v13, v13, s2, s2
	v_cmp_lt_i32_e32 vcc, s13, v12
	v_lshlrev_b32_e32 v128, 2, v19
	v_readlane_b32 s2, v250, 15
	v_cndmask_b32_e32 v14, 0, v13, vcc
	v_ashrrev_i32_e32 v15, 31, v14
	v_lshlrev_b64 v[24:25], 2, v[14:15]
	v_ashrrev_i32_e32 v13, 31, v12
	v_lshl_add_u64 v[14:15], s[40:41], 0, v[24:25]
	v_lshl_add_u64 v[48:49], v[14:15], 0, v[128:129]
	v_lshlrev_b64 v[14:15], 12, v[12:13]
	v_readlane_b32 s3, v250, 16
	v_lshl_add_u64 v[28:29], s[42:43], 0, v[24:25]
	v_lshlrev_b64 v[32:33], 11, v[12:13]
	v_lshl_add_u64 v[14:15], s[2:3], 0, v[14:15]
	v_lshl_add_u64 v[50:51], v[14:15], 0, v[128:129]
	global_load_dwordx4 v[72:75], v[48:49], off
	global_load_dwordx4 v[80:83], v[48:49], off offset:64
	global_load_dwordx4 v[88:91], v[48:49], off offset:128
	global_load_dwordx4 v[136:139], v[48:49], off offset:192
	global_load_dwordx4 v[194:197], v[50:51], off
	global_load_dwordx4 v[198:201], v[50:51], off offset:64
	global_load_dwordx4 v[202:205], v[50:51], off offset:128
	global_load_dwordx4 v[206:209], v[50:51], off offset:192
	v_add_co_u32_e32 v58, vcc, 0x10000, v50
	s_nop 1
	v_addc_co_u32_e32 v59, vcc, 0, v51, vcc
	global_load_dwordx4 v[210:213], v[58:59], off
	global_load_dwordx4 v[214:217], v[58:59], off offset:64
	global_load_dwordx4 v[218:221], v[58:59], off offset:128
	global_load_dwordx4 v[222:225], v[58:59], off offset:192
	v_readlane_b32 s2, v250, 21
	v_readlane_b32 s3, v250, 22
	v_cmp_eq_u32_e32 vcc, 0, v84
	s_waitcnt vmcnt(4)
	v_pk_fma_f32 v[22:23], v[78:79], v[74:75], v[196:197]
	v_pk_fma_f32 v[20:21], v[76:77], v[72:73], v[194:195]
	global_store_dwordx4 v[50:51], v[20:23], off
	v_lshl_add_u64 v[14:15], v[28:29], 0, v[128:129]
	global_load_dwordx4 v[140:143], v128, s[0:1]
	global_load_dwordx4 v[144:147], v128, s[0:1] offset:64
	global_load_dwordx4 v[148:151], v128, s[0:1] offset:128
	global_load_dwordx4 v[152:155], v128, s[0:1] offset:192
	global_load_dwordx4 v[156:159], v[14:15], off
	global_load_dwordx4 v[160:163], v[14:15], off offset:64
	global_load_dwordx4 v[180:183], v[14:15], off offset:128
	global_load_dwordx4 v[190:193], v[14:15], off offset:192
	v_lshlrev_b32_e32 v16, 1, v19
	v_mov_b32_e32 v17, v129
	v_lshl_add_u64 v[32:33], s[2:3], 0, v[32:33]
	v_lshl_add_u64 v[56:57], v[32:33], 0, v[16:17]
	s_waitcnt vmcnt(0)
	v_pk_mul_f32 v[26:27], v[22:23], v[142:143]
	v_pk_mul_f32 v[24:25], v[20:21], v[140:141]
	s_waitcnt vmcnt(0)
	v_pk_add_f32 v[30:31], v[158:159], 1.0 op_sel_hi:[1,0]
	v_pk_add_f32 v[28:29], v[156:157], 1.0 op_sel_hi:[1,0]
	v_pk_mul_f32 v[26:27], v[26:27], v[30:31]
	v_pk_mul_f32 v[24:25], v[24:25], v[28:29]
	v_and_b32_sdwa v19, v26, v170 dst_sel:DWORD dst_unused:UNUSED_PAD src0_sel:WORD_1 src1_sel:DWORD
	v_and_b32_sdwa v29, v27, v170 dst_sel:DWORD dst_unused:UNUSED_PAD src0_sel:WORD_1 src1_sel:DWORD
	v_and_b32_sdwa v30, v25, v170 dst_sel:DWORD dst_unused:UNUSED_PAD src0_sel:WORD_1 src1_sel:DWORD
	v_and_b32_sdwa v28, v24, v170 dst_sel:DWORD dst_unused:UNUSED_PAD src0_sel:WORD_1 src1_sel:DWORD
	v_add3_u32 v19, v26, v19, s56
	v_add3_u32 v26, v27, v29, s56
	v_add3_u32 v25, v25, v30, s56
	v_add3_u32 v24, v24, v28, s56
	v_and_b32_e32 v26, 0xffff0000, v26
	v_and_b32_e32 v27, 0xffff0000, v25
	v_or_b32_sdwa v25, v26, v19 dst_sel:DWORD dst_unused:UNUSED_PAD src0_sel:DWORD src1_sel:WORD_1
	v_or_b32_sdwa v24, v27, v24 dst_sel:DWORD dst_unused:UNUSED_PAD src0_sel:DWORD src1_sel:WORD_1
	global_store_dwordx2 v[56:57], v[24:25], off
	s_nop 0
	s_waitcnt vmcnt(0)
	v_pk_fma_f32 v[26:27], v[70:71], v[82:83], v[200:201]
	v_pk_fma_f32 v[24:25], v[68:69], v[80:81], v[198:199]
	global_store_dwordx4 v[50:51], v[24:27], off offset:64
	v_pk_mul_f32 v[30:31], v[26:27], v[146:147]
	v_pk_mul_f32 v[28:29], v[24:25], v[144:145]
	v_pk_add_f32 v[34:35], v[162:163], 1.0 op_sel_hi:[1,0]
	v_pk_add_f32 v[32:33], v[160:161], 1.0 op_sel_hi:[1,0]
	v_pk_mul_f32 v[30:31], v[30:31], v[34:35]
	v_pk_mul_f32 v[28:29], v[28:29], v[32:33]
	v_and_b32_sdwa v19, v30, v170 dst_sel:DWORD dst_unused:UNUSED_PAD src0_sel:WORD_1 src1_sel:DWORD
	v_and_b32_sdwa v33, v31, v170 dst_sel:DWORD dst_unused:UNUSED_PAD src0_sel:WORD_1 src1_sel:DWORD
	v_and_b32_sdwa v34, v29, v170 dst_sel:DWORD dst_unused:UNUSED_PAD src0_sel:WORD_1 src1_sel:DWORD
	v_and_b32_sdwa v32, v28, v170 dst_sel:DWORD dst_unused:UNUSED_PAD src0_sel:WORD_1 src1_sel:DWORD
	v_add3_u32 v19, v30, v19, s56
	v_add3_u32 v30, v31, v33, s56
	v_add3_u32 v29, v29, v34, s56
	v_add3_u32 v28, v28, v32, s56
	v_and_b32_e32 v30, 0xffff0000, v30
	v_and_b32_e32 v31, 0xffff0000, v29
	v_or_b32_sdwa v29, v30, v19 dst_sel:DWORD dst_unused:UNUSED_PAD src0_sel:DWORD src1_sel:WORD_1
	v_or_b32_sdwa v28, v31, v28 dst_sel:DWORD dst_unused:UNUSED_PAD src0_sel:DWORD src1_sel:WORD_1
	global_store_dwordx2 v[56:57], v[28:29], off offset:32
	s_nop 0
	v_pk_fma_f32 v[30:31], v[54:55], v[90:91], v[204:205]
	v_pk_fma_f32 v[28:29], v[52:53], v[88:89], v[202:203]
	global_store_dwordx4 v[50:51], v[28:31], off offset:128
	v_pk_mul_f32 v[34:35], v[30:31], v[150:151]
	v_pk_mul_f32 v[32:33], v[28:29], v[148:149]
	v_pk_add_f32 v[46:47], v[182:183], 1.0 op_sel_hi:[1,0]
	v_pk_add_f32 v[44:45], v[180:181], 1.0 op_sel_hi:[1,0]
	v_pk_mul_f32 v[34:35], v[34:35], v[46:47]
	v_pk_mul_f32 v[32:33], v[32:33], v[44:45]
	v_and_b32_sdwa v19, v34, v170 dst_sel:DWORD dst_unused:UNUSED_PAD src0_sel:WORD_1 src1_sel:DWORD
	v_and_b32_sdwa v45, v35, v170 dst_sel:DWORD dst_unused:UNUSED_PAD src0_sel:WORD_1 src1_sel:DWORD
	v_and_b32_sdwa v46, v33, v170 dst_sel:DWORD dst_unused:UNUSED_PAD src0_sel:WORD_1 src1_sel:DWORD
	v_and_b32_sdwa v44, v32, v170 dst_sel:DWORD dst_unused:UNUSED_PAD src0_sel:WORD_1 src1_sel:DWORD
	v_add3_u32 v19, v34, v19, s56
	v_add3_u32 v34, v35, v45, s56
	v_add3_u32 v33, v33, v46, s56
	v_add3_u32 v32, v32, v44, s56
	v_and_b32_e32 v34, 0xffff0000, v34
	v_and_b32_e32 v35, 0xffff0000, v33
	v_or_b32_sdwa v33, v34, v19 dst_sel:DWORD dst_unused:UNUSED_PAD src0_sel:DWORD src1_sel:WORD_1
	v_or_b32_sdwa v32, v35, v32 dst_sel:DWORD dst_unused:UNUSED_PAD src0_sel:DWORD src1_sel:WORD_1
	global_store_dwordx2 v[56:57], v[32:33], off offset:64
	s_nop 0
	v_pk_fma_f32 v[34:35], v[42:43], v[138:139], v[208:209]
	v_pk_fma_f32 v[32:33], v[40:41], v[136:137], v[206:207]
	global_store_dwordx4 v[50:51], v[32:35], off offset:192
	v_mul_f32_e32 v14, v21, v21
	v_mul_f32_e32 v15, v25, v25
	v_fmac_f32_e32 v14, v20, v20
	v_fmac_f32_e32 v15, v24, v24
	v_fmac_f32_e32 v14, v22, v22
	v_fmac_f32_e32 v15, v26, v26
	v_fmac_f32_e32 v14, v23, v23
	v_fmac_f32_e32 v15, v27, v27
	v_add_f32_e32 v14, v14, v15
	v_mul_f32_e32 v15, v29, v29
	v_fmac_f32_e32 v15, v28, v28
	v_fmac_f32_e32 v15, v30, v30
	v_fmac_f32_e32 v15, v31, v31
	v_add_f32_e32 v14, v14, v15
	v_mul_f32_e32 v15, v33, v33
	v_fmac_f32_e32 v15, v32, v32
	v_fmac_f32_e32 v15, v34, v34
	v_fmac_f32_e32 v15, v35, v35
	v_add_f32_e32 v14, v14, v15
	ds_bpermute_b32 v15, v105, v14
	s_waitcnt lgkmcnt(0)
	v_add_f32_e32 v14, v14, v15
	ds_bpermute_b32 v15, v104, v14
	v_pk_mul_f32 v[20:21], v[34:35], v[154:155]
	v_pk_mul_f32 v[22:23], v[32:33], v[152:153]
	v_pk_add_f32 v[24:25], v[192:193], 1.0 op_sel_hi:[1,0]
	v_pk_add_f32 v[26:27], v[190:191], 1.0 op_sel_hi:[1,0]
	v_pk_mul_f32 v[20:21], v[20:21], v[24:25]
	v_pk_mul_f32 v[22:23], v[22:23], v[26:27]
	v_and_b32_sdwa v19, v20, v170 dst_sel:DWORD dst_unused:UNUSED_PAD src0_sel:WORD_1 src1_sel:DWORD
	v_and_b32_sdwa v25, v21, v170 dst_sel:DWORD dst_unused:UNUSED_PAD src0_sel:WORD_1 src1_sel:DWORD
	v_and_b32_sdwa v26, v23, v170 dst_sel:DWORD dst_unused:UNUSED_PAD src0_sel:WORD_1 src1_sel:DWORD
	v_and_b32_sdwa v24, v22, v170 dst_sel:DWORD dst_unused:UNUSED_PAD src0_sel:WORD_1 src1_sel:DWORD
	v_add3_u32 v19, v20, v19, s56
	v_add3_u32 v20, v21, v25, s56
	v_add3_u32 v21, v23, v26, s56
	v_add3_u32 v22, v22, v24, s56
	v_and_b32_e32 v20, 0xffff0000, v20
	v_and_b32_e32 v23, 0xffff0000, v21
	v_or_b32_sdwa v21, v20, v19 dst_sel:DWORD dst_unused:UNUSED_PAD src0_sel:DWORD src1_sel:WORD_1
	v_or_b32_sdwa v20, v23, v22 dst_sel:DWORD dst_unused:UNUSED_PAD src0_sel:DWORD src1_sel:WORD_1
	global_store_dwordx2 v[56:57], v[20:21], off offset:96
	s_and_saveexec_b64 s[2:3], vcc
	s_cbranch_execz .LBB0_422
	v_readlane_b32 s16, v253, 20
	s_add_u32 s24, s38, s16
	s_addc_u32 s25, s39, 0
	v_lshl_add_u64 v[20:21], v[12:13], 2, s[24:25]
	s_waitcnt lgkmcnt(0)
	v_add_f32_e32 v13, v14, v15
	global_store_dword v[20:21], v13, off
.LBB0_422:
	s_or_b64 exec, exec, s[2:3]
	v_add_u32_e32 v13, 0xffffe010, v18
	s_waitcnt lgkmcnt(0)
	v_lshl_add_u64 v[14:15], s[0:1], 0, v[128:129]
	v_or_b32_e32 v12, 16, v12
	v_lshrrev_b32_e32 v13, 10, v13
	s_movk_i32 s0, 0x1800
	v_mad_u32_u24 v13, v13, s0, s0
	v_cmp_lt_i32_e64 s[0:1], s13, v12
	s_nop 1
	v_cndmask_b32_e64 v18, 0, v13, s[0:1]
	v_ashrrev_i32_e32 v19, 31, v18
	v_lshlrev_b64 v[34:35], 2, v[18:19]
	v_ashrrev_i32_e32 v13, 31, v12
	v_lshl_add_u64 v[18:19], s[40:41], 0, v[34:35]
	v_readlane_b32 s0, v250, 15
	v_lshl_add_u64 v[20:21], v[18:19], 0, v[128:129]
	v_lshlrev_b64 v[18:19], 12, v[12:13]
	v_readlane_b32 s1, v250, 16
	s_nop 0
	v_lshl_add_u64 v[18:19], s[0:1], 0, v[18:19]
	v_lshl_add_u64 v[18:19], v[18:19], 0, v[128:129]
	v_readlane_b32 s0, v250, 21
	v_readlane_b32 s1, v250, 22
	s_waitcnt vmcnt(16)
	v_pk_fma_f32 v[28:29], v[38:39], v[74:75], v[212:213]
	v_pk_fma_f32 v[26:27], v[36:37], v[72:73], v[210:211]
	v_lshl_add_u64 v[22:23], s[42:43], 0, v[34:35]
	global_store_dwordx4 v[18:19], v[26:29], off
	v_lshl_add_u64 v[22:23], v[22:23], 0, v[128:129]
	v_mul_f32_e32 v38, v27, v27
	v_fmac_f32_e32 v38, v26, v26
	v_fmac_f32_e32 v38, v28, v28
	v_fmac_f32_e32 v38, v29, v29
	v_pk_mul_f32 v[24:25], v[28:29], v[142:143]
	v_pk_add_f32 v[28:29], v[158:159], 1.0 op_sel_hi:[1,0]
	v_pk_mul_f32 v[26:27], v[26:27], v[140:141]
	v_pk_add_f32 v[30:31], v[156:157], 1.0 op_sel_hi:[1,0]
	v_pk_mul_f32 v[24:25], v[24:25], v[28:29]
	v_lshlrev_b64 v[28:29], 11, v[12:13]
	v_pk_mul_f32 v[26:27], v[26:27], v[30:31]
	v_lshl_add_u64 v[28:29], s[0:1], 0, v[28:29]
	v_lshl_add_u64 v[16:17], v[28:29], 0, v[16:17]
	v_and_b32_sdwa v28, v24, v170 dst_sel:DWORD dst_unused:UNUSED_PAD src0_sel:WORD_1 src1_sel:DWORD
	v_and_b32_sdwa v29, v26, v170 dst_sel:DWORD dst_unused:UNUSED_PAD src0_sel:WORD_1 src1_sel:DWORD
	v_add3_u32 v26, v26, v29, s56
	v_add3_u32 v24, v24, v28, s56
	v_and_b32_sdwa v28, v25, v170 dst_sel:DWORD dst_unused:UNUSED_PAD src0_sel:WORD_1 src1_sel:DWORD
	v_and_b32_sdwa v29, v27, v170 dst_sel:DWORD dst_unused:UNUSED_PAD src0_sel:WORD_1 src1_sel:DWORD
	v_add3_u32 v25, v25, v28, s56
	v_add3_u32 v27, v27, v29, s56
	v_and_b32_e32 v25, 0xffff0000, v25
	v_and_b32_e32 v27, 0xffff0000, v27
	v_or_b32_sdwa v25, v25, v24 dst_sel:DWORD dst_unused:UNUSED_PAD src0_sel:DWORD src1_sel:WORD_1
	v_or_b32_sdwa v24, v27, v26 dst_sel:DWORD dst_unused:UNUSED_PAD src0_sel:DWORD src1_sel:WORD_1
	global_store_dwordx2 v[16:17], v[24:25], off
	s_nop 0
	v_pk_fma_f32 v[8:9], v[8:9], v[80:81], v[214:215]
	s_nop 0
	v_mul_f32_e32 v24, v9, v9
	v_pk_fma_f32 v[10:11], v[10:11], v[82:83], v[216:217]
	v_fmac_f32_e32 v24, v8, v8
	v_fmac_f32_e32 v24, v10, v10
	global_store_dwordx4 v[18:19], v[8:11], off offset:64
	v_fmac_f32_e32 v24, v11, v11
	v_add_f32_e32 v32, v38, v24
	v_pk_mul_f32 v[10:11], v[10:11], v[146:147]
	v_pk_mul_f32 v[8:9], v[8:9], v[144:145]
	v_pk_add_f32 v[24:25], v[162:163], 1.0 op_sel_hi:[1,0]
	v_pk_add_f32 v[26:27], v[160:161], 1.0 op_sel_hi:[1,0]
	v_pk_mul_f32 v[10:11], v[10:11], v[24:25]
	v_pk_mul_f32 v[8:9], v[8:9], v[26:27]
	v_and_b32_sdwa v24, v10, v170 dst_sel:DWORD dst_unused:UNUSED_PAD src0_sel:WORD_1 src1_sel:DWORD
	v_and_b32_sdwa v25, v8, v170 dst_sel:DWORD dst_unused:UNUSED_PAD src0_sel:WORD_1 src1_sel:DWORD
	v_add3_u32 v8, v8, v25, s56
	v_add3_u32 v10, v10, v24, s56
	v_and_b32_sdwa v24, v11, v170 dst_sel:DWORD dst_unused:UNUSED_PAD src0_sel:WORD_1 src1_sel:DWORD
	v_and_b32_sdwa v25, v9, v170 dst_sel:DWORD dst_unused:UNUSED_PAD src0_sel:WORD_1 src1_sel:DWORD
	v_add3_u32 v11, v11, v24, s56
	v_add3_u32 v9, v9, v25, s56
	v_and_b32_e32 v11, 0xffff0000, v11
	v_and_b32_e32 v24, 0xffff0000, v9
	v_or_b32_sdwa v9, v11, v10 dst_sel:DWORD dst_unused:UNUSED_PAD src0_sel:DWORD src1_sel:WORD_1
	v_or_b32_sdwa v8, v24, v8 dst_sel:DWORD dst_unused:UNUSED_PAD src0_sel:DWORD src1_sel:WORD_1
	global_store_dwordx2 v[16:17], v[8:9], off offset:32
	s_nop 0
	v_pk_fma_f32 v[4:5], v[4:5], v[88:89], v[218:219]
	s_nop 0
	v_mul_f32_e32 v8, v5, v5
	v_pk_fma_f32 v[6:7], v[6:7], v[90:91], v[220:221]
	v_fmac_f32_e32 v8, v4, v4
	v_fmac_f32_e32 v8, v6, v6
	global_store_dwordx4 v[18:19], v[4:7], off offset:128
	v_fmac_f32_e32 v8, v7, v7
	v_add_f32_e32 v28, v32, v8
	v_pk_mul_f32 v[6:7], v[6:7], v[150:151]
	v_pk_mul_f32 v[4:5], v[4:5], v[148:149]
	v_pk_add_f32 v[8:9], v[182:183], 1.0 op_sel_hi:[1,0]
	v_pk_add_f32 v[10:11], v[180:181], 1.0 op_sel_hi:[1,0]
	v_pk_mul_f32 v[6:7], v[6:7], v[8:9]
	v_pk_mul_f32 v[4:5], v[4:5], v[10:11]
	v_and_b32_sdwa v8, v6, v170 dst_sel:DWORD dst_unused:UNUSED_PAD src0_sel:WORD_1 src1_sel:DWORD
	v_and_b32_sdwa v9, v4, v170 dst_sel:DWORD dst_unused:UNUSED_PAD src0_sel:WORD_1 src1_sel:DWORD
	v_add3_u32 v4, v4, v9, s56
	v_add3_u32 v6, v6, v8, s56
	v_and_b32_sdwa v8, v7, v170 dst_sel:DWORD dst_unused:UNUSED_PAD src0_sel:WORD_1 src1_sel:DWORD
	v_and_b32_sdwa v9, v5, v170 dst_sel:DWORD dst_unused:UNUSED_PAD src0_sel:WORD_1 src1_sel:DWORD
	v_add3_u32 v7, v7, v8, s56
	v_add3_u32 v5, v5, v9, s56
	v_and_b32_e32 v7, 0xffff0000, v7
	v_and_b32_e32 v8, 0xffff0000, v5
	v_or_b32_sdwa v5, v7, v6 dst_sel:DWORD dst_unused:UNUSED_PAD src0_sel:DWORD src1_sel:WORD_1
	v_or_b32_sdwa v4, v8, v4 dst_sel:DWORD dst_unused:UNUSED_PAD src0_sel:DWORD src1_sel:WORD_1
	global_store_dwordx2 v[16:17], v[4:5], off offset:64
	s_nop 0
	v_pk_fma_f32 v[0:1], v[0:1], v[136:137], v[222:223]
	s_nop 0
	v_mul_f32_e32 v4, v1, v1
	v_pk_fma_f32 v[2:3], v[2:3], v[138:139], v[224:225]
	v_fmac_f32_e32 v4, v0, v0
	v_fmac_f32_e32 v4, v2, v2
	global_store_dwordx4 v[18:19], v[0:3], off offset:192
	v_fmac_f32_e32 v4, v3, v3
	v_add_f32_e32 v18, v28, v4
	v_pk_mul_f32 v[2:3], v[2:3], v[154:155]
	v_pk_mul_f32 v[0:1], v[0:1], v[152:153]
	v_pk_add_f32 v[4:5], v[192:193], 1.0 op_sel_hi:[1,0]
	v_pk_add_f32 v[6:7], v[190:191], 1.0 op_sel_hi:[1,0]
	v_pk_mul_f32 v[2:3], v[2:3], v[4:5]
	v_pk_mul_f32 v[0:1], v[0:1], v[6:7]
	v_and_b32_sdwa v4, v2, v170 dst_sel:DWORD dst_unused:UNUSED_PAD src0_sel:WORD_1 src1_sel:DWORD
	v_and_b32_sdwa v5, v0, v170 dst_sel:DWORD dst_unused:UNUSED_PAD src0_sel:WORD_1 src1_sel:DWORD
	v_add3_u32 v0, v0, v5, s56
	v_add3_u32 v2, v2, v4, s56
	v_and_b32_sdwa v4, v3, v170 dst_sel:DWORD dst_unused:UNUSED_PAD src0_sel:WORD_1 src1_sel:DWORD
	v_and_b32_sdwa v5, v1, v170 dst_sel:DWORD dst_unused:UNUSED_PAD src0_sel:WORD_1 src1_sel:DWORD
	v_add3_u32 v3, v3, v4, s56
	v_add3_u32 v1, v1, v5, s56
	v_and_b32_e32 v3, 0xffff0000, v3
	v_and_b32_e32 v4, 0xffff0000, v1
	v_or_b32_sdwa v1, v3, v2 dst_sel:DWORD dst_unused:UNUSED_PAD src0_sel:DWORD src1_sel:WORD_1
	v_or_b32_sdwa v0, v4, v0 dst_sel:DWORD dst_unused:UNUSED_PAD src0_sel:DWORD src1_sel:WORD_1
	global_store_dwordx2 v[16:17], v[0:1], off offset:96
	ds_bpermute_b32 v0, v105, v18
	s_waitcnt lgkmcnt(0)
	v_add_f32_e32 v0, v18, v0
	ds_bpermute_b32 v1, v104, v0
	s_and_saveexec_b64 s[0:1], vcc
	s_movk_i32 s89, 0xff
	s_cbranch_execz .LBB0_424
	v_readlane_b32 s2, v253, 20
	s_add_u32 s2, s38, s2
	s_addc_u32 s3, s39, 0
	v_lshl_add_u64 v[2:3], v[12:13], 2, s[2:3]
	s_waitcnt lgkmcnt(0)
	v_add_f32_e32 v0, v0, v1
	global_store_dword v[2:3], v0, off

.LBB0_582:
	s_add_i32 s0, s1, 2
	s_setprio 1
	v_add_u32_e32 v111, v104, v105
	ds_read_b128 v[136:139], v111 offset:16384
	ds_read_b128 v[140:143], v111 offset:18432
	ds_read_b128 v[144:147], v111 offset:20480
	ds_read_b128 v[148:151], v111 offset:22528
	v_add_u32_e32 v110, v103, v105
	ds_read_b128 v[116:119], v110
	s_add_i32 s1, s1, 4
	ds_read_b128 v[120:123], v110 offset:2048
	s_min_u32 s1, s1, 63
	v_add_u32_e32 v113, v104, v114
	s_lshl_b32 s92, s1, 7
	ds_read_b128 v[124:127], v110 offset:4096
	v_add_u32_e32 v112, v103, v114
	ds_read_b128 v[194:197], v113 offset:16384
	ds_read_b128 v[198:201], v113 offset:18432
	ds_read_b128 v[202:205], v113 offset:20480
	ds_read_b128 v[206:209], v113 offset:22528
	v_lshl_add_u64 v[164:165], v[98:99], 0, s[92:93]
	ds_read_b128 v[132:135], v110 offset:6144
	ds_read_b128 v[152:155], v112
	ds_read_b128 v[156:159], v112 offset:2048
	ds_read_b128 v[160:163], v112 offset:4096
	ds_read_b128 v[190:193], v112 offset:6144
	s_waitcnt lgkmcnt(11)
	v_mfma_f32_16x16x32_bf16 v[92:95], v[136:139], v[116:119], v[92:95]
	v_mfma_f32_16x16x32_bf16 v[88:91], v[140:143], v[116:119], v[88:91]
	v_mfma_f32_16x16x32_bf16 v[52:55], v[144:147], v[116:119], v[52:55]
	v_mfma_f32_16x16x32_bf16 v[48:51], v[148:151], v[116:119], v[48:51]
	global_load_dwordx4 v[116:119], v[164:165], off
	s_waitcnt vmcnt(6)
	ds_write_b128 v109, v[56:59] offset:32768
	v_add_co_u32_e32 v56, vcc, s7, v164
	s_waitcnt lgkmcnt(11)
	v_mfma_f32_16x16x32_bf16 v[44:47], v[136:139], v[120:123], v[44:47]
	v_addc_co_u32_e32 v57, vcc, 0, v165, vcc
	v_mfma_f32_16x16x32_bf16 v[40:43], v[140:143], v[120:123], v[40:43]
	v_mfma_f32_16x16x32_bf16 v[36:39], v[144:147], v[120:123], v[36:39]
	v_mfma_f32_16x16x32_bf16 v[32:35], v[148:151], v[120:123], v[32:35]
	global_load_dwordx4 v[120:123], v[56:57], off
	v_add_co_u32_e32 v56, vcc, s52, v164
	ds_write_b128 v109, v[60:63] offset:36864
	s_nop 0
	v_addc_co_u32_e32 v57, vcc, 0, v165, vcc
	s_waitcnt lgkmcnt(11)
	v_mfma_f32_16x16x32_bf16 v[28:31], v[136:139], v[124:127], v[28:31]
	v_mfma_f32_16x16x32_bf16 v[24:27], v[140:143], v[124:127], v[24:27]
	v_mfma_f32_16x16x32_bf16 v[20:23], v[144:147], v[124:127], v[20:23]
	v_mfma_f32_16x16x32_bf16 v[16:19], v[148:151], v[124:127], v[16:19]
	global_load_dwordx4 v[124:127], v[56:57], off
	v_add_co_u32_e32 v56, vcc, s34, v164
	ds_write_b128 v109, v[64:67] offset:40960
	s_nop 0
	v_addc_co_u32_e32 v57, vcc, 0, v165, vcc
	v_lshl_add_u64 v[64:65], v[100:101], 0, s[92:93]
	v_add_co_u32_e32 v66, vcc, s7, v64
	s_waitcnt lgkmcnt(7)
	v_mfma_f32_16x16x32_bf16 v[12:15], v[136:139], v[132:135], v[12:15]
	v_addc_co_u32_e32 v67, vcc, 0, v65, vcc
	v_mfma_f32_16x16x32_bf16 v[8:11], v[140:143], v[132:135], v[8:11]
	v_mfma_f32_16x16x32_bf16 v[4:7], v[144:147], v[132:135], v[4:7]
	v_mfma_f32_16x16x32_bf16 v[0:3], v[148:151], v[132:135], v[0:3]
	global_load_dwordx4 v[132:135], v[56:57], off
	s_waitcnt vmcnt(7)
	ds_write_b128 v109, v[72:75] offset:45056
	s_waitcnt lgkmcnt(7)
	v_mfma_f32_16x16x32_bf16 v[56:59], v[194:197], v[152:155], v[92:95]
	v_mfma_f32_16x16x32_bf16 v[60:63], v[198:201], v[152:155], v[88:91]
	v_mfma_f32_16x16x32_bf16 v[52:55], v[202:205], v[152:155], v[52:55]
	v_mfma_f32_16x16x32_bf16 v[48:51], v[206:209], v[152:155], v[48:51]
	global_load_dwordx4 v[136:139], v[64:65], off
	ds_write_b128 v109, v[68:71] offset:49152
	s_waitcnt lgkmcnt(7)
	v_mfma_f32_16x16x32_bf16 v[44:47], v[194:197], v[156:159], v[44:47]
	v_mfma_f32_16x16x32_bf16 v[40:43], v[198:201], v[156:159], v[40:43]
	v_mfma_f32_16x16x32_bf16 v[36:39], v[202:205], v[156:159], v[36:39]
	v_mfma_f32_16x16x32_bf16 v[32:35], v[206:209], v[156:159], v[32:35]
	global_load_dwordx4 v[140:143], v[66:67], off
	v_add_co_u32_e32 v66, vcc, s52, v64
	s_waitcnt vmcnt(8)
	ds_write_b128 v109, v[76:79] offset:53248
	v_addc_co_u32_e32 v67, vcc, 0, v65, vcc
	v_add_co_u32_e32 v64, vcc, s34, v64
	s_waitcnt lgkmcnt(7)
	v_mfma_f32_16x16x32_bf16 v[28:31], v[194:197], v[160:163], v[28:31]
	v_addc_co_u32_e32 v65, vcc, 0, v65, vcc
	v_mfma_f32_16x16x32_bf16 v[24:27], v[198:201], v[160:163], v[24:27]
	v_mfma_f32_16x16x32_bf16 v[20:23], v[202:205], v[160:163], v[20:23]
	v_mfma_f32_16x16x32_bf16 v[16:19], v[206:209], v[160:163], v[16:19]
	global_load_dwordx4 v[144:147], v[66:67], off
	s_waitcnt vmcnt(8)
	ds_write_b128 v109, v[80:83] offset:57344
	s_waitcnt lgkmcnt(7)
	v_mfma_f32_16x16x32_bf16 v[12:15], v[194:197], v[190:193], v[12:15]
	v_mfma_f32_16x16x32_bf16 v[8:11], v[198:201], v[190:193], v[8:11]
	v_mfma_f32_16x16x32_bf16 v[4:7], v[202:205], v[190:193], v[4:7]
	v_mfma_f32_16x16x32_bf16 v[0:3], v[206:209], v[190:193], v[0:3]
	global_load_dwordx4 v[148:151], v[64:65], off
	s_waitcnt vmcnt(8)
	ds_write_b128 v109, v[84:87] offset:61440
	s_setprio 0
	s_waitcnt lgkmcnt(0)
	s_barrier
	s_setprio 1
	ds_read_b128 v[84:87], v111 offset:51200
	ds_read_b128 v[80:83], v111 offset:49152
	ds_read_b128 v[88:91], v111 offset:53248
	ds_read_b128 v[92:95], v111 offset:55296
	ds_read_b128 v[64:67], v110 offset:32768
	s_min_u32 s1, s0, 60
	s_lshl_b32 s92, s1, 7
	ds_read_b128 v[68:71], v110 offset:34816
	v_lshl_add_u64 v[164:165], v[98:99], 0, s[92:93]
	ds_read_b128 v[72:75], v110 offset:36864
	ds_read_b128 v[76:79], v110 offset:38912
	ds_read_b128 v[152:155], v112 offset:32768
	ds_read_b128 v[156:159], v112 offset:34816
	ds_read_b128 v[160:163], v112 offset:36864
	ds_read_b128 v[190:193], v112 offset:38912
	ds_read_b128 v[194:197], v113 offset:49152
	ds_read_b128 v[198:201], v113 offset:51200
	ds_read_b128 v[202:205], v113 offset:53248
	ds_read_b128 v[206:209], v113 offset:55296
	s_waitcnt lgkmcnt(11)
	v_mfma_f32_16x16x32_bf16 v[214:217], v[84:87], v[64:67], v[60:63]
	v_mfma_f32_16x16x32_bf16 v[210:213], v[80:83], v[64:67], v[56:59]
	s_nop 1
	v_add_co_u32_e32 v60, vcc, s7, v164
	s_nop 1
	v_addc_co_u32_e32 v61, vcc, 0, v165, vcc
	v_mfma_f32_16x16x32_bf16 v[52:55], v[88:91], v[64:67], v[52:55]
	v_mfma_f32_16x16x32_bf16 v[48:51], v[92:95], v[64:67], v[48:51]
	v_add_co_u32_e32 v64, vcc, s52, v164
	global_load_dwordx4 v[56:59], v[164:165], off offset:384
	s_nop 0
	v_addc_co_u32_e32 v65, vcc, 0, v165, vcc
	s_waitcnt vmcnt(8)
	ds_write_b128 v109, v[116:119]
	s_waitcnt lgkmcnt(11)
	v_mfma_f32_16x16x32_bf16 v[44:47], v[80:83], v[68:71], v[44:47]
	v_mfma_f32_16x16x32_bf16 v[40:43], v[84:87], v[68:71], v[40:43]
	v_mfma_f32_16x16x32_bf16 v[36:39], v[88:91], v[68:71], v[36:39]
	v_mfma_f32_16x16x32_bf16 v[32:35], v[92:95], v[68:71], v[32:35]
	v_add_co_u32_e32 v68, vcc, s34, v164
	global_load_dwordx4 v[60:63], v[60:61], off offset:384
	s_waitcnt vmcnt(8)
	ds_write_b128 v109, v[120:123] offset:4096
	s_waitcnt lgkmcnt(11)
	v_mfma_f32_16x16x32_bf16 v[28:31], v[80:83], v[72:75], v[28:31]
	v_addc_co_u32_e32 v69, vcc, 0, v165, vcc
	v_mfma_f32_16x16x32_bf16 v[24:27], v[84:87], v[72:75], v[24:27]
	v_mfma_f32_16x16x32_bf16 v[20:23], v[88:91], v[72:75], v[20:23]
	v_mfma_f32_16x16x32_bf16 v[16:19], v[92:95], v[72:75], v[16:19]
	global_load_dwordx4 v[64:67], v[64:65], off offset:384
	s_waitcnt vmcnt(8)
	ds_write_b128 v109, v[124:127] offset:8192
	s_waitcnt lgkmcnt(11)
	v_mfma_f32_16x16x32_bf16 v[8:11], v[84:87], v[76:79], v[8:11]
	v_lshl_add_u64 v[84:85], v[100:101], 0, s[92:93]
	v_mfma_f32_16x16x32_bf16 v[12:15], v[80:83], v[76:79], v[12:15]
	v_mfma_f32_16x16x32_bf16 v[4:7], v[88:91], v[76:79], v[4:7]
	v_mfma_f32_16x16x32_bf16 v[0:3], v[92:95], v[76:79], v[0:3]
	v_add_co_u32_e32 v76, vcc, s7, v84
	global_load_dwordx4 v[72:75], v[68:69], off offset:384
	s_nop 0
	v_addc_co_u32_e32 v77, vcc, 0, v85, vcc
	v_add_co_u32_e32 v80, vcc, s52, v84
	s_waitcnt vmcnt(8)
	ds_write_b128 v109, v[132:135] offset:12288
	v_addc_co_u32_e32 v81, vcc, 0, v85, vcc
	s_waitcnt lgkmcnt(7)
	v_mfma_f32_16x16x32_bf16 v[92:95], v[194:197], v[152:155], v[210:213]
	s_waitcnt lgkmcnt(6)
	v_mfma_f32_16x16x32_bf16 v[88:91], v[198:201], v[152:155], v[214:217]
	s_waitcnt lgkmcnt(5)
	v_mfma_f32_16x16x32_bf16 v[52:55], v[202:205], v[152:155], v[52:55]
	s_waitcnt lgkmcnt(4)
	v_mfma_f32_16x16x32_bf16 v[48:51], v[206:209], v[152:155], v[48:51]
	global_load_dwordx4 v[68:71], v[84:85], off offset:384
	v_add_co_u32_e32 v84, vcc, s34, v84
	s_waitcnt vmcnt(8)
	ds_write_b128 v109, v[136:139] offset:16384
	v_addc_co_u32_e32 v85, vcc, 0, v85, vcc
	v_mfma_f32_16x16x32_bf16 v[44:47], v[194:197], v[156:159], v[44:47]
	v_mfma_f32_16x16x32_bf16 v[40:43], v[198:201], v[156:159], v[40:43]
	v_mfma_f32_16x16x32_bf16 v[36:39], v[202:205], v[156:159], v[36:39]
	v_mfma_f32_16x16x32_bf16 v[32:35], v[206:209], v[156:159], v[32:35]
	global_load_dwordx4 v[76:79], v[76:77], off offset:384
	s_waitcnt vmcnt(8)
	ds_write_b128 v109, v[140:143] offset:20480
	v_mfma_f32_16x16x32_bf16 v[28:31], v[194:197], v[160:163], v[28:31]
	v_mfma_f32_16x16x32_bf16 v[24:27], v[198:201], v[160:163], v[24:27]
	v_mfma_f32_16x16x32_bf16 v[20:23], v[202:205], v[160:163], v[20:23]
	v_mfma_f32_16x16x32_bf16 v[16:19], v[206:209], v[160:163], v[16:19]
	global_load_dwordx4 v[80:83], v[80:81], off offset:384
	s_waitcnt vmcnt(8)
	ds_write_b128 v109, v[144:147] offset:24576
	v_mfma_f32_16x16x32_bf16 v[12:15], v[194:197], v[190:193], v[12:15]
	v_mfma_f32_16x16x32_bf16 v[8:11], v[198:201], v[190:193], v[8:11]
	v_mfma_f32_16x16x32_bf16 v[4:7], v[202:205], v[190:193], v[4:7]
	v_mfma_f32_16x16x32_bf16 v[0:3], v[206:209], v[190:193], v[0:3]
	global_load_dwordx4 v[84:87], v[84:85], off offset:384
	s_waitcnt vmcnt(8)
	ds_write_b128 v109, v[148:151] offset:28672
	s_setprio 0
	s_cmp_lt_u32 s0, 62
	s_mov_b32 s1, s0
	s_waitcnt lgkmcnt(0)
	s_barrier
	s_cbranch_scc1 .LBB0_582
	s_or_b32 s0, s69, 1
	s_mul_i32 s1, s69, 0x12000
	v_readlane_b32 s26, v250, 25
	v_readlane_b32 s27, v250, 26
	s_add_u32 s1, s26, s1
	s_addc_u32 s24, s27, 0
	s_add_u32 s38, s1, 0x5000
	v_readlane_b32 s1, v251, 5
	v_lshlrev_b32_e32 v114, 6, v102
	v_lshlrev_b32_e32 v115, 2, v97
	s_waitcnt vmcnt(5)
	v_add_u32_e32 v64, s1, v108
	v_readlane_b32 s1, v251, 6
	v_add_u32_e32 v56, 0xffffe000, v64
	v_or_b32_e32 v62, v64, v107
	v_or_b32_e32 v65, s1, v114
	v_lshrrev_b32_e32 v56, 10, v56
	s_movk_i32 s1, 0x1800
	v_mad_u32_u24 v56, v56, s1, s1
	v_cmp_lt_i32_e32 vcc, s13, v62
	v_or_b32_e32 v58, v65, v115
	s_addc_u32 s39, s24, 0
	v_cndmask_b32_e32 v56, 0, v56, vcc
	v_ashrrev_i32_e32 v57, 31, v56
	s_waitcnt vmcnt(4)
	v_lshlrev_b64 v[74:75], 2, v[56:57]
	v_ashrrev_i32_e32 v59, 31, v58
	v_ashrrev_i32_e32 v63, 31, v62
	v_lshl_add_u64 v[56:57], s[38:39], 0, v[74:75]
	v_lshlrev_b64 v[60:61], 2, v[58:59]
	v_readlane_b32 s16, v250, 15
	s_waitcnt vmcnt(1)
	v_lshl_add_u64 v[82:83], v[56:57], 0, v[60:61]
	v_lshlrev_b64 v[56:57], 12, v[62:63]
	v_readlane_b32 s17, v250, 16
	v_readlane_b32 s68, v250, 41
	s_mul_i32 s24, s0, 0x12000
	v_lshl_add_u64 v[56:57], s[16:17], 0, v[56:57]
	s_waitcnt vmcnt(0)
	v_lshl_add_u64 v[84:85], v[56:57], 0, v[60:61]
	global_load_dwordx4 v[116:119], v[82:83], off
	global_load_dwordx4 v[120:123], v[82:83], off offset:64
	global_load_dwordx4 v[124:127], v[82:83], off offset:128
	global_load_dwordx4 v[132:135], v[82:83], off offset:192
	global_load_dwordx4 v[190:193], v[84:85], off
	global_load_dwordx4 v[194:197], v[84:85], off offset:64
	global_load_dwordx4 v[198:201], v[84:85], off offset:128
	global_load_dwordx4 v[202:205], v[84:85], off offset:192
	v_add_co_u32_e32 v164, vcc, 0x10000, v84
	s_nop 1
	v_addc_co_u32_e32 v165, vcc, 0, v85, vcc
	v_add_co_u32_e32 v222, vcc, 0x20000, v84
	s_nop 1
	v_addc_co_u32_e32 v223, vcc, 0, v85, vcc
	v_add_co_u32_e32 v224, vcc, 0x30000, v84
	s_nop 1
	v_addc_co_u32_e32 v225, vcc, 0, v85, vcc
	global_load_dwordx4 v[206:209], v[164:165], off
	global_load_dwordx4 v[210:213], v[164:165], off offset:64
	global_load_dwordx4 v[214:217], v[164:165], off offset:128
	global_load_dwordx4 v[218:221], v[164:165], off offset:192
	s_lshl_b32 s0, s0, 12
	v_readlane_b32 s70, v250, 43
	v_readlane_b32 s71, v250, 44
	s_add_u32 s0, s70, s0
	s_addc_u32 s1, s71, 0
	s_add_u32 s24, s26, s24
	s_addc_u32 s25, s27, 0
	s_add_u32 s40, s24, 0x1000
	s_addc_u32 s41, s25, 0
	v_lshl_add_u64 v[74:75], s[40:41], 0, v[74:75]
	v_lshl_add_u64 v[56:57], s[0:1], 0, v[60:61]
	v_lshl_add_u64 v[86:87], v[74:75], 0, v[60:61]
	v_readlane_b32 s16, v250, 21
	v_lshlrev_b64 v[78:79], 11, v[62:63]
	v_readlane_b32 s17, v250, 22
	v_readlane_b32 s69, v250, 42
	v_readlane_b32 s69, v254, 49
	v_lshl_add_u64 v[78:79], s[16:17], 0, v[78:79]
	s_mul_i32 s24, s69, 0x140000
	s_add_u32 s24, s86, s24
	s_mov_b32 s16, 0xa000
	s_addc_u32 s25, s87, 0
	s_add_u32 s26, s24, 0xafba000
	s_addc_u32 s27, s25, 0
	v_cmp_eq_u32_e64 s[36:37], 0, v97
	v_readlane_b32 s72, v250, 45
	v_readlane_b32 s73, v250, 46
	v_readlane_b32 s74, v250, 47
	v_readlane_b32 s75, v250, 48
	v_readlane_b32 s76, v250, 49
	v_readlane_b32 s77, v250, 50
	v_readlane_b32 s78, v250, 51
	v_readlane_b32 s79, v250, 52
	v_readlane_b32 s80, v250, 53
	v_readlane_b32 s81, v250, 54
	v_readlane_b32 s82, v250, 55
	v_readlane_b32 s83, v250, 56
	s_waitcnt vmcnt(4)
	v_pk_fma_f32 v[68:69], v[94:95], v[118:119], v[192:193]
	v_pk_fma_f32 v[66:67], v[92:93], v[116:117], v[190:191]
	global_store_dwordx4 v[84:85], v[66:69], off
	global_load_dwordx4 v[136:139], v[56:57], off
	global_load_dwordx4 v[140:143], v[56:57], off offset:64
	global_load_dwordx4 v[144:147], v[56:57], off offset:128
	global_load_dwordx4 v[148:151], v[56:57], off offset:192
	global_load_dwordx4 v[152:155], v[86:87], off
	global_load_dwordx4 v[156:159], v[86:87], off offset:64
	global_load_dwordx4 v[160:163], v[86:87], off offset:128
	global_load_dwordx4 v[180:183], v[86:87], off offset:192
	v_lshl_add_u64 v[92:93], v[58:59], 1, v[78:79]
	s_waitcnt vmcnt(0)
	v_pk_mul_f32 v[72:73], v[68:69], v[138:139]
	v_pk_mul_f32 v[70:71], v[66:67], v[136:137]
	s_waitcnt vmcnt(0)
	v_pk_add_f32 v[76:77], v[154:155], 1.0 op_sel_hi:[1,0]
	v_pk_add_f32 v[74:75], v[152:153], 1.0 op_sel_hi:[1,0]
	v_pk_mul_f32 v[72:73], v[72:73], v[76:77]
	v_pk_mul_f32 v[70:71], v[70:71], v[74:75]
	v_and_b32_sdwa v76, v73, v170 dst_sel:DWORD dst_unused:UNUSED_PAD src0_sel:WORD_1 src1_sel:DWORD
	v_and_b32_sdwa v77, v71, v170 dst_sel:DWORD dst_unused:UNUSED_PAD src0_sel:WORD_1 src1_sel:DWORD
	v_and_b32_sdwa v74, v72, v170 dst_sel:DWORD dst_unused:UNUSED_PAD src0_sel:WORD_1 src1_sel:DWORD
	v_and_b32_sdwa v75, v70, v170 dst_sel:DWORD dst_unused:UNUSED_PAD src0_sel:WORD_1 src1_sel:DWORD
	v_add3_u32 v73, v73, v76, s56
	v_add3_u32 v71, v71, v77, s56
	v_add3_u32 v70, v70, v75, s56
	v_add3_u32 v72, v72, v74, s56
	v_and_b32_e32 v73, 0xffff0000, v73
	v_and_b32_e32 v74, 0xffff0000, v71
	v_or_b32_sdwa v71, v73, v72 dst_sel:DWORD dst_unused:UNUSED_PAD src0_sel:DWORD src1_sel:WORD_1
	v_or_b32_sdwa v70, v74, v70 dst_sel:DWORD dst_unused:UNUSED_PAD src0_sel:DWORD src1_sel:WORD_1
	global_store_dwordx2 v[92:93], v[70:71], off
	s_nop 0
	s_waitcnt vmcnt(0)
	v_pk_fma_f32 v[72:73], v[90:91], v[122:123], v[196:197]
	v_pk_fma_f32 v[70:71], v[88:89], v[120:121], v[194:195]
	global_store_dwordx4 v[84:85], v[70:73], off offset:64
	v_pk_mul_f32 v[76:77], v[72:73], v[142:143]
	v_pk_mul_f32 v[74:75], v[70:71], v[140:141]
	v_pk_add_f32 v[80:81], v[158:159], 1.0 op_sel_hi:[1,0]
	v_pk_add_f32 v[78:79], v[156:157], 1.0 op_sel_hi:[1,0]
	v_pk_mul_f32 v[76:77], v[76:77], v[80:81]
	v_pk_mul_f32 v[74:75], v[74:75], v[78:79]
	v_and_b32_sdwa v80, v77, v170 dst_sel:DWORD dst_unused:UNUSED_PAD src0_sel:WORD_1 src1_sel:DWORD
	v_and_b32_sdwa v81, v75, v170 dst_sel:DWORD dst_unused:UNUSED_PAD src0_sel:WORD_1 src1_sel:DWORD
	v_and_b32_sdwa v78, v76, v170 dst_sel:DWORD dst_unused:UNUSED_PAD src0_sel:WORD_1 src1_sel:DWORD
	v_and_b32_sdwa v79, v74, v170 dst_sel:DWORD dst_unused:UNUSED_PAD src0_sel:WORD_1 src1_sel:DWORD
	v_add3_u32 v77, v77, v80, s56
	v_add3_u32 v75, v75, v81, s56
	v_add3_u32 v74, v74, v79, s56
	v_add3_u32 v76, v76, v78, s56
	v_and_b32_e32 v77, 0xffff0000, v77
	v_and_b32_e32 v78, 0xffff0000, v75
	v_or_b32_sdwa v75, v77, v76 dst_sel:DWORD dst_unused:UNUSED_PAD src0_sel:DWORD src1_sel:WORD_1
	v_or_b32_sdwa v74, v78, v74 dst_sel:DWORD dst_unused:UNUSED_PAD src0_sel:DWORD src1_sel:WORD_1
	global_store_dwordx2 v[92:93], v[74:75], off offset:32
	s_nop 0
	v_pk_fma_f32 v[54:55], v[54:55], v[126:127], v[200:201]
	v_pk_fma_f32 v[52:53], v[52:53], v[124:125], v[198:199]
	global_store_dwordx4 v[84:85], v[52:55], off offset:128
	v_pk_mul_f32 v[76:77], v[54:55], v[146:147]
	v_pk_mul_f32 v[74:75], v[52:53], v[144:145]
	v_pk_add_f32 v[80:81], v[162:163], 1.0 op_sel_hi:[1,0]
	v_pk_add_f32 v[78:79], v[160:161], 1.0 op_sel_hi:[1,0]
	v_pk_mul_f32 v[76:77], v[76:77], v[80:81]
	v_pk_mul_f32 v[74:75], v[74:75], v[78:79]
	v_and_b32_sdwa v80, v77, v170 dst_sel:DWORD dst_unused:UNUSED_PAD src0_sel:WORD_1 src1_sel:DWORD
	v_and_b32_sdwa v81, v75, v170 dst_sel:DWORD dst_unused:UNUSED_PAD src0_sel:WORD_1 src1_sel:DWORD
	v_and_b32_sdwa v78, v76, v170 dst_sel:DWORD dst_unused:UNUSED_PAD src0_sel:WORD_1 src1_sel:DWORD
	v_and_b32_sdwa v79, v74, v170 dst_sel:DWORD dst_unused:UNUSED_PAD src0_sel:WORD_1 src1_sel:DWORD
	v_add3_u32 v77, v77, v80, s56
	v_add3_u32 v75, v75, v81, s56
	v_add3_u32 v74, v74, v79, s56
	v_add3_u32 v76, v76, v78, s56
	v_and_b32_e32 v77, 0xffff0000, v77
	v_and_b32_e32 v78, 0xffff0000, v75
	v_or_b32_sdwa v75, v77, v76 dst_sel:DWORD dst_unused:UNUSED_PAD src0_sel:DWORD src1_sel:WORD_1
	v_or_b32_sdwa v74, v78, v74 dst_sel:DWORD dst_unused:UNUSED_PAD src0_sel:DWORD src1_sel:WORD_1
	global_store_dwordx2 v[92:93], v[74:75], off offset:64
	s_nop 0
	v_pk_fma_f32 v[76:77], v[50:51], v[134:135], v[204:205]
	v_pk_fma_f32 v[74:75], v[48:49], v[132:133], v[202:203]
	global_store_dwordx4 v[84:85], v[74:77], off offset:192
	s_nop 0
	v_mul_f32_e32 v50, v67, v67
	v_mul_f32_e32 v51, v71, v71
	v_fmac_f32_e32 v50, v66, v66
	v_fmac_f32_e32 v51, v70, v70
	v_fmac_f32_e32 v50, v68, v68
	v_fmac_f32_e32 v51, v72, v72
	v_fmac_f32_e32 v50, v69, v69
	v_fmac_f32_e32 v51, v73, v73
	v_add_f32_e32 v50, v50, v51
	v_mul_f32_e32 v51, v53, v53
	v_fmac_f32_e32 v51, v52, v52
	v_fmac_f32_e32 v51, v54, v54
	v_fmac_f32_e32 v51, v55, v55
	v_add_f32_e32 v50, v50, v51
	v_mul_f32_e32 v51, v75, v75
	v_xor_b32_e32 v48, 16, v176
	v_fmac_f32_e32 v51, v74, v74
	v_cmp_lt_i32_e32 vcc, v48, v177
	v_fmac_f32_e32 v51, v76, v76
	v_fmac_f32_e32 v51, v77, v77
	v_cndmask_b32_e32 v48, v176, v48, vcc
	v_lshlrev_b32_e32 v105, 2, v48
	v_add_f32_e32 v50, v50, v51
	ds_bpermute_b32 v51, v105, v50
	v_xor_b32_e32 v49, 32, v176
	v_cmp_lt_i32_e32 vcc, v49, v177
	v_lshrrev_b32_e32 v48, 6, v65
	v_mul_lo_u32 v48, v48, s16
	v_cndmask_b32_e32 v49, v176, v49, vcc
	v_lshlrev_b32_e32 v104, 2, v49
	s_waitcnt lgkmcnt(0)
	v_add_f32_e32 v50, v50, v51
	ds_bpermute_b32 v51, v104, v50
	v_ashrrev_i32_e32 v49, 31, v48
	v_lshl_add_u64 v[48:49], s[26:27], 0, v[48:49]
	v_lshl_add_u64 v[48:49], v[62:63], 2, v[48:49]
	v_pk_mul_f32 v[52:53], v[76:77], v[150:151]
	v_pk_mul_f32 v[54:55], v[74:75], v[148:149]
	v_pk_add_f32 v[66:67], v[182:183], 1.0 op_sel_hi:[1,0]
	v_pk_add_f32 v[68:69], v[180:181], 1.0 op_sel_hi:[1,0]
	v_pk_mul_f32 v[52:53], v[52:53], v[66:67]
	v_pk_mul_f32 v[54:55], v[54:55], v[68:69]
	v_and_b32_sdwa v67, v53, v170 dst_sel:DWORD dst_unused:UNUSED_PAD src0_sel:WORD_1 src1_sel:DWORD
	v_and_b32_sdwa v68, v55, v170 dst_sel:DWORD dst_unused:UNUSED_PAD src0_sel:WORD_1 src1_sel:DWORD
	v_and_b32_sdwa v65, v52, v170 dst_sel:DWORD dst_unused:UNUSED_PAD src0_sel:WORD_1 src1_sel:DWORD
	v_and_b32_sdwa v66, v54, v170 dst_sel:DWORD dst_unused:UNUSED_PAD src0_sel:WORD_1 src1_sel:DWORD
	v_add3_u32 v53, v53, v67, s56
	v_add3_u32 v55, v55, v68, s56
	v_add3_u32 v54, v54, v66, s56
	v_add3_u32 v52, v52, v65, s56
	v_and_b32_e32 v53, 0xffff0000, v53
	v_and_b32_e32 v55, 0xffff0000, v55
	v_or_b32_sdwa v53, v53, v52 dst_sel:DWORD dst_unused:UNUSED_PAD src0_sel:DWORD src1_sel:WORD_1
	v_or_b32_sdwa v52, v55, v54 dst_sel:DWORD dst_unused:UNUSED_PAD src0_sel:DWORD src1_sel:WORD_1
	global_store_dwordx2 v[92:93], v[52:53], off offset:96
	s_and_saveexec_b64 s[24:25], s[36:37]
	s_cbranch_execz .LBB0_585
	s_waitcnt lgkmcnt(0)
	v_add_f32_e32 v50, v50, v51
	global_store_dword v[48:49], v50, off
.LBB0_585:
	s_or_b64 exec, exec, s[24:25]
	v_add_u32_e32 v50, 0xffffe010, v64
	v_or_b32_e32 v54, 16, v62
	v_lshrrev_b32_e32 v50, 10, v50
	s_movk_i32 s5, 0x1800
	s_movk_i32 s13, 0x1fff
	v_mad_u32_u24 v50, v50, s5, s5
	v_cmp_lt_i32_e32 vcc, s13, v54
	v_ashrrev_i32_e32 v55, 31, v54
	v_readlane_b32 s16, v250, 15
	v_cndmask_b32_e32 v50, 0, v50, vcc
	s_waitcnt lgkmcnt(0)
	v_ashrrev_i32_e32 v51, 31, v50
	v_lshlrev_b64 v[70:71], 2, v[50:51]
	v_lshl_add_u64 v[50:51], s[38:39], 0, v[70:71]
	v_lshl_add_u64 v[72:73], v[50:51], 0, v[60:61]
	v_lshlrev_b64 v[50:51], 12, v[54:55]
	v_readlane_b32 s17, v250, 16
	v_lshl_add_u64 v[70:71], s[40:41], 0, v[70:71]
	v_lshl_add_u64 v[70:71], v[70:71], 0, v[60:61]
	v_lshl_add_u64 v[50:51], s[16:17], 0, v[50:51]
	v_lshl_add_u64 v[74:75], v[50:51], 0, v[60:61]
	v_readlane_b32 s16, v250, 21
	v_lshlrev_b64 v[54:55], 11, v[54:55]
	v_readlane_b32 s17, v250, 22
	global_load_dwordx4 v[190:193], v[222:223], off
	global_load_dwordx4 v[194:197], v[222:223], off offset:64
	global_load_dwordx4 v[198:201], v[222:223], off offset:128
	global_load_dwordx4 v[202:205], v[222:223], off offset:192
	s_waitcnt vmcnt(20)
	v_pk_fma_f32 v[46:47], v[46:47], v[118:119], v[208:209]
	v_pk_fma_f32 v[44:45], v[44:45], v[116:117], v[206:207]
	global_store_dwordx4 v[74:75], v[44:47], off
	v_lshl_add_u64 v[54:55], s[16:17], 0, v[54:55]
	v_lshl_add_u64 v[54:55], v[58:59], 1, v[54:55]
	v_pk_mul_f32 v[52:53], v[46:47], v[138:139]
	v_pk_mul_f32 v[50:51], v[44:45], v[136:137]
	v_pk_add_f32 v[68:69], v[154:155], 1.0 op_sel_hi:[1,0]
	v_pk_add_f32 v[66:67], v[152:153], 1.0 op_sel_hi:[1,0]
	v_pk_mul_f32 v[52:53], v[52:53], v[68:69]
	v_pk_mul_f32 v[50:51], v[50:51], v[66:67]
	v_and_b32_sdwa v66, v53, v170 dst_sel:DWORD dst_unused:UNUSED_PAD src0_sel:WORD_1 src1_sel:DWORD
	v_and_b32_sdwa v67, v51, v170 dst_sel:DWORD dst_unused:UNUSED_PAD src0_sel:WORD_1 src1_sel:DWORD
	v_and_b32_sdwa v63, v52, v170 dst_sel:DWORD dst_unused:UNUSED_PAD src0_sel:WORD_1 src1_sel:DWORD
	v_and_b32_sdwa v65, v50, v170 dst_sel:DWORD dst_unused:UNUSED_PAD src0_sel:WORD_1 src1_sel:DWORD
	v_add3_u32 v53, v53, v66, s56
	v_add3_u32 v51, v51, v67, s56
	v_add3_u32 v50, v50, v65, s56
	v_add3_u32 v52, v52, v63, s56
	v_and_b32_e32 v53, 0xffff0000, v53
	v_and_b32_e32 v63, 0xffff0000, v51
	v_or_b32_sdwa v51, v53, v52 dst_sel:DWORD dst_unused:UNUSED_PAD src0_sel:DWORD src1_sel:WORD_1
	v_or_b32_sdwa v50, v63, v50 dst_sel:DWORD dst_unused:UNUSED_PAD src0_sel:DWORD src1_sel:WORD_1
	global_store_dwordx2 v[54:55], v[50:51], off
	s_nop 0
	v_pk_fma_f32 v[42:43], v[42:43], v[122:123], v[212:213]
	v_pk_fma_f32 v[40:41], v[40:41], v[120:121], v[210:211]
	global_store_dwordx4 v[74:75], v[40:43], off offset:64
	v_pk_mul_f32 v[52:53], v[42:43], v[142:143]
	v_pk_mul_f32 v[50:51], v[40:41], v[140:141]
	v_pk_add_f32 v[68:69], v[158:159], 1.0 op_sel_hi:[1,0]
	v_pk_add_f32 v[66:67], v[156:157], 1.0 op_sel_hi:[1,0]
	v_pk_mul_f32 v[52:53], v[52:53], v[68:69]
	v_pk_mul_f32 v[50:51], v[50:51], v[66:67]
	v_and_b32_sdwa v66, v53, v170 dst_sel:DWORD dst_unused:UNUSED_PAD src0_sel:WORD_1 src1_sel:DWORD
	v_and_b32_sdwa v67, v51, v170 dst_sel:DWORD dst_unused:UNUSED_PAD src0_sel:WORD_1 src1_sel:DWORD
	v_and_b32_sdwa v63, v52, v170 dst_sel:DWORD dst_unused:UNUSED_PAD src0_sel:WORD_1 src1_sel:DWORD
	v_and_b32_sdwa v65, v50, v170 dst_sel:DWORD dst_unused:UNUSED_PAD src0_sel:WORD_1 src1_sel:DWORD
	v_add3_u32 v53, v53, v66, s56
	v_add3_u32 v51, v51, v67, s56
	v_add3_u32 v50, v50, v65, s56
	v_add3_u32 v52, v52, v63, s56
	v_and_b32_e32 v53, 0xffff0000, v53
	v_and_b32_e32 v63, 0xffff0000, v51
	v_or_b32_sdwa v51, v53, v52 dst_sel:DWORD dst_unused:UNUSED_PAD src0_sel:DWORD src1_sel:WORD_1
	v_or_b32_sdwa v50, v63, v50 dst_sel:DWORD dst_unused:UNUSED_PAD src0_sel:DWORD src1_sel:WORD_1
	global_store_dwordx2 v[54:55], v[50:51], off offset:32
	s_nop 0
	v_pk_fma_f32 v[38:39], v[38:39], v[126:127], v[216:217]
	v_pk_fma_f32 v[36:37], v[36:37], v[124:125], v[214:215]
	global_store_dwordx4 v[74:75], v[36:39], off offset:128
	v_pk_mul_f32 v[52:53], v[38:39], v[146:147]
	v_pk_mul_f32 v[50:51], v[36:37], v[144:145]
	v_pk_add_f32 v[68:69], v[162:163], 1.0 op_sel_hi:[1,0]
	v_pk_add_f32 v[66:67], v[160:161], 1.0 op_sel_hi:[1,0]
	v_pk_mul_f32 v[52:53], v[52:53], v[68:69]
	v_pk_mul_f32 v[50:51], v[50:51], v[66:67]
	v_and_b32_sdwa v66, v53, v170 dst_sel:DWORD dst_unused:UNUSED_PAD src0_sel:WORD_1 src1_sel:DWORD
	v_and_b32_sdwa v67, v51, v170 dst_sel:DWORD dst_unused:UNUSED_PAD src0_sel:WORD_1 src1_sel:DWORD
	v_and_b32_sdwa v63, v52, v170 dst_sel:DWORD dst_unused:UNUSED_PAD src0_sel:WORD_1 src1_sel:DWORD
	v_and_b32_sdwa v65, v50, v170 dst_sel:DWORD dst_unused:UNUSED_PAD src0_sel:WORD_1 src1_sel:DWORD
	v_add3_u32 v53, v53, v66, s56
	v_add3_u32 v51, v51, v67, s56
	v_add3_u32 v50, v50, v65, s56
	v_add3_u32 v52, v52, v63, s56
	v_and_b32_e32 v53, 0xffff0000, v53
	v_and_b32_e32 v63, 0xffff0000, v51
	v_or_b32_sdwa v51, v53, v52 dst_sel:DWORD dst_unused:UNUSED_PAD src0_sel:DWORD src1_sel:WORD_1
	v_or_b32_sdwa v50, v63, v50 dst_sel:DWORD dst_unused:UNUSED_PAD src0_sel:DWORD src1_sel:WORD_1
	global_store_dwordx2 v[54:55], v[50:51], off offset:64
	s_nop 0
	v_pk_fma_f32 v[52:53], v[34:35], v[134:135], v[220:221]
	v_pk_fma_f32 v[50:51], v[32:33], v[132:133], v[218:219]
	global_store_dwordx4 v[74:75], v[50:53], off offset:192
	s_nop 0
	v_mul_f32_e32 v32, v45, v45
	v_mul_f32_e32 v33, v41, v41
	v_fmac_f32_e32 v32, v44, v44
	v_fmac_f32_e32 v33, v40, v40
	v_fmac_f32_e32 v32, v46, v46
	v_fmac_f32_e32 v33, v42, v42
	v_fmac_f32_e32 v32, v47, v47
	v_fmac_f32_e32 v33, v43, v43
	v_add_f32_e32 v32, v32, v33
	v_mul_f32_e32 v33, v37, v37
	v_fmac_f32_e32 v33, v36, v36
	v_fmac_f32_e32 v33, v38, v38
	v_fmac_f32_e32 v33, v39, v39
	v_add_f32_e32 v32, v32, v33
	v_mul_f32_e32 v33, v51, v51
	v_fmac_f32_e32 v33, v50, v50
	v_fmac_f32_e32 v33, v52, v52
	v_fmac_f32_e32 v33, v53, v53
	v_add_f32_e32 v32, v32, v33
	ds_bpermute_b32 v33, v105, v32
	s_waitcnt lgkmcnt(0)
	v_add_f32_e32 v32, v32, v33
	ds_bpermute_b32 v33, v104, v32
	v_pk_mul_f32 v[34:35], v[52:53], v[150:151]
	v_pk_mul_f32 v[36:37], v[50:51], v[148:149]
	v_pk_add_f32 v[38:39], v[182:183], 1.0 op_sel_hi:[1,0]
	v_pk_add_f32 v[40:41], v[180:181], 1.0 op_sel_hi:[1,0]
	v_pk_mul_f32 v[34:35], v[34:35], v[38:39]
	v_pk_mul_f32 v[36:37], v[36:37], v[40:41]
	v_and_b32_sdwa v40, v35, v170 dst_sel:DWORD dst_unused:UNUSED_PAD src0_sel:WORD_1 src1_sel:DWORD
	v_and_b32_sdwa v41, v37, v170 dst_sel:DWORD dst_unused:UNUSED_PAD src0_sel:WORD_1 src1_sel:DWORD
	v_and_b32_sdwa v38, v34, v170 dst_sel:DWORD dst_unused:UNUSED_PAD src0_sel:WORD_1 src1_sel:DWORD
	v_and_b32_sdwa v39, v36, v170 dst_sel:DWORD dst_unused:UNUSED_PAD src0_sel:WORD_1 src1_sel:DWORD
	v_add3_u32 v35, v35, v40, s56
	v_add3_u32 v37, v37, v41, s56
	v_add3_u32 v36, v36, v39, s56
	v_add3_u32 v34, v34, v38, s56
	v_and_b32_e32 v35, 0xffff0000, v35
	v_and_b32_e32 v37, 0xffff0000, v37
	v_or_b32_sdwa v35, v35, v34 dst_sel:DWORD dst_unused:UNUSED_PAD src0_sel:DWORD src1_sel:WORD_1
	v_or_b32_sdwa v34, v37, v36 dst_sel:DWORD dst_unused:UNUSED_PAD src0_sel:DWORD src1_sel:WORD_1
	global_store_dwordx2 v[54:55], v[34:35], off offset:96
	s_and_saveexec_b64 s[24:25], s[36:37]
	s_cbranch_execz .LBB0_587
	s_waitcnt lgkmcnt(0)
	v_add_f32_e32 v32, v32, v33
	global_store_dword v[48:49], v32, off offset:64
.LBB0_587:
	s_or_b64 exec, exec, s[24:25]
	v_add_u32_e32 v32, 0xffffe020, v64
	v_or_b32_e32 v40, 32, v62
	v_lshrrev_b32_e32 v32, 10, v32
	v_mad_u32_u24 v32, v32, s5, s5
	v_cmp_lt_i32_e32 vcc, s13, v40
	v_ashrrev_i32_e32 v41, 31, v40
	v_readlane_b32 s16, v250, 15
	v_cndmask_b32_e32 v32, 0, v32, vcc
	s_waitcnt lgkmcnt(0)
	v_ashrrev_i32_e32 v33, 31, v32
	v_lshlrev_b64 v[42:43], 2, v[32:33]
	v_lshl_add_u64 v[32:33], s[38:39], 0, v[42:43]
	v_lshl_add_u64 v[44:45], v[32:33], 0, v[60:61]
	v_lshlrev_b64 v[32:33], 12, v[40:41]
	v_readlane_b32 s17, v250, 16
	v_lshl_add_u64 v[42:43], s[40:41], 0, v[42:43]
	v_lshl_add_u64 v[42:43], v[42:43], 0, v[60:61]
	v_lshl_add_u64 v[32:33], s[16:17], 0, v[32:33]
	v_lshl_add_u64 v[46:47], v[32:33], 0, v[60:61]
	v_readlane_b32 s16, v250, 21
	v_lshlrev_b64 v[40:41], 11, v[40:41]
	v_readlane_b32 s17, v250, 22
	global_load_dwordx4 v[206:209], v[224:225], off
	global_load_dwordx4 v[210:213], v[224:225], off offset:64
	global_load_dwordx4 v[214:217], v[224:225], off offset:128
	global_load_dwordx4 v[218:221], v[224:225], off offset:192
	s_waitcnt vmcnt(12)
	v_pk_fma_f32 v[30:31], v[30:31], v[118:119], v[192:193]
	v_pk_fma_f32 v[28:29], v[28:29], v[116:117], v[190:191]
	global_store_dwordx4 v[46:47], v[28:31], off
	v_lshl_add_u64 v[40:41], s[16:17], 0, v[40:41]
	v_lshl_add_u64 v[50:51], v[58:59], 1, v[40:41]
	v_pk_mul_f32 v[34:35], v[30:31], v[138:139]
	v_pk_mul_f32 v[32:33], v[28:29], v[136:137]
	v_pk_add_f32 v[38:39], v[154:155], 1.0 op_sel_hi:[1,0]
	v_pk_add_f32 v[36:37], v[152:153], 1.0 op_sel_hi:[1,0]
	v_pk_mul_f32 v[34:35], v[34:35], v[38:39]
	v_pk_mul_f32 v[32:33], v[32:33], v[36:37]
	v_and_b32_sdwa v38, v35, v170 dst_sel:DWORD dst_unused:UNUSED_PAD src0_sel:WORD_1 src1_sel:DWORD
	v_and_b32_sdwa v39, v33, v170 dst_sel:DWORD dst_unused:UNUSED_PAD src0_sel:WORD_1 src1_sel:DWORD
	v_and_b32_sdwa v36, v34, v170 dst_sel:DWORD dst_unused:UNUSED_PAD src0_sel:WORD_1 src1_sel:DWORD
	v_and_b32_sdwa v37, v32, v170 dst_sel:DWORD dst_unused:UNUSED_PAD src0_sel:WORD_1 src1_sel:DWORD
	v_add3_u32 v35, v35, v38, s56
	v_add3_u32 v33, v33, v39, s56
	v_add3_u32 v32, v32, v37, s56
	v_add3_u32 v34, v34, v36, s56
	v_and_b32_e32 v35, 0xffff0000, v35
	v_and_b32_e32 v36, 0xffff0000, v33
	v_or_b32_sdwa v33, v35, v34 dst_sel:DWORD dst_unused:UNUSED_PAD src0_sel:DWORD src1_sel:WORD_1
	v_or_b32_sdwa v32, v36, v32 dst_sel:DWORD dst_unused:UNUSED_PAD src0_sel:DWORD src1_sel:WORD_1
	global_store_dwordx2 v[50:51], v[32:33], off
	s_nop 0
	v_pk_fma_f32 v[26:27], v[26:27], v[122:123], v[196:197]
	v_pk_fma_f32 v[24:25], v[24:25], v[120:121], v[194:195]
	global_store_dwordx4 v[46:47], v[24:27], off offset:64
	v_pk_mul_f32 v[34:35], v[26:27], v[142:143]
	v_pk_mul_f32 v[32:33], v[24:25], v[140:141]
	v_pk_add_f32 v[38:39], v[158:159], 1.0 op_sel_hi:[1,0]
	v_pk_add_f32 v[36:37], v[156:157], 1.0 op_sel_hi:[1,0]
	v_pk_mul_f32 v[34:35], v[34:35], v[38:39]
	v_pk_mul_f32 v[32:33], v[32:33], v[36:37]
	v_and_b32_sdwa v38, v35, v170 dst_sel:DWORD dst_unused:UNUSED_PAD src0_sel:WORD_1 src1_sel:DWORD
	v_and_b32_sdwa v39, v33, v170 dst_sel:DWORD dst_unused:UNUSED_PAD src0_sel:WORD_1 src1_sel:DWORD
	v_and_b32_sdwa v36, v34, v170 dst_sel:DWORD dst_unused:UNUSED_PAD src0_sel:WORD_1 src1_sel:DWORD
	v_and_b32_sdwa v37, v32, v170 dst_sel:DWORD dst_unused:UNUSED_PAD src0_sel:WORD_1 src1_sel:DWORD
	v_add3_u32 v35, v35, v38, s56
	v_add3_u32 v33, v33, v39, s56
	v_add3_u32 v32, v32, v37, s56
	v_add3_u32 v34, v34, v36, s56
	v_and_b32_e32 v35, 0xffff0000, v35
	v_and_b32_e32 v36, 0xffff0000, v33
	v_or_b32_sdwa v33, v35, v34 dst_sel:DWORD dst_unused:UNUSED_PAD src0_sel:DWORD src1_sel:WORD_1
	v_or_b32_sdwa v32, v36, v32 dst_sel:DWORD dst_unused:UNUSED_PAD src0_sel:DWORD src1_sel:WORD_1
	global_store_dwordx2 v[50:51], v[32:33], off offset:32
	s_nop 0
	v_pk_fma_f32 v[22:23], v[22:23], v[126:127], v[200:201]
	v_pk_fma_f32 v[20:21], v[20:21], v[124:125], v[198:199]
	global_store_dwordx4 v[46:47], v[20:23], off offset:128
	v_pk_mul_f32 v[34:35], v[22:23], v[146:147]
	v_pk_mul_f32 v[32:33], v[20:21], v[144:145]
	v_pk_add_f32 v[38:39], v[162:163], 1.0 op_sel_hi:[1,0]
	v_pk_add_f32 v[36:37], v[160:161], 1.0 op_sel_hi:[1,0]
	v_pk_mul_f32 v[34:35], v[34:35], v[38:39]
	v_pk_mul_f32 v[32:33], v[32:33], v[36:37]
	v_and_b32_sdwa v38, v35, v170 dst_sel:DWORD dst_unused:UNUSED_PAD src0_sel:WORD_1 src1_sel:DWORD
	v_and_b32_sdwa v39, v33, v170 dst_sel:DWORD dst_unused:UNUSED_PAD src0_sel:WORD_1 src1_sel:DWORD
	v_and_b32_sdwa v36, v34, v170 dst_sel:DWORD dst_unused:UNUSED_PAD src0_sel:WORD_1 src1_sel:DWORD
	v_and_b32_sdwa v37, v32, v170 dst_sel:DWORD dst_unused:UNUSED_PAD src0_sel:WORD_1 src1_sel:DWORD
	v_add3_u32 v35, v35, v38, s56
	v_add3_u32 v33, v33, v39, s56
	v_add3_u32 v32, v32, v37, s56
	v_add3_u32 v34, v34, v36, s56
	v_and_b32_e32 v35, 0xffff0000, v35
	v_and_b32_e32 v36, 0xffff0000, v33
	v_or_b32_sdwa v33, v35, v34 dst_sel:DWORD dst_unused:UNUSED_PAD src0_sel:DWORD src1_sel:WORD_1
	v_or_b32_sdwa v32, v36, v32 dst_sel:DWORD dst_unused:UNUSED_PAD src0_sel:DWORD src1_sel:WORD_1
	global_store_dwordx2 v[50:51], v[32:33], off offset:64
	s_nop 0
	v_pk_fma_f32 v[34:35], v[18:19], v[134:135], v[204:205]
	v_pk_fma_f32 v[32:33], v[16:17], v[132:133], v[202:203]
	global_store_dwordx4 v[46:47], v[32:35], off offset:192
	s_nop 0
	v_mul_f32_e32 v16, v29, v29
	v_mul_f32_e32 v17, v25, v25
	v_fmac_f32_e32 v16, v28, v28
	v_fmac_f32_e32 v17, v24, v24
	v_fmac_f32_e32 v16, v30, v30
	v_fmac_f32_e32 v17, v26, v26
	v_fmac_f32_e32 v16, v31, v31
	v_fmac_f32_e32 v17, v27, v27
	v_add_f32_e32 v16, v16, v17
	v_mul_f32_e32 v17, v21, v21
	v_fmac_f32_e32 v17, v20, v20
	v_fmac_f32_e32 v17, v22, v22
	v_fmac_f32_e32 v17, v23, v23
	v_add_f32_e32 v16, v16, v17
	v_mul_f32_e32 v17, v33, v33
	v_fmac_f32_e32 v17, v32, v32
	v_fmac_f32_e32 v17, v34, v34
	v_fmac_f32_e32 v17, v35, v35
	v_add_f32_e32 v16, v16, v17
	ds_bpermute_b32 v17, v105, v16
	s_waitcnt lgkmcnt(0)
	v_add_f32_e32 v16, v16, v17
	ds_bpermute_b32 v17, v104, v16
	v_pk_mul_f32 v[18:19], v[34:35], v[150:151]
	v_pk_mul_f32 v[20:21], v[32:33], v[148:149]
	v_pk_add_f32 v[22:23], v[182:183], 1.0 op_sel_hi:[1,0]
	v_pk_add_f32 v[24:25], v[180:181], 1.0 op_sel_hi:[1,0]
	v_pk_mul_f32 v[18:19], v[18:19], v[22:23]
	v_pk_mul_f32 v[20:21], v[20:21], v[24:25]
	v_and_b32_sdwa v24, v19, v170 dst_sel:DWORD dst_unused:UNUSED_PAD src0_sel:WORD_1 src1_sel:DWORD
	v_and_b32_sdwa v25, v21, v170 dst_sel:DWORD dst_unused:UNUSED_PAD src0_sel:WORD_1 src1_sel:DWORD
	v_and_b32_sdwa v22, v18, v170 dst_sel:DWORD dst_unused:UNUSED_PAD src0_sel:WORD_1 src1_sel:DWORD
	v_and_b32_sdwa v23, v20, v170 dst_sel:DWORD dst_unused:UNUSED_PAD src0_sel:WORD_1 src1_sel:DWORD
	v_add3_u32 v19, v19, v24, s56
	v_add3_u32 v21, v21, v25, s56
	v_add3_u32 v20, v20, v23, s56
	v_add3_u32 v18, v18, v22, s56
	v_and_b32_e32 v19, 0xffff0000, v19
	v_and_b32_e32 v21, 0xffff0000, v21
	v_or_b32_sdwa v19, v19, v18 dst_sel:DWORD dst_unused:UNUSED_PAD src0_sel:DWORD src1_sel:WORD_1
	v_or_b32_sdwa v18, v21, v20 dst_sel:DWORD dst_unused:UNUSED_PAD src0_sel:DWORD src1_sel:WORD_1
	global_store_dwordx2 v[50:51], v[18:19], off offset:96
	s_and_saveexec_b64 s[24:25], s[36:37]
	s_movk_i32 s8, 0x400
	s_mov_b32 s5, 0xffff0000
	s_mov_b32 s9, 0x12000
	s_movk_i32 s89, 0xff
	s_cbranch_execz .LBB0_589
	s_waitcnt lgkmcnt(0)
	v_add_f32_e32 v16, v16, v17
	global_store_dword v[48:49], v16, off offset:128
.LBB0_589:
	s_or_b64 exec, exec, s[24:25]
	v_add_u32_e32 v16, 0xffffe030, v64
	v_or_b32_e32 v24, 48, v62
	v_lshrrev_b32_e32 v16, 10, v16
	s_movk_i32 s16, 0x1800
	v_mad_u32_u24 v16, v16, s16, s16
	v_cmp_lt_i32_e32 vcc, s13, v24
	v_ashrrev_i32_e32 v25, 31, v24
	v_readlane_b32 s16, v250, 15
	v_cndmask_b32_e32 v16, 0, v16, vcc
	s_waitcnt lgkmcnt(0)
	v_ashrrev_i32_e32 v17, 31, v16
	v_lshlrev_b64 v[26:27], 2, v[16:17]
	v_lshl_add_u64 v[16:17], s[38:39], 0, v[26:27]
	v_lshl_add_u64 v[28:29], v[16:17], 0, v[60:61]
	v_lshlrev_b64 v[16:17], 12, v[24:25]
	v_readlane_b32 s17, v250, 16
	v_lshl_add_u64 v[26:27], s[40:41], 0, v[26:27]
	v_lshl_add_u64 v[26:27], v[26:27], 0, v[60:61]
	v_lshl_add_u64 v[16:17], s[16:17], 0, v[16:17]
	v_lshl_add_u64 v[30:31], v[16:17], 0, v[60:61]
	v_readlane_b32 s16, v250, 21
	v_lshlrev_b64 v[24:25], 11, v[24:25]
	v_readlane_b32 s17, v250, 22
	s_waitcnt vmcnt(8)
	v_pk_fma_f32 v[14:15], v[14:15], v[118:119], v[208:209]
	v_pk_fma_f32 v[12:13], v[12:13], v[116:117], v[206:207]
	global_store_dwordx4 v[30:31], v[12:15], off
	v_lshl_add_u64 v[24:25], s[16:17], 0, v[24:25]
	v_lshl_add_u64 v[32:33], v[58:59], 1, v[24:25]
	v_pk_mul_f32 v[18:19], v[14:15], v[138:139]
	v_pk_mul_f32 v[16:17], v[12:13], v[136:137]
	v_pk_add_f32 v[22:23], v[154:155], 1.0 op_sel_hi:[1,0]
	v_pk_add_f32 v[20:21], v[152:153], 1.0 op_sel_hi:[1,0]
	v_pk_mul_f32 v[18:19], v[18:19], v[22:23]
	v_pk_mul_f32 v[16:17], v[16:17], v[20:21]
	v_and_b32_sdwa v22, v19, v170 dst_sel:DWORD dst_unused:UNUSED_PAD src0_sel:WORD_1 src1_sel:DWORD
	v_and_b32_sdwa v23, v17, v170 dst_sel:DWORD dst_unused:UNUSED_PAD src0_sel:WORD_1 src1_sel:DWORD
	v_and_b32_sdwa v20, v18, v170 dst_sel:DWORD dst_unused:UNUSED_PAD src0_sel:WORD_1 src1_sel:DWORD
	v_and_b32_sdwa v21, v16, v170 dst_sel:DWORD dst_unused:UNUSED_PAD src0_sel:WORD_1 src1_sel:DWORD
	v_add3_u32 v19, v19, v22, s56
	v_add3_u32 v17, v17, v23, s56
	v_add3_u32 v16, v16, v21, s56
	v_add3_u32 v18, v18, v20, s56
	v_and_b32_e32 v19, 0xffff0000, v19
	v_and_b32_e32 v20, 0xffff0000, v17
	v_or_b32_sdwa v17, v19, v18 dst_sel:DWORD dst_unused:UNUSED_PAD src0_sel:DWORD src1_sel:WORD_1
	v_or_b32_sdwa v16, v20, v16 dst_sel:DWORD dst_unused:UNUSED_PAD src0_sel:DWORD src1_sel:WORD_1
	global_store_dwordx2 v[32:33], v[16:17], off
	s_nop 0
	v_pk_fma_f32 v[10:11], v[10:11], v[122:123], v[212:213]
	v_pk_fma_f32 v[8:9], v[8:9], v[120:121], v[210:211]
	global_store_dwordx4 v[30:31], v[8:11], off offset:64
	v_pk_mul_f32 v[18:19], v[10:11], v[142:143]
	v_pk_mul_f32 v[16:17], v[8:9], v[140:141]
	v_pk_add_f32 v[22:23], v[158:159], 1.0 op_sel_hi:[1,0]
	v_pk_add_f32 v[20:21], v[156:157], 1.0 op_sel_hi:[1,0]
	v_pk_mul_f32 v[18:19], v[18:19], v[22:23]
	v_pk_mul_f32 v[16:17], v[16:17], v[20:21]
	v_and_b32_sdwa v22, v19, v170 dst_sel:DWORD dst_unused:UNUSED_PAD src0_sel:WORD_1 src1_sel:DWORD
	v_and_b32_sdwa v23, v17, v170 dst_sel:DWORD dst_unused:UNUSED_PAD src0_sel:WORD_1 src1_sel:DWORD
	v_and_b32_sdwa v20, v18, v170 dst_sel:DWORD dst_unused:UNUSED_PAD src0_sel:WORD_1 src1_sel:DWORD
	v_and_b32_sdwa v21, v16, v170 dst_sel:DWORD dst_unused:UNUSED_PAD src0_sel:WORD_1 src1_sel:DWORD
	v_add3_u32 v19, v19, v22, s56
	v_add3_u32 v17, v17, v23, s56
	v_add3_u32 v16, v16, v21, s56
	v_add3_u32 v18, v18, v20, s56
	v_and_b32_e32 v19, 0xffff0000, v19
	v_and_b32_e32 v20, 0xffff0000, v17
	v_or_b32_sdwa v17, v19, v18 dst_sel:DWORD dst_unused:UNUSED_PAD src0_sel:DWORD src1_sel:WORD_1
	v_or_b32_sdwa v16, v20, v16 dst_sel:DWORD dst_unused:UNUSED_PAD src0_sel:DWORD src1_sel:WORD_1
	global_store_dwordx2 v[32:33], v[16:17], off offset:32
	s_nop 0
	v_pk_fma_f32 v[6:7], v[6:7], v[126:127], v[216:217]
	v_pk_fma_f32 v[4:5], v[4:5], v[124:125], v[214:215]
	global_store_dwordx4 v[30:31], v[4:7], off offset:128
	v_pk_mul_f32 v[18:19], v[6:7], v[146:147]
	v_pk_mul_f32 v[16:17], v[4:5], v[144:145]
	v_pk_add_f32 v[22:23], v[162:163], 1.0 op_sel_hi:[1,0]
	v_pk_add_f32 v[20:21], v[160:161], 1.0 op_sel_hi:[1,0]
	v_pk_mul_f32 v[18:19], v[18:19], v[22:23]
	v_pk_mul_f32 v[16:17], v[16:17], v[20:21]
	v_and_b32_sdwa v22, v19, v170 dst_sel:DWORD dst_unused:UNUSED_PAD src0_sel:WORD_1 src1_sel:DWORD
	v_and_b32_sdwa v23, v17, v170 dst_sel:DWORD dst_unused:UNUSED_PAD src0_sel:WORD_1 src1_sel:DWORD
	v_and_b32_sdwa v20, v18, v170 dst_sel:DWORD dst_unused:UNUSED_PAD src0_sel:WORD_1 src1_sel:DWORD
	v_and_b32_sdwa v21, v16, v170 dst_sel:DWORD dst_unused:UNUSED_PAD src0_sel:WORD_1 src1_sel:DWORD
	v_add3_u32 v19, v19, v22, s56
	v_add3_u32 v17, v17, v23, s56
	v_add3_u32 v16, v16, v21, s56
	v_add3_u32 v18, v18, v20, s56
	v_and_b32_e32 v19, 0xffff0000, v19
	v_and_b32_e32 v20, 0xffff0000, v17
	v_or_b32_sdwa v17, v19, v18 dst_sel:DWORD dst_unused:UNUSED_PAD src0_sel:DWORD src1_sel:WORD_1
	v_or_b32_sdwa v16, v20, v16 dst_sel:DWORD dst_unused:UNUSED_PAD src0_sel:DWORD src1_sel:WORD_1
	global_store_dwordx2 v[32:33], v[16:17], off offset:64
	s_nop 0
	v_pk_fma_f32 v[18:19], v[2:3], v[134:135], v[220:221]
	v_pk_fma_f32 v[16:17], v[0:1], v[132:133], v[218:219]
	global_store_dwordx4 v[30:31], v[16:19], off offset:192
	s_nop 0
	v_mul_f32_e32 v0, v13, v13
	v_mul_f32_e32 v1, v9, v9
	v_fmac_f32_e32 v0, v12, v12
	v_fmac_f32_e32 v1, v8, v8
	v_fmac_f32_e32 v0, v14, v14
	v_fmac_f32_e32 v1, v10, v10
	v_fmac_f32_e32 v0, v15, v15
	v_fmac_f32_e32 v1, v11, v11
	v_add_f32_e32 v0, v0, v1
	v_mul_f32_e32 v1, v5, v5
	v_fmac_f32_e32 v1, v4, v4
	v_fmac_f32_e32 v1, v6, v6
	v_fmac_f32_e32 v1, v7, v7
	v_add_f32_e32 v0, v0, v1
	v_mul_f32_e32 v1, v17, v17
	v_fmac_f32_e32 v1, v16, v16
	v_fmac_f32_e32 v1, v18, v18
	v_fmac_f32_e32 v1, v19, v19
	v_add_f32_e32 v0, v0, v1
	ds_bpermute_b32 v1, v105, v0
	s_waitcnt lgkmcnt(0)
	v_add_f32_e32 v0, v0, v1
	ds_bpermute_b32 v1, v104, v0
	v_pk_mul_f32 v[2:3], v[18:19], v[150:151]
	v_pk_mul_f32 v[4:5], v[16:17], v[148:149]
	v_pk_add_f32 v[6:7], v[182:183], 1.0 op_sel_hi:[1,0]
	v_pk_add_f32 v[8:9], v[180:181], 1.0 op_sel_hi:[1,0]
	v_pk_mul_f32 v[2:3], v[2:3], v[6:7]
	v_pk_mul_f32 v[4:5], v[4:5], v[8:9]
	v_and_b32_sdwa v8, v3, v170 dst_sel:DWORD dst_unused:UNUSED_PAD src0_sel:WORD_1 src1_sel:DWORD
	v_and_b32_sdwa v9, v5, v170 dst_sel:DWORD dst_unused:UNUSED_PAD src0_sel:WORD_1 src1_sel:DWORD
	v_and_b32_sdwa v6, v2, v170 dst_sel:DWORD dst_unused:UNUSED_PAD src0_sel:WORD_1 src1_sel:DWORD
	v_and_b32_sdwa v7, v4, v170 dst_sel:DWORD dst_unused:UNUSED_PAD src0_sel:WORD_1 src1_sel:DWORD
	v_add3_u32 v3, v3, v8, s56
	v_add3_u32 v5, v5, v9, s56
	v_add3_u32 v4, v4, v7, s56
	v_add3_u32 v2, v2, v6, s56
	v_and_b32_e32 v3, 0xffff0000, v3
	v_and_b32_e32 v5, 0xffff0000, v5
	v_or_b32_sdwa v3, v3, v2 dst_sel:DWORD dst_unused:UNUSED_PAD src0_sel:DWORD src1_sel:WORD_1
	v_or_b32_sdwa v2, v5, v4 dst_sel:DWORD dst_unused:UNUSED_PAD src0_sel:DWORD src1_sel:WORD_1
	global_store_dwordx2 v[32:33], v[2:3], off offset:96
	s_and_saveexec_b64 s[24:25], s[36:37]
	s_cbranch_execz .LBB0_591
	s_waitcnt lgkmcnt(0)
	v_add_f32_e32 v0, v0, v1
	global_store_dword v[48:49], v0, off offset:192

.LBB0_609:
	s_add_i32 s2, s3, 2
	s_setprio 1
	v_add_u32_e32 v127, v89, v90
	ds_read_b128 v[100:103], v127 offset:16384
	ds_read_b128 v[106:109], v127 offset:18432
	ds_read_b128 v[110:113], v127 offset:20480
	ds_read_b128 v[114:117], v127 offset:22528
	v_add_u32_e32 v126, v88, v90
	ds_read_b128 v[92:95], v126
	ds_read_b128 v[96:99], v126 offset:2048
	s_add_i32 s3, s3, 4
	s_min_u32 s3, s3, 63
	v_add_u32_e32 v128, v88, v91
	v_add_u32_e32 v130, v89, v91
	s_lshl_b32 s92, s3, 7
	ds_read_b128 v[118:121], v130 offset:18432
	ds_read_b128 v[122:125], v130 offset:20480
	ds_read_b128 v[132:135], v130 offset:22528
	s_waitcnt lgkmcnt(4)
	v_mfma_f32_16x16x32_bf16 v[76:79], v[100:103], v[92:95], v[76:79]
	v_lshl_add_u64 v[44:45], v[80:81], 0, s[92:93]
	v_add_co_u32_e32 v46, vcc, s7, v44
	v_mfma_f32_16x16x32_bf16 v[68:71], v[106:109], v[92:95], v[68:71]
	s_nop 0
	v_addc_co_u32_e32 v47, vcc, 0, v45, vcc
	v_mfma_f32_16x16x32_bf16 v[52:55], v[110:113], v[92:95], v[52:55]
	v_mfma_f32_16x16x32_bf16 v[40:43], v[114:117], v[92:95], v[40:43]
	s_waitcnt lgkmcnt(3)
	v_mfma_f32_16x16x32_bf16 v[92:95], v[100:103], v[96:99], v[36:39]
	s_nop 2
	ds_read_b128 v[36:39], v128
	v_mfma_f32_16x16x32_bf16 v[100:103], v[106:109], v[96:99], v[8:11]
	v_mfma_f32_16x16x32_bf16 v[106:109], v[110:113], v[96:99], v[4:7]
	ds_read_b128 v[110:113], v128 offset:2048
	v_mfma_f32_16x16x32_bf16 v[96:99], v[114:117], v[96:99], v[0:3]
	ds_read_b128 v[114:117], v130 offset:16384
	global_load_dwordx4 v[72:75], v[44:45], off
	s_waitcnt vmcnt(1)
	ds_write_b128 v87, v[12:15] offset:53248
	global_load_dwordx4 v[64:67], v[46:47], off
	v_add_co_u32_e32 v46, vcc, s52, v44
	ds_write_b128 v87, v[16:19] offset:49152
	s_nop 0
	v_addc_co_u32_e32 v47, vcc, 0, v45, vcc
	v_add_co_u32_e32 v44, vcc, s34, v44
	global_load_dwordx4 v[60:63], v[46:47], off
	s_nop 0
	v_addc_co_u32_e32 v45, vcc, 0, v45, vcc
	ds_write_b128 v87, v[20:23] offset:45056
	global_load_dwordx4 v[56:59], v[44:45], off
	v_lshl_add_u64 v[44:45], v[82:83], 0, s[92:93]
	ds_write_b128 v87, v[28:31] offset:32768
	s_waitcnt lgkmcnt(4)
	v_mfma_f32_16x16x32_bf16 v[0:3], v[114:117], v[36:39], v[76:79]
	v_mfma_f32_16x16x32_bf16 v[4:7], v[118:121], v[36:39], v[68:71]
	global_load_dwordx4 v[48:51], v[44:45], off
	v_add_co_u32_e32 v44, vcc, s7, v44
	ds_write_b128 v87, v[32:35] offset:36864
	s_nop 0
	v_addc_co_u32_e32 v45, vcc, 0, v45, vcc
	v_mfma_f32_16x16x32_bf16 v[8:11], v[122:125], v[36:39], v[52:55]
	v_mfma_f32_16x16x32_bf16 v[36:39], v[132:135], v[36:39], v[40:43]
	global_load_dwordx4 v[44:47], v[44:45], off
	ds_write_b128 v87, v[24:27] offset:40960
	v_mfma_f32_16x16x32_bf16 v[40:43], v[114:117], v[110:113], v[92:95]
	v_mfma_f32_16x16x32_bf16 v[52:55], v[118:121], v[110:113], v[100:103]
	v_mfma_f32_16x16x32_bf16 v[68:71], v[122:125], v[110:113], v[106:109]
	v_mfma_f32_16x16x32_bf16 v[76:79], v[132:135], v[110:113], v[96:99]
	s_setprio 0
	s_waitcnt lgkmcnt(0)
	s_barrier
	s_setprio 1
	ds_read_b128 v[100:103], v127 offset:49152
	ds_read_b128 v[106:109], v127 offset:51200
	ds_read_b128 v[110:113], v127 offset:53248
	ds_read_b128 v[114:117], v127 offset:55296
	ds_read_b128 v[92:95], v126 offset:32768
	ds_read_b128 v[96:99], v126 offset:34816
	s_min_u32 s3, s2, 60
	s_lshl_b32 s92, s3, 7
	ds_read_b128 v[118:121], v130 offset:51200
	ds_read_b128 v[122:125], v130 offset:53248
	ds_read_b128 v[132:135], v130 offset:55296
	s_waitcnt lgkmcnt(4)
	v_mfma_f32_16x16x32_bf16 v[0:3], v[100:103], v[92:95], v[0:3]
	v_lshl_add_u64 v[12:13], v[80:81], 0, s[92:93]
	v_add_co_u32_e32 v14, vcc, s7, v12
	v_mfma_f32_16x16x32_bf16 v[4:7], v[106:109], v[92:95], v[4:7]
	s_nop 0
	v_addc_co_u32_e32 v15, vcc, 0, v13, vcc
	v_mfma_f32_16x16x32_bf16 v[8:11], v[110:113], v[92:95], v[8:11]
	v_mfma_f32_16x16x32_bf16 v[36:39], v[114:117], v[92:95], v[36:39]
	s_waitcnt lgkmcnt(3)
	v_mfma_f32_16x16x32_bf16 v[92:95], v[100:103], v[96:99], v[40:43]
	s_nop 2
	ds_read_b128 v[40:43], v128 offset:32768
	v_mfma_f32_16x16x32_bf16 v[100:103], v[106:109], v[96:99], v[52:55]
	v_mfma_f32_16x16x32_bf16 v[106:109], v[110:113], v[96:99], v[68:71]
	ds_read_b128 v[110:113], v128 offset:34816
	v_mfma_f32_16x16x32_bf16 v[96:99], v[114:117], v[96:99], v[76:79]
	ds_read_b128 v[114:117], v130 offset:49152
	global_load_dwordx4 v[28:31], v[12:13], off offset:384
	s_waitcnt vmcnt(1)
	ds_write_b128 v87, v[44:47] offset:20480
	global_load_dwordx4 v[32:35], v[14:15], off offset:384
	v_add_co_u32_e32 v14, vcc, s52, v12
	ds_write_b128 v87, v[48:51] offset:16384
	s_nop 0
	v_addc_co_u32_e32 v15, vcc, 0, v13, vcc
	v_add_co_u32_e32 v12, vcc, s34, v12
	global_load_dwordx4 v[24:27], v[14:15], off offset:384
	s_nop 0
	v_addc_co_u32_e32 v13, vcc, 0, v13, vcc
	ds_write_b128 v87, v[56:59] offset:12288
	global_load_dwordx4 v[20:23], v[12:13], off offset:384
	v_lshl_add_u64 v[12:13], v[82:83], 0, s[92:93]
	ds_write_b128 v87, v[72:75]
	s_waitcnt lgkmcnt(4)
	v_mfma_f32_16x16x32_bf16 v[76:79], v[114:117], v[40:43], v[0:3]
	v_mfma_f32_16x16x32_bf16 v[68:71], v[118:121], v[40:43], v[4:7]
	global_load_dwordx4 v[16:19], v[12:13], off offset:384
	v_add_co_u32_e32 v12, vcc, s7, v12
	ds_write_b128 v87, v[64:67] offset:4096
	s_nop 0
	v_addc_co_u32_e32 v13, vcc, 0, v13, vcc
	v_mfma_f32_16x16x32_bf16 v[52:55], v[122:125], v[40:43], v[8:11]
	v_mfma_f32_16x16x32_bf16 v[40:43], v[132:135], v[40:43], v[36:39]
	global_load_dwordx4 v[12:15], v[12:13], off offset:384
	ds_write_b128 v87, v[60:63] offset:8192
	v_mfma_f32_16x16x32_bf16 v[36:39], v[114:117], v[110:113], v[92:95]
	v_mfma_f32_16x16x32_bf16 v[8:11], v[118:121], v[110:113], v[100:103]
	v_mfma_f32_16x16x32_bf16 v[4:7], v[122:125], v[110:113], v[106:109]
	v_mfma_f32_16x16x32_bf16 v[0:3], v[132:135], v[110:113], v[96:99]
	s_setprio 0
	s_cmp_lt_u32 s2, 62
	s_mov_b32 s3, s2
	s_waitcnt lgkmcnt(0)
	s_barrier
	s_cbranch_scc1 .LBB0_609
	v_readlane_b32 s2, v251, 18
	s_waitcnt vmcnt(1)
	s_nop 0
	v_add_u32_e32 v18, s2, v86
	v_readlane_b32 s2, v251, 19
	s_waitcnt vmcnt(0)
	v_add_u32_e32 v13, 0xffffe000, v18
	v_or_b32_e32 v12, v18, v85
	v_lshl_or_b32 v19, v84, 2, s2
	v_lshrrev_b32_e32 v13, 10, v13
	s_movk_i32 s2, 0x1800
	v_mad_u32_u24 v13, v13, s2, s2
	v_cmp_lt_i32_e32 vcc, s13, v12
	v_lshlrev_b32_e32 v128, 2, v19
	v_readlane_b32 s2, v250, 15
	v_cndmask_b32_e32 v14, 0, v13, vcc
	v_ashrrev_i32_e32 v15, 31, v14
	v_lshlrev_b64 v[24:25], 2, v[14:15]
	v_ashrrev_i32_e32 v13, 31, v12
	v_lshl_add_u64 v[14:15], s[38:39], 0, v[24:25]
	v_lshl_add_u64 v[48:49], v[14:15], 0, v[128:129]
	v_lshlrev_b64 v[14:15], 12, v[12:13]
	v_readlane_b32 s3, v250, 16
	v_lshl_add_u64 v[28:29], s[40:41], 0, v[24:25]
	v_lshlrev_b64 v[32:33], 11, v[12:13]
	v_lshl_add_u64 v[14:15], s[2:3], 0, v[14:15]
	v_lshl_add_u64 v[50:51], v[14:15], 0, v[128:129]
	global_load_dwordx4 v[72:75], v[48:49], off
	global_load_dwordx4 v[80:83], v[48:49], off offset:64
	global_load_dwordx4 v[88:91], v[48:49], off offset:128
	global_load_dwordx4 v[136:139], v[48:49], off offset:192
	global_load_dwordx4 v[194:197], v[50:51], off
	global_load_dwordx4 v[198:201], v[50:51], off offset:64
	global_load_dwordx4 v[202:205], v[50:51], off offset:128
	global_load_dwordx4 v[206:209], v[50:51], off offset:192
	v_add_co_u32_e32 v58, vcc, 0x10000, v50
	s_nop 1
	v_addc_co_u32_e32 v59, vcc, 0, v51, vcc
	global_load_dwordx4 v[210:213], v[58:59], off
	global_load_dwordx4 v[214:217], v[58:59], off offset:64
	global_load_dwordx4 v[218:221], v[58:59], off offset:128
	global_load_dwordx4 v[222:225], v[58:59], off offset:192
	v_readlane_b32 s2, v250, 21
	v_readlane_b32 s3, v250, 22
	v_cmp_eq_u32_e32 vcc, 0, v84
	s_waitcnt vmcnt(4)
	v_pk_fma_f32 v[22:23], v[78:79], v[74:75], v[196:197]
	v_pk_fma_f32 v[20:21], v[76:77], v[72:73], v[194:195]
	global_store_dwordx4 v[50:51], v[20:23], off
	v_lshl_add_u64 v[14:15], v[28:29], 0, v[128:129]
	global_load_dwordx4 v[140:143], v128, s[0:1]
	global_load_dwordx4 v[144:147], v128, s[0:1] offset:64
	global_load_dwordx4 v[148:151], v128, s[0:1] offset:128
	global_load_dwordx4 v[152:155], v128, s[0:1] offset:192
	global_load_dwordx4 v[156:159], v[14:15], off
	global_load_dwordx4 v[160:163], v[14:15], off offset:64
	global_load_dwordx4 v[180:183], v[14:15], off offset:128
	global_load_dwordx4 v[190:193], v[14:15], off offset:192
	v_lshlrev_b32_e32 v16, 1, v19
	v_mov_b32_e32 v17, v129
	v_lshl_add_u64 v[32:33], s[2:3], 0, v[32:33]
	v_lshl_add_u64 v[56:57], v[32:33], 0, v[16:17]
	s_waitcnt vmcnt(0)
	v_pk_mul_f32 v[26:27], v[22:23], v[142:143]
	v_pk_mul_f32 v[24:25], v[20:21], v[140:141]
	s_waitcnt vmcnt(0)
	v_pk_add_f32 v[30:31], v[158:159], 1.0 op_sel_hi:[1,0]
	v_pk_add_f32 v[28:29], v[156:157], 1.0 op_sel_hi:[1,0]
	v_pk_mul_f32 v[26:27], v[26:27], v[30:31]
	v_pk_mul_f32 v[24:25], v[24:25], v[28:29]
	v_and_b32_sdwa v19, v26, v170 dst_sel:DWORD dst_unused:UNUSED_PAD src0_sel:WORD_1 src1_sel:DWORD
	v_and_b32_sdwa v29, v27, v170 dst_sel:DWORD dst_unused:UNUSED_PAD src0_sel:WORD_1 src1_sel:DWORD
	v_and_b32_sdwa v30, v25, v170 dst_sel:DWORD dst_unused:UNUSED_PAD src0_sel:WORD_1 src1_sel:DWORD
	v_and_b32_sdwa v28, v24, v170 dst_sel:DWORD dst_unused:UNUSED_PAD src0_sel:WORD_1 src1_sel:DWORD
	v_add3_u32 v19, v26, v19, s56
	v_add3_u32 v26, v27, v29, s56
	v_add3_u32 v25, v25, v30, s56
	v_add3_u32 v24, v24, v28, s56
	v_and_b32_e32 v26, 0xffff0000, v26
	v_and_b32_e32 v27, 0xffff0000, v25
	v_or_b32_sdwa v25, v26, v19 dst_sel:DWORD dst_unused:UNUSED_PAD src0_sel:DWORD src1_sel:WORD_1
	v_or_b32_sdwa v24, v27, v24 dst_sel:DWORD dst_unused:UNUSED_PAD src0_sel:DWORD src1_sel:WORD_1
	global_store_dwordx2 v[56:57], v[24:25], off
	s_nop 0
	s_waitcnt vmcnt(0)
	v_pk_fma_f32 v[26:27], v[70:71], v[82:83], v[200:201]
	v_pk_fma_f32 v[24:25], v[68:69], v[80:81], v[198:199]
	global_store_dwordx4 v[50:51], v[24:27], off offset:64
	v_pk_mul_f32 v[30:31], v[26:27], v[146:147]
	v_pk_mul_f32 v[28:29], v[24:25], v[144:145]
	v_pk_add_f32 v[34:35], v[162:163], 1.0 op_sel_hi:[1,0]
	v_pk_add_f32 v[32:33], v[160:161], 1.0 op_sel_hi:[1,0]
	v_pk_mul_f32 v[30:31], v[30:31], v[34:35]
	v_pk_mul_f32 v[28:29], v[28:29], v[32:33]
	v_and_b32_sdwa v19, v30, v170 dst_sel:DWORD dst_unused:UNUSED_PAD src0_sel:WORD_1 src1_sel:DWORD
	v_and_b32_sdwa v33, v31, v170 dst_sel:DWORD dst_unused:UNUSED_PAD src0_sel:WORD_1 src1_sel:DWORD
	v_and_b32_sdwa v34, v29, v170 dst_sel:DWORD dst_unused:UNUSED_PAD src0_sel:WORD_1 src1_sel:DWORD
	v_and_b32_sdwa v32, v28, v170 dst_sel:DWORD dst_unused:UNUSED_PAD src0_sel:WORD_1 src1_sel:DWORD
	v_add3_u32 v19, v30, v19, s56
	v_add3_u32 v30, v31, v33, s56
	v_add3_u32 v29, v29, v34, s56
	v_add3_u32 v28, v28, v32, s56
	v_and_b32_e32 v30, 0xffff0000, v30
	v_and_b32_e32 v31, 0xffff0000, v29
	v_or_b32_sdwa v29, v30, v19 dst_sel:DWORD dst_unused:UNUSED_PAD src0_sel:DWORD src1_sel:WORD_1
	v_or_b32_sdwa v28, v31, v28 dst_sel:DWORD dst_unused:UNUSED_PAD src0_sel:DWORD src1_sel:WORD_1
	global_store_dwordx2 v[56:57], v[28:29], off offset:32
	s_nop 0
	v_pk_fma_f32 v[30:31], v[54:55], v[90:91], v[204:205]
	v_pk_fma_f32 v[28:29], v[52:53], v[88:89], v[202:203]
	global_store_dwordx4 v[50:51], v[28:31], off offset:128
	v_pk_mul_f32 v[34:35], v[30:31], v[150:151]
	v_pk_mul_f32 v[32:33], v[28:29], v[148:149]
	v_pk_add_f32 v[46:47], v[182:183], 1.0 op_sel_hi:[1,0]
	v_pk_add_f32 v[44:45], v[180:181], 1.0 op_sel_hi:[1,0]
	v_pk_mul_f32 v[34:35], v[34:35], v[46:47]
	v_pk_mul_f32 v[32:33], v[32:33], v[44:45]
	v_and_b32_sdwa v19, v34, v170 dst_sel:DWORD dst_unused:UNUSED_PAD src0_sel:WORD_1 src1_sel:DWORD
	v_and_b32_sdwa v45, v35, v170 dst_sel:DWORD dst_unused:UNUSED_PAD src0_sel:WORD_1 src1_sel:DWORD
	v_and_b32_sdwa v46, v33, v170 dst_sel:DWORD dst_unused:UNUSED_PAD src0_sel:WORD_1 src1_sel:DWORD
	v_and_b32_sdwa v44, v32, v170 dst_sel:DWORD dst_unused:UNUSED_PAD src0_sel:WORD_1 src1_sel:DWORD
	v_add3_u32 v19, v34, v19, s56
	v_add3_u32 v34, v35, v45, s56
	v_add3_u32 v33, v33, v46, s56
	v_add3_u32 v32, v32, v44, s56
	v_and_b32_e32 v34, 0xffff0000, v34
	v_and_b32_e32 v35, 0xffff0000, v33
	v_or_b32_sdwa v33, v34, v19 dst_sel:DWORD dst_unused:UNUSED_PAD src0_sel:DWORD src1_sel:WORD_1
	v_or_b32_sdwa v32, v35, v32 dst_sel:DWORD dst_unused:UNUSED_PAD src0_sel:DWORD src1_sel:WORD_1
	global_store_dwordx2 v[56:57], v[32:33], off offset:64
	s_nop 0
	v_pk_fma_f32 v[34:35], v[42:43], v[138:139], v[208:209]
	v_pk_fma_f32 v[32:33], v[40:41], v[136:137], v[206:207]
	global_store_dwordx4 v[50:51], v[32:35], off offset:192
	v_mul_f32_e32 v14, v21, v21
	v_mul_f32_e32 v15, v25, v25
	v_fmac_f32_e32 v14, v20, v20
	v_fmac_f32_e32 v15, v24, v24
	v_fmac_f32_e32 v14, v22, v22
	v_fmac_f32_e32 v15, v26, v26
	v_fmac_f32_e32 v14, v23, v23
	v_fmac_f32_e32 v15, v27, v27
	v_add_f32_e32 v14, v14, v15
	v_mul_f32_e32 v15, v29, v29
	v_fmac_f32_e32 v15, v28, v28
	v_fmac_f32_e32 v15, v30, v30
	v_fmac_f32_e32 v15, v31, v31
	v_add_f32_e32 v14, v14, v15
	v_mul_f32_e32 v15, v33, v33
	v_fmac_f32_e32 v15, v32, v32
	v_fmac_f32_e32 v15, v34, v34
	v_fmac_f32_e32 v15, v35, v35
	v_add_f32_e32 v14, v14, v15
	ds_bpermute_b32 v15, v105, v14
	s_waitcnt lgkmcnt(0)
	v_add_f32_e32 v14, v14, v15
	ds_bpermute_b32 v15, v104, v14
	v_pk_mul_f32 v[20:21], v[34:35], v[154:155]
	v_pk_mul_f32 v[22:23], v[32:33], v[152:153]
	v_pk_add_f32 v[24:25], v[192:193], 1.0 op_sel_hi:[1,0]
	v_pk_add_f32 v[26:27], v[190:191], 1.0 op_sel_hi:[1,0]
	v_pk_mul_f32 v[20:21], v[20:21], v[24:25]
	v_pk_mul_f32 v[22:23], v[22:23], v[26:27]
	v_and_b32_sdwa v19, v20, v170 dst_sel:DWORD dst_unused:UNUSED_PAD src0_sel:WORD_1 src1_sel:DWORD
	v_and_b32_sdwa v25, v21, v170 dst_sel:DWORD dst_unused:UNUSED_PAD src0_sel:WORD_1 src1_sel:DWORD
	v_and_b32_sdwa v26, v23, v170 dst_sel:DWORD dst_unused:UNUSED_PAD src0_sel:WORD_1 src1_sel:DWORD
	v_and_b32_sdwa v24, v22, v170 dst_sel:DWORD dst_unused:UNUSED_PAD src0_sel:WORD_1 src1_sel:DWORD
	v_add3_u32 v19, v20, v19, s56
	v_add3_u32 v20, v21, v25, s56
	v_add3_u32 v21, v23, v26, s56
	v_add3_u32 v22, v22, v24, s56
	v_and_b32_e32 v20, 0xffff0000, v20
	v_and_b32_e32 v23, 0xffff0000, v21
	v_or_b32_sdwa v21, v20, v19 dst_sel:DWORD dst_unused:UNUSED_PAD src0_sel:DWORD src1_sel:WORD_1
	v_or_b32_sdwa v20, v23, v22 dst_sel:DWORD dst_unused:UNUSED_PAD src0_sel:DWORD src1_sel:WORD_1
	global_store_dwordx2 v[56:57], v[20:21], off offset:96
	s_and_saveexec_b64 s[2:3], vcc
	s_cbranch_execz .LBB0_612
	v_readlane_b32 s16, v253, 20
	s_add_u32 s24, s26, s16
	s_addc_u32 s25, s27, 0
	v_lshl_add_u64 v[20:21], v[12:13], 2, s[24:25]
	s_waitcnt lgkmcnt(0)
	v_add_f32_e32 v13, v14, v15
	global_store_dword v[20:21], v13, off
.LBB0_612:
	s_or_b64 exec, exec, s[2:3]
	v_add_u32_e32 v13, 0xffffe010, v18
	s_waitcnt lgkmcnt(0)
	v_lshl_add_u64 v[14:15], s[0:1], 0, v[128:129]
	v_or_b32_e32 v12, 16, v12
	v_lshrrev_b32_e32 v13, 10, v13
	s_movk_i32 s0, 0x1800
	v_mad_u32_u24 v13, v13, s0, s0
	v_cmp_lt_i32_e64 s[0:1], s13, v12
	s_nop 1
	v_cndmask_b32_e64 v18, 0, v13, s[0:1]
	v_ashrrev_i32_e32 v19, 31, v18
	v_lshlrev_b64 v[34:35], 2, v[18:19]
	v_ashrrev_i32_e32 v13, 31, v12
	v_lshl_add_u64 v[18:19], s[38:39], 0, v[34:35]
	v_readlane_b32 s0, v250, 15
	v_lshl_add_u64 v[20:21], v[18:19], 0, v[128:129]
	v_lshlrev_b64 v[18:19], 12, v[12:13]
	v_readlane_b32 s1, v250, 16
	s_nop 0
	v_lshl_add_u64 v[18:19], s[0:1], 0, v[18:19]
	v_lshl_add_u64 v[18:19], v[18:19], 0, v[128:129]
	v_readlane_b32 s0, v250, 21
	v_readlane_b32 s1, v250, 22
	s_waitcnt vmcnt(16)
	v_pk_fma_f32 v[28:29], v[38:39], v[74:75], v[212:213]
	v_pk_fma_f32 v[26:27], v[36:37], v[72:73], v[210:211]
	v_lshl_add_u64 v[22:23], s[40:41], 0, v[34:35]
	global_store_dwordx4 v[18:19], v[26:29], off
	v_lshl_add_u64 v[22:23], v[22:23], 0, v[128:129]
	v_mul_f32_e32 v38, v27, v27
	v_fmac_f32_e32 v38, v26, v26
	v_fmac_f32_e32 v38, v28, v28
	v_fmac_f32_e32 v38, v29, v29
	v_pk_mul_f32 v[24:25], v[28:29], v[142:143]
	v_pk_add_f32 v[28:29], v[158:159], 1.0 op_sel_hi:[1,0]
	v_pk_mul_f32 v[26:27], v[26:27], v[140:141]
	v_pk_add_f32 v[30:31], v[156:157], 1.0 op_sel_hi:[1,0]
	v_pk_mul_f32 v[24:25], v[24:25], v[28:29]
	v_lshlrev_b64 v[28:29], 11, v[12:13]
	v_pk_mul_f32 v[26:27], v[26:27], v[30:31]
	v_lshl_add_u64 v[28:29], s[0:1], 0, v[28:29]
	v_lshl_add_u64 v[16:17], v[28:29], 0, v[16:17]
	v_and_b32_sdwa v28, v24, v170 dst_sel:DWORD dst_unused:UNUSED_PAD src0_sel:WORD_1 src1_sel:DWORD
	v_and_b32_sdwa v29, v26, v170 dst_sel:DWORD dst_unused:UNUSED_PAD src0_sel:WORD_1 src1_sel:DWORD
	v_add3_u32 v26, v26, v29, s56
	v_add3_u32 v24, v24, v28, s56
	v_and_b32_sdwa v28, v25, v170 dst_sel:DWORD dst_unused:UNUSED_PAD src0_sel:WORD_1 src1_sel:DWORD
	v_and_b32_sdwa v29, v27, v170 dst_sel:DWORD dst_unused:UNUSED_PAD src0_sel:WORD_1 src1_sel:DWORD
	v_add3_u32 v25, v25, v28, s56
	v_add3_u32 v27, v27, v29, s56
	v_and_b32_e32 v25, 0xffff0000, v25
	v_and_b32_e32 v27, 0xffff0000, v27
	v_or_b32_sdwa v25, v25, v24 dst_sel:DWORD dst_unused:UNUSED_PAD src0_sel:DWORD src1_sel:WORD_1
	v_or_b32_sdwa v24, v27, v26 dst_sel:DWORD dst_unused:UNUSED_PAD src0_sel:DWORD src1_sel:WORD_1
	global_store_dwordx2 v[16:17], v[24:25], off
	s_nop 0
	v_pk_fma_f32 v[8:9], v[8:9], v[80:81], v[214:215]
	s_nop 0
	v_mul_f32_e32 v24, v9, v9
	v_pk_fma_f32 v[10:11], v[10:11], v[82:83], v[216:217]
	v_fmac_f32_e32 v24, v8, v8
	v_fmac_f32_e32 v24, v10, v10
	global_store_dwordx4 v[18:19], v[8:11], off offset:64
	v_fmac_f32_e32 v24, v11, v11
	v_add_f32_e32 v32, v38, v24
	v_pk_mul_f32 v[10:11], v[10:11], v[146:147]
	v_pk_mul_f32 v[8:9], v[8:9], v[144:145]
	v_pk_add_f32 v[24:25], v[162:163], 1.0 op_sel_hi:[1,0]
	v_pk_add_f32 v[26:27], v[160:161], 1.0 op_sel_hi:[1,0]
	v_pk_mul_f32 v[10:11], v[10:11], v[24:25]
	v_pk_mul_f32 v[8:9], v[8:9], v[26:27]
	v_and_b32_sdwa v24, v10, v170 dst_sel:DWORD dst_unused:UNUSED_PAD src0_sel:WORD_1 src1_sel:DWORD
	v_and_b32_sdwa v25, v8, v170 dst_sel:DWORD dst_unused:UNUSED_PAD src0_sel:WORD_1 src1_sel:DWORD
	v_add3_u32 v8, v8, v25, s56
	v_add3_u32 v10, v10, v24, s56
	v_and_b32_sdwa v24, v11, v170 dst_sel:DWORD dst_unused:UNUSED_PAD src0_sel:WORD_1 src1_sel:DWORD
	v_and_b32_sdwa v25, v9, v170 dst_sel:DWORD dst_unused:UNUSED_PAD src0_sel:WORD_1 src1_sel:DWORD
	v_add3_u32 v11, v11, v24, s56
	v_add3_u32 v9, v9, v25, s56
	v_and_b32_e32 v11, 0xffff0000, v11
	v_and_b32_e32 v24, 0xffff0000, v9
	v_or_b32_sdwa v9, v11, v10 dst_sel:DWORD dst_unused:UNUSED_PAD src0_sel:DWORD src1_sel:WORD_1
	v_or_b32_sdwa v8, v24, v8 dst_sel:DWORD dst_unused:UNUSED_PAD src0_sel:DWORD src1_sel:WORD_1
	global_store_dwordx2 v[16:17], v[8:9], off offset:32
	s_nop 0
	v_pk_fma_f32 v[4:5], v[4:5], v[88:89], v[218:219]
	s_nop 0
	v_mul_f32_e32 v8, v5, v5
	v_pk_fma_f32 v[6:7], v[6:7], v[90:91], v[220:221]
	v_fmac_f32_e32 v8, v4, v4
	v_fmac_f32_e32 v8, v6, v6
	global_store_dwordx4 v[18:19], v[4:7], off offset:128
	v_fmac_f32_e32 v8, v7, v7
	v_add_f32_e32 v28, v32, v8
	v_pk_mul_f32 v[6:7], v[6:7], v[150:151]
	v_pk_mul_f32 v[4:5], v[4:5], v[148:149]
	v_pk_add_f32 v[8:9], v[182:183], 1.0 op_sel_hi:[1,0]
	v_pk_add_f32 v[10:11], v[180:181], 1.0 op_sel_hi:[1,0]
	v_pk_mul_f32 v[6:7], v[6:7], v[8:9]
	v_pk_mul_f32 v[4:5], v[4:5], v[10:11]
	v_and_b32_sdwa v8, v6, v170 dst_sel:DWORD dst_unused:UNUSED_PAD src0_sel:WORD_1 src1_sel:DWORD
	v_and_b32_sdwa v9, v4, v170 dst_sel:DWORD dst_unused:UNUSED_PAD src0_sel:WORD_1 src1_sel:DWORD
	v_add3_u32 v4, v4, v9, s56
	v_add3_u32 v6, v6, v8, s56
	v_and_b32_sdwa v8, v7, v170 dst_sel:DWORD dst_unused:UNUSED_PAD src0_sel:WORD_1 src1_sel:DWORD
	v_and_b32_sdwa v9, v5, v170 dst_sel:DWORD dst_unused:UNUSED_PAD src0_sel:WORD_1 src1_sel:DWORD
	v_add3_u32 v7, v7, v8, s56
	v_add3_u32 v5, v5, v9, s56
	v_and_b32_e32 v7, 0xffff0000, v7
	v_and_b32_e32 v8, 0xffff0000, v5
	v_or_b32_sdwa v5, v7, v6 dst_sel:DWORD dst_unused:UNUSED_PAD src0_sel:DWORD src1_sel:WORD_1
	v_or_b32_sdwa v4, v8, v4 dst_sel:DWORD dst_unused:UNUSED_PAD src0_sel:DWORD src1_sel:WORD_1
	global_store_dwordx2 v[16:17], v[4:5], off offset:64
	s_nop 0
	v_pk_fma_f32 v[0:1], v[0:1], v[136:137], v[222:223]
	s_nop 0
	v_mul_f32_e32 v4, v1, v1
	v_pk_fma_f32 v[2:3], v[2:3], v[138:139], v[224:225]
	v_fmac_f32_e32 v4, v0, v0
	v_fmac_f32_e32 v4, v2, v2
	global_store_dwordx4 v[18:19], v[0:3], off offset:192
	v_fmac_f32_e32 v4, v3, v3
	v_add_f32_e32 v18, v28, v4
	v_pk_mul_f32 v[2:3], v[2:3], v[154:155]
	v_pk_mul_f32 v[0:1], v[0:1], v[152:153]
	v_pk_add_f32 v[4:5], v[192:193], 1.0 op_sel_hi:[1,0]
	v_pk_add_f32 v[6:7], v[190:191], 1.0 op_sel_hi:[1,0]
	v_pk_mul_f32 v[2:3], v[2:3], v[4:5]
	v_pk_mul_f32 v[0:1], v[0:1], v[6:7]
	v_and_b32_sdwa v4, v2, v170 dst_sel:DWORD dst_unused:UNUSED_PAD src0_sel:WORD_1 src1_sel:DWORD
	v_and_b32_sdwa v5, v0, v170 dst_sel:DWORD dst_unused:UNUSED_PAD src0_sel:WORD_1 src1_sel:DWORD
	v_add3_u32 v0, v0, v5, s56
	v_add3_u32 v2, v2, v4, s56
	v_and_b32_sdwa v4, v3, v170 dst_sel:DWORD dst_unused:UNUSED_PAD src0_sel:WORD_1 src1_sel:DWORD
	v_and_b32_sdwa v5, v1, v170 dst_sel:DWORD dst_unused:UNUSED_PAD src0_sel:WORD_1 src1_sel:DWORD
	v_add3_u32 v3, v3, v4, s56
	v_add3_u32 v1, v1, v5, s56
	v_and_b32_e32 v3, 0xffff0000, v3
	v_and_b32_e32 v4, 0xffff0000, v1
	v_or_b32_sdwa v1, v3, v2 dst_sel:DWORD dst_unused:UNUSED_PAD src0_sel:DWORD src1_sel:WORD_1
	v_or_b32_sdwa v0, v4, v0 dst_sel:DWORD dst_unused:UNUSED_PAD src0_sel:DWORD src1_sel:WORD_1
	global_store_dwordx2 v[16:17], v[0:1], off offset:96
	ds_bpermute_b32 v0, v105, v18
	s_waitcnt lgkmcnt(0)
	v_add_f32_e32 v0, v18, v0
	ds_bpermute_b32 v1, v104, v0
	s_and_saveexec_b64 s[0:1], vcc
	s_movk_i32 s89, 0xff
	s_cbranch_execz .LBB0_614
	v_readlane_b32 s2, v253, 20
	s_add_u32 s2, s26, s2
	s_addc_u32 s3, s27, 0
	v_lshl_add_u64 v[2:3], v[12:13], 2, s[2:3]
	s_waitcnt lgkmcnt(0)
	v_add_f32_e32 v0, v0, v1
	global_store_dword v[2:3], v0, off
